# GEMM K-loops: per-phase s_setprio toggling replaced by one static s_setprio 1 for the wave half that starts one barrier late (reset after the loop); attention priority kept
# baseline (speedup 1.0000x reference)
.LBB0_123:
	s_or_b64 exec, exec, s[0:1]
	s_add_u32 s0, s88, 0x16200000
	s_addc_u32 s1, s89, 0
	s_add_u32 s60, s88, 0x14200000
	s_addc_u32 s61, s89, 0
	v_writelane_b32 v237, s0, 24
	s_cmpk_lt_i32 s97, 0x580
	v_mov_b32_e32 v9, v236
	v_writelane_b32 v237, s1, 25
	s_cselect_b64 s[0:1], -1, 0
	v_writelane_b32 v237, s0, 26
	s_waitcnt lgkmcnt(0)
	s_barrier
	v_writelane_b32 v237, s1, 27
	s_cmpk_gt_i32 s97, 0x57f
	v_readfirstlane_b32 s1, v9
	s_cbranch_scc1 .LBB0_141
	v_lshlrev_b32_e32 v0, 4, v9
	v_add_u32_e32 v1, 0x2000, v0
	v_ashrrev_i32_e32 v2, 31, v1
	v_lshrrev_b32_e32 v2, 22, v2
	v_add_u32_e32 v2, v1, v2
	v_ashrrev_i32_e32 v8, 10, v2
	v_mul_i32_i24_e32 v2, 0x400, v8
	v_sub_u32_e32 v1, v1, v2
	v_lshrrev_b32_e32 v2, 4, v1
	v_bitop3_b32 v1, v2, v1, 32 bitop3:0x6c
	v_ashrrev_i32_e32 v2, 31, v1
	v_lshrrev_b32_e32 v2, 26, v2
	v_add_u32_e32 v2, v1, v2
	v_lshlrev_b32_e32 v3, 3, v8
	v_ashrrev_i32_e32 v10, 6, v2
	v_and_b32_e32 v3, -16, v3
	v_add_u32_e32 v3, v10, v3
	v_and_b32_e32 v4, 3, v10
	s_mov_b32 s0, 0xfffe0
	v_lshrrev_b32_e32 v5, 2, v3
	v_lshlrev_b32_e32 v6, 1, v3
	v_and_b32_e32 v2, 0xc0, v2
	v_and_or_b32 v4, v3, s0, v4
	v_and_b32_e32 v5, 4, v5
	v_and_b32_e32 v6, 24, v6
	v_sub_u32_e32 v1, v1, v2
	v_mov_b32_e32 v2, 1
	v_or3_b32 v4, v4, v5, v6
	v_lshlrev_b32_e32 v5, 5, v8
	v_ashrrev_i16_sdwa v1, v2, sext(v1) dst_sel:DWORD dst_unused:UNUSED_PAD src0_sel:DWORD src1_sel:BYTE_0
	v_and_b32_e32 v5, 32, v5
	v_bfe_i32 v11, v1, 0, 16
	v_add_lshl_u32 v1, v5, v11, 1
	s_waitcnt vmcnt(0)
	v_lshl_add_u32 v128, v4, 12, v1
	v_lshl_add_u32 v130, v3, 12, v1
	v_bfe_i32 v1, v9, 27, 1
	v_lshrrev_b32_e32 v1, 22, v1
	v_add_u32_e32 v1, v0, v1
	v_and_b32_e32 v1, 0xfffffc00, v1
	v_sub_u32_e32 v0, v0, v1
	v_lshrrev_b32_e32 v1, 4, v0
	v_ashrrev_i32_e32 v3, 31, v9
	v_bitop3_b32 v0, v1, v0, 32 bitop3:0x6c
	v_lshrrev_b32_e32 v3, 26, v3
	v_ashrrev_i32_e32 v1, 31, v0
	v_add_u32_e32 v3, v9, v3
	v_lshrrev_b32_e32 v1, 26, v1
	v_ashrrev_i32_e32 v13, 6, v3
	v_add_u32_e32 v1, v0, v1
	v_lshlrev_b32_e32 v3, 3, v13
	v_ashrrev_i32_e32 v12, 6, v1
	v_and_b32_e32 v3, -16, v3
	v_add_u32_e32 v3, v12, v3
	v_and_b32_e32 v4, 3, v12
	s_ashr_i32 s3, s97, 31
	v_and_or_b32 v4, v3, s0, v4
	s_lshr_b32 s0, s3, 29
	s_add_i32 s0, s97, s0
	s_ashr_i32 s6, s1, 6
	s_ashr_i32 s4, s0, 3
	s_and_b32 s0, s0, -8
	s_ashr_i32 s12, s1, 8
	s_lshl_b32 s2, s6, 10
	s_sub_i32 s0, s97, s0
	s_cmp_lt_i32 s0, 0
	s_movk_i32 s17, 0xb1
	s_cselect_b32 s5, s17, 0xb0
	s_mul_i32 s0, s0, s5
	s_add_i32 s0, s0, s4
	s_mul_hi_i32 s4, s0, 0x2e8ba2e9
	s_lshr_b32 s5, s4, 31
	s_ashr_i32 s4, s4, 6
	s_add_i32 s4, s4, s5
	s_lshl_b32 s5, s4, 3
	s_mulk_i32 s4, 0x160
	s_sub_i32 s4, s0, s4
	s_sext_i32_i16 s0, s4
	s_bfe_u32 s0, s0, 0x3001c
	s_add_i32 s7, s4, s0
	s_sext_i32_i16 s0, s7
	s_and_b32 s7, s7, 0xfff8
	s_sub_i32 s4, s4, s7
	s_sext_i32_i16 s4, s4
	v_lshrrev_b32_e32 v5, 2, v3
	v_lshlrev_b32_e32 v6, 1, v3
	v_and_b32_e32 v1, 0xc0, v1
	s_lshr_b32 s0, s0, 3
	s_add_i32 s28, s5, s4
	v_and_b32_e32 v5, 4, v5
	v_and_b32_e32 v6, 24, v6
	v_sub_u32_e32 v0, v0, v1
	s_ashr_i32 s29, s28, 31
	s_bfe_i64 s[8:9], s[0:1], 0x100000
	v_or3_b32 v4, v4, v5, v6
	v_lshlrev_b32_e32 v5, 5, v13
	v_ashrrev_i16_sdwa v0, v2, sext(v0) dst_sel:DWORD dst_unused:UNUSED_PAD src0_sel:DWORD src1_sel:BYTE_0
	s_lshl_b64 s[4:5], s[28:29], 20
	s_lshl_b64 s[8:9], s[8:9], 20
	v_and_b32_e32 v5, 32, v5
	v_bfe_i32 v14, v0, 0, 16
	s_add_u32 s30, s88, s8
	v_add_lshl_u32 v0, v5, v14, 1
	s_addc_u32 s31, s89, s9
	s_add_i32 s19, s2, 0
	v_lshl_add_u32 v132, v4, 12, v0
	s_add_i32 m0, s19, 0x10000
	v_lshl_add_u32 v134, v3, 12, v0
	global_load_lds_dwordx4 v132, s[30:31]
	s_add_i32 m0, s19, 0x12000
	s_add_u32 s8, s30, 0x80000
	global_load_lds_dwordx4 v128, s[30:31]
	s_addc_u32 s9, s31, 0
	s_add_i32 m0, s19, 0x14000
	v_mov_b32_e32 v133, 0
	global_load_lds_dwordx4 v132, s[8:9]
	s_add_i32 m0, s19, 0x16000
	s_add_u32 s34, s60, s4
	s_addc_u32 s35, s61, s5
	s_add_i32 s33, s19, 0x2000
	global_load_lds_dwordx4 v128, s[8:9]
	s_mov_b32 m0, s19
	s_add_u32 s4, s34, 0x80000
	global_load_lds_dwordx4 v134, s[34:35]
	s_mov_b32 m0, s33
	s_addc_u32 s5, s35, 0
	s_add_i32 s36, s19, 0x4000
	global_load_lds_dwordx4 v130, s[34:35]
	s_mov_b32 m0, s36
	s_add_i32 s37, s19, 0x6000
	global_load_lds_dwordx4 v134, s[4:5]
	s_mov_b32 m0, s37
	v_mov_b32_e32 v129, v133
	global_load_lds_dwordx4 v130, s[4:5]
	v_mov_b32_e32 v135, v133
	v_mov_b32_e32 v131, v133
	s_cmp_eq_u32 s12, 1
	s_mov_b32 s38, 0
	v_lshl_add_u64 v[6:7], s[30:31], 0, v[132:133]
	v_lshl_add_u64 v[4:5], s[30:31], 0, v[128:129]
	v_lshl_add_u64 v[0:1], s[34:35], 0, v[134:135]
	s_cselect_b64 s[4:5], -1, 0
	s_cmp_lg_u32 s12, 1
	v_lshl_add_u64 v[2:3], s[34:35], 0, v[130:131]
	s_cbranch_scc1 .LBB0_126
	s_setprio 1
	s_barrier

.LBB0_137:
	s_setprio 0
	v_readlane_b32 s28, v237, 24
	v_readlane_b32 s29, v237, 25
	v_lshl_or_b32 v156, s47, 7, v162
	v_ashrrev_i32_e32 v157, 31, v156
	v_mov_b64_e32 v[154:155], s[28:29]
	s_mov_b32 s28, 0x358637bd
	v_mov_b64_e32 v[158:159], s[28:29]
	v_pk_fma_f32 v[164:165], v[148:149], s[18:19], v[158:159] op_sel_hi:[1,0,0]
	v_mad_i64_i32 v[166:167], s[28:29], v152, s45, v[154:155]
	v_mul_f32_e32 v153, 0x4b800000, v165
	v_cmp_gt_f32_e32 vcc, s46, v165
	v_lshlrev_b64 v[156:157], 1, v[156:157]
	v_lshl_add_u64 v[166:167], v[166:167], 0, v[156:157]
	v_cndmask_b32_e32 v153, v165, v153, vcc
	v_rsq_f32_e32 v153, v153
	s_nop 0
	v_mul_f32_e32 v165, 0x45800000, v153
	v_cndmask_b32_e32 v168, v153, v165, vcc
	v_pk_mul_f32 v[124:125], v[168:169], v[124:125] op_sel_hi:[0,1]
	v_mul_f32_e32 v153, 0xbfb8aa3b, v124
	v_exp_f32_e32 v153, v153
	v_mul_f32_e32 v165, 0xbfb8aa3b, v125
	v_exp_f32_e32 v165, v165
	v_pk_mul_f32 v[126:127], v[168:169], v[126:127] op_sel_hi:[0,1]
	v_add_f32_e32 v153, 1.0, v153
	v_rcp_f32_e32 v170, v153
	v_add_f32_e32 v153, 1.0, v165
	v_mul_f32_e32 v165, 0xbfb8aa3b, v126
	v_pk_mul_f32 v[116:117], v[168:169], v[116:117] op_sel_hi:[0,1]
	v_exp_f32_e32 v165, v165
	v_mul_f32_e32 v169, 0xbfb8aa3b, v127
	v_exp_f32_e32 v169, v169
	v_rcp_f32_e32 v171, v153
	v_add_f32_e32 v153, 1.0, v165
	v_rcp_f32_e32 v172, v153
	v_add_f32_e32 v153, 1.0, v169
	v_rcp_f32_e32 v173, v153
	v_pk_mul_f32 v[124:125], v[124:125], v[170:171]
	v_pk_mul_f32 v[120:121], v[168:169], v[120:121] op_sel_hi:[0,1]
	v_pk_mul_f32 v[116:117], v[124:125], v[116:117]
	v_pk_mul_f32 v[124:125], v[126:127], v[172:173]
	v_mul_f32_e32 v126, 0xbfb8aa3b, v120
	v_exp_f32_e32 v126, v126
	v_pk_mul_f32 v[118:119], v[168:169], v[118:119] op_sel_hi:[0,1]
	v_pk_mul_f32 v[118:119], v[124:125], v[118:119]
	v_mul_f32_e32 v124, 0xbfb8aa3b, v121
	v_pk_mul_f32 v[122:123], v[168:169], v[122:123] op_sel_hi:[0,1]
	v_exp_f32_e32 v125, v124
	v_add_f32_e32 v124, 1.0, v126
	v_mul_f32_e32 v126, 0xbfb8aa3b, v122
	v_mul_f32_e32 v127, 0xbfb8aa3b, v123
	v_exp_f32_e32 v126, v126
	v_exp_f32_e32 v127, v127
	v_add_f32_e32 v125, 1.0, v125
	v_rcp_f32_e32 v124, v124
	v_rcp_f32_e32 v125, v125
	v_add_f32_e32 v126, 1.0, v126
	v_add_f32_e32 v127, 1.0, v127
	v_rcp_f32_e32 v126, v126
	v_rcp_f32_e32 v127, v127
	v_pk_mul_f32 v[112:113], v[168:169], v[112:113] op_sel_hi:[0,1]
	v_pk_mul_f32 v[120:121], v[120:121], v[124:125]
	v_cmp_gt_f32_e32 vcc, s46, v164
	v_pk_mul_f32 v[120:121], v[120:121], v[112:113]
	v_pk_mul_f32 v[112:113], v[168:169], v[114:115] op_sel_hi:[0,1]
	v_pk_mul_f32 v[114:115], v[122:123], v[126:127]
	s_nop 0
	v_pk_mul_f32 v[122:123], v[114:115], v[112:113]
	v_mul_f32_e32 v113, 0x4b800000, v164
	v_cndmask_b32_e32 v113, v164, v113, vcc
	v_cvt_pk_bf16_f32 v112, v116, v117
	v_rsq_f32_e32 v116, v113
	v_cvt_pk_bf16_f32 v113, v118, v119
	v_cvt_pk_bf16_f32 v114, v120, v121
	v_cvt_pk_bf16_f32 v115, v122, v123
	v_mul_f32_e32 v117, 0x45800000, v116
	v_cndmask_b32_e32 v116, v116, v117, vcc
	v_pk_mul_f32 v[108:109], v[116:117], v[108:109] op_sel_hi:[0,1]
	v_mul_f32_e32 v117, 0xbfb8aa3b, v108
	v_exp_f32_e32 v117, v117
	global_store_dwordx4 v[166:167], v[112:115], off
	v_pk_mul_f32 v[110:111], v[116:117], v[110:111] op_sel_hi:[0,1]
	s_nop 0
	v_mul_f32_e32 v112, 0xbfb8aa3b, v109
	v_exp_f32_e32 v113, v112
	v_mul_f32_e32 v114, 0xbfb8aa3b, v110
	v_mul_f32_e32 v115, 0xbfb8aa3b, v111
	v_exp_f32_e32 v114, v114
	v_exp_f32_e32 v115, v115
	v_add_f32_e32 v112, 1.0, v117
	v_add_f32_e32 v113, 1.0, v113
	v_rcp_f32_e32 v112, v112
	v_rcp_f32_e32 v113, v113
	v_add_f32_e32 v114, 1.0, v114
	v_add_f32_e32 v115, 1.0, v115
	v_rcp_f32_e32 v114, v114
	v_rcp_f32_e32 v115, v115
	v_pk_mul_f32 v[100:101], v[116:117], v[100:101] op_sel_hi:[0,1]
	v_pk_mul_f32 v[108:109], v[108:109], v[112:113]
	v_pk_mul_f32 v[104:105], v[116:117], v[104:105] op_sel_hi:[0,1]
	v_pk_mul_f32 v[100:101], v[108:109], v[100:101]
	v_pk_mul_f32 v[108:109], v[110:111], v[114:115]
	v_mul_f32_e32 v110, 0xbfb8aa3b, v104
	v_exp_f32_e32 v110, v110
	v_pk_mul_f32 v[102:103], v[116:117], v[102:103] op_sel_hi:[0,1]
	v_pk_mul_f32 v[102:103], v[108:109], v[102:103]
	v_mul_f32_e32 v108, 0xbfb8aa3b, v105
	v_pk_mul_f32 v[106:107], v[116:117], v[106:107] op_sel_hi:[0,1]
	v_exp_f32_e32 v109, v108
	v_add_f32_e32 v108, 1.0, v110
	v_mul_f32_e32 v110, 0xbfb8aa3b, v106
	v_mul_f32_e32 v111, 0xbfb8aa3b, v107
	v_exp_f32_e32 v110, v110
	v_exp_f32_e32 v111, v111
	v_add_f32_e32 v109, 1.0, v109
	v_rcp_f32_e32 v108, v108
	v_rcp_f32_e32 v109, v109
	v_add_f32_e32 v110, 1.0, v110
	v_add_f32_e32 v111, 1.0, v111
	v_rcp_f32_e32 v110, v110
	v_rcp_f32_e32 v111, v111
	v_pk_mul_f32 v[96:97], v[116:117], v[96:97] op_sel_hi:[0,1]
	v_pk_mul_f32 v[104:105], v[104:105], v[108:109]
	s_nop 0
	v_pk_mul_f32 v[104:105], v[104:105], v[96:97]
	v_pk_mul_f32 v[96:97], v[116:117], v[98:99] op_sel_hi:[0,1]
	v_pk_mul_f32 v[98:99], v[106:107], v[110:111]
	s_nop 0
	v_pk_mul_f32 v[106:107], v[98:99], v[96:97]
	v_cvt_pk_bf16_f32 v96, v100, v101
	v_or_b32_e32 v100, 16, v152
	v_mad_i64_i32 v[100:101], s[28:29], v100, s45, v[154:155]
	v_cvt_pk_bf16_f32 v97, v102, v103
	v_cvt_pk_bf16_f32 v98, v104, v105
	v_cvt_pk_bf16_f32 v99, v106, v107
	v_lshl_add_u64 v[100:101], v[100:101], 0, v[156:157]
	global_store_dwordx4 v[100:101], v[96:99], off
	s_nop 1
	v_pk_fma_f32 v[96:97], v[146:147], s[18:19], v[158:159] op_sel_hi:[1,0,0]
	s_nop 0
	v_mul_f32_e32 v98, 0x4b800000, v97
	v_cmp_gt_f32_e32 vcc, s46, v97
	s_nop 1
	v_cndmask_b32_e32 v97, v97, v98, vcc
	v_rsq_f32_e32 v97, v97
	v_or_b32_e32 v98, 32, v152
	v_mad_i64_i32 v[98:99], s[28:29], v98, s45, v[154:155]
	v_mul_f32_e32 v100, 0x45800000, v97
	v_cndmask_b32_e32 v100, v97, v100, vcc
	v_pk_mul_f32 v[92:93], v[100:101], v[92:93] op_sel_hi:[0,1]
	v_mul_f32_e32 v97, 0xbfb8aa3b, v92
	v_mul_f32_e32 v101, 0xbfb8aa3b, v93
	v_exp_f32_e32 v97, v97
	v_exp_f32_e32 v101, v101
	v_cmp_gt_f32_e32 vcc, s46, v96
	v_lshl_add_u64 v[98:99], v[98:99], 0, v[156:157]
	v_add_f32_e32 v97, 1.0, v97
	v_pk_mul_f32 v[94:95], v[100:101], v[94:95] op_sel_hi:[0,1]
	v_rcp_f32_e32 v102, v97
	v_pk_mul_f32 v[84:85], v[100:101], v[84:85] op_sel_hi:[0,1]
	v_add_f32_e32 v97, 1.0, v101
	v_mul_f32_e32 v101, 0xbfb8aa3b, v94
	v_exp_f32_e32 v101, v101
	v_mul_f32_e32 v103, 0xbfb8aa3b, v95
	v_exp_f32_e32 v105, v103
	v_rcp_f32_e32 v103, v97
	v_add_f32_e32 v97, 1.0, v101
	v_rcp_f32_e32 v104, v97
	v_add_f32_e32 v97, 1.0, v105
	v_rcp_f32_e32 v105, v97
	v_pk_mul_f32 v[92:93], v[92:93], v[102:103]
	v_pk_mul_f32 v[88:89], v[100:101], v[88:89] op_sel_hi:[0,1]
	v_pk_mul_f32 v[84:85], v[92:93], v[84:85]
	v_pk_mul_f32 v[92:93], v[94:95], v[104:105]
	v_mul_f32_e32 v94, 0xbfb8aa3b, v88
	v_exp_f32_e32 v94, v94
	v_pk_mul_f32 v[86:87], v[100:101], v[86:87] op_sel_hi:[0,1]
	v_pk_mul_f32 v[86:87], v[92:93], v[86:87]
	v_mul_f32_e32 v92, 0xbfb8aa3b, v89
	v_pk_mul_f32 v[90:91], v[100:101], v[90:91] op_sel_hi:[0,1]
	v_exp_f32_e32 v93, v92
	v_add_f32_e32 v92, 1.0, v94
	v_mul_f32_e32 v94, 0xbfb8aa3b, v90
	v_mul_f32_e32 v95, 0xbfb8aa3b, v91
	v_exp_f32_e32 v94, v94
	v_exp_f32_e32 v95, v95
	v_add_f32_e32 v93, 1.0, v93
	v_rcp_f32_e32 v92, v92
	v_rcp_f32_e32 v93, v93
	v_add_f32_e32 v94, 1.0, v94
	v_add_f32_e32 v95, 1.0, v95
	v_rcp_f32_e32 v94, v94
	v_rcp_f32_e32 v95, v95
	v_pk_mul_f32 v[80:81], v[100:101], v[80:81] op_sel_hi:[0,1]
	v_pk_mul_f32 v[88:89], v[88:89], v[92:93]
	s_nop 0
	v_pk_mul_f32 v[88:89], v[88:89], v[80:81]
	v_pk_mul_f32 v[80:81], v[100:101], v[82:83] op_sel_hi:[0,1]
	v_pk_mul_f32 v[82:83], v[90:91], v[94:95]
	s_nop 0
	v_pk_mul_f32 v[90:91], v[82:83], v[80:81]
	v_mul_f32_e32 v81, 0x4b800000, v96
	v_cndmask_b32_e32 v81, v96, v81, vcc
	v_cvt_pk_bf16_f32 v80, v84, v85
	v_rsq_f32_e32 v84, v81
	v_cvt_pk_bf16_f32 v81, v86, v87
	v_cvt_pk_bf16_f32 v82, v88, v89
	v_cvt_pk_bf16_f32 v83, v90, v91
	v_mul_f32_e32 v85, 0x45800000, v84
	v_cndmask_b32_e32 v84, v84, v85, vcc
	v_pk_mul_f32 v[76:77], v[84:85], v[76:77] op_sel_hi:[0,1]
	v_mul_f32_e32 v85, 0xbfb8aa3b, v76
	v_exp_f32_e32 v85, v85
	global_store_dwordx4 v[98:99], v[80:83], off
	v_pk_mul_f32 v[78:79], v[84:85], v[78:79] op_sel_hi:[0,1]
	s_nop 0
	v_mul_f32_e32 v80, 0xbfb8aa3b, v77
	v_exp_f32_e32 v81, v80
	v_mul_f32_e32 v82, 0xbfb8aa3b, v78
	v_mul_f32_e32 v83, 0xbfb8aa3b, v79
	v_exp_f32_e32 v82, v82
	v_exp_f32_e32 v83, v83
	v_add_f32_e32 v80, 1.0, v85
	v_add_f32_e32 v81, 1.0, v81
	v_rcp_f32_e32 v80, v80
	v_rcp_f32_e32 v81, v81
	v_add_f32_e32 v82, 1.0, v82
	v_add_f32_e32 v83, 1.0, v83
	v_rcp_f32_e32 v82, v82
	v_rcp_f32_e32 v83, v83
	v_pk_mul_f32 v[68:69], v[84:85], v[68:69] op_sel_hi:[0,1]
	v_pk_mul_f32 v[76:77], v[76:77], v[80:81]
	v_pk_mul_f32 v[72:73], v[84:85], v[72:73] op_sel_hi:[0,1]
	v_pk_mul_f32 v[68:69], v[76:77], v[68:69]
	v_pk_mul_f32 v[76:77], v[78:79], v[82:83]
	v_mul_f32_e32 v78, 0xbfb8aa3b, v72
	v_exp_f32_e32 v78, v78
	v_pk_mul_f32 v[70:71], v[84:85], v[70:71] op_sel_hi:[0,1]
	v_pk_mul_f32 v[70:71], v[76:77], v[70:71]
	v_mul_f32_e32 v76, 0xbfb8aa3b, v73
	v_pk_mul_f32 v[74:75], v[84:85], v[74:75] op_sel_hi:[0,1]
	v_exp_f32_e32 v77, v76
	v_add_f32_e32 v76, 1.0, v78
	v_mul_f32_e32 v78, 0xbfb8aa3b, v74
	v_mul_f32_e32 v79, 0xbfb8aa3b, v75
	v_exp_f32_e32 v78, v78
	v_exp_f32_e32 v79, v79
	v_add_f32_e32 v77, 1.0, v77
	v_rcp_f32_e32 v76, v76
	v_rcp_f32_e32 v77, v77
	v_add_f32_e32 v78, 1.0, v78
	v_add_f32_e32 v79, 1.0, v79
	v_rcp_f32_e32 v78, v78
	v_rcp_f32_e32 v79, v79
	v_pk_mul_f32 v[64:65], v[84:85], v[64:65] op_sel_hi:[0,1]
	v_pk_mul_f32 v[72:73], v[72:73], v[76:77]
	s_nop 0
	v_pk_mul_f32 v[72:73], v[72:73], v[64:65]
	v_pk_mul_f32 v[64:65], v[84:85], v[66:67] op_sel_hi:[0,1]
	v_pk_mul_f32 v[66:67], v[74:75], v[78:79]
	s_nop 0
	v_pk_mul_f32 v[74:75], v[66:67], v[64:65]
	v_cvt_pk_bf16_f32 v64, v68, v69
	v_or_b32_e32 v68, 48, v152
	v_mad_i64_i32 v[68:69], s[28:29], v68, s45, v[154:155]
	v_cvt_pk_bf16_f32 v65, v70, v71
	v_cvt_pk_bf16_f32 v66, v72, v73
	v_cvt_pk_bf16_f32 v67, v74, v75
	v_lshl_add_u64 v[68:69], v[68:69], 0, v[156:157]
	global_store_dwordx4 v[68:69], v[64:67], off
	s_nop 1
	v_pk_fma_f32 v[64:65], v[144:145], s[18:19], v[158:159] op_sel_hi:[1,0,0]
	s_nop 0
	v_mul_f32_e32 v66, 0x4b800000, v65
	v_cmp_gt_f32_e32 vcc, s46, v65
	s_nop 1
	v_cndmask_b32_e32 v65, v65, v66, vcc
	v_rsq_f32_e32 v65, v65
	v_add_u32_e32 v66, 0x80, v152
	v_mad_i64_i32 v[66:67], s[28:29], v66, s45, v[154:155]
	v_mul_f32_e32 v68, 0x45800000, v65
	v_cndmask_b32_e32 v68, v65, v68, vcc
	v_pk_mul_f32 v[60:61], v[68:69], v[60:61] op_sel_hi:[0,1]
	v_mul_f32_e32 v65, 0xbfb8aa3b, v60
	v_mul_f32_e32 v69, 0xbfb8aa3b, v61
	v_exp_f32_e32 v65, v65
	v_exp_f32_e32 v69, v69
	v_cmp_gt_f32_e32 vcc, s46, v64
	v_lshl_add_u64 v[66:67], v[66:67], 0, v[156:157]
	v_add_f32_e32 v65, 1.0, v65
	v_pk_mul_f32 v[62:63], v[68:69], v[62:63] op_sel_hi:[0,1]
	v_rcp_f32_e32 v70, v65
	v_pk_mul_f32 v[52:53], v[68:69], v[52:53] op_sel_hi:[0,1]
	v_add_f32_e32 v65, 1.0, v69
	v_mul_f32_e32 v69, 0xbfb8aa3b, v62
	v_exp_f32_e32 v69, v69
	v_mul_f32_e32 v71, 0xbfb8aa3b, v63
	v_exp_f32_e32 v73, v71
	v_rcp_f32_e32 v71, v65
	v_add_f32_e32 v65, 1.0, v69
	v_rcp_f32_e32 v72, v65
	v_add_f32_e32 v65, 1.0, v73
	v_rcp_f32_e32 v73, v65
	v_pk_mul_f32 v[60:61], v[60:61], v[70:71]
	v_pk_mul_f32 v[56:57], v[68:69], v[56:57] op_sel_hi:[0,1]
	v_pk_mul_f32 v[52:53], v[60:61], v[52:53]
	v_pk_mul_f32 v[60:61], v[62:63], v[72:73]
	v_mul_f32_e32 v62, 0xbfb8aa3b, v56
	v_exp_f32_e32 v62, v62
	v_pk_mul_f32 v[54:55], v[68:69], v[54:55] op_sel_hi:[0,1]
	v_pk_mul_f32 v[54:55], v[60:61], v[54:55]
	v_mul_f32_e32 v60, 0xbfb8aa3b, v57
	v_pk_mul_f32 v[58:59], v[68:69], v[58:59] op_sel_hi:[0,1]
	v_exp_f32_e32 v61, v60
	v_add_f32_e32 v60, 1.0, v62
	v_mul_f32_e32 v62, 0xbfb8aa3b, v58
	v_mul_f32_e32 v63, 0xbfb8aa3b, v59
	v_exp_f32_e32 v62, v62
	v_exp_f32_e32 v63, v63
	v_add_f32_e32 v61, 1.0, v61
	v_rcp_f32_e32 v60, v60
	v_rcp_f32_e32 v61, v61
	v_add_f32_e32 v62, 1.0, v62
	v_add_f32_e32 v63, 1.0, v63
	v_rcp_f32_e32 v62, v62
	v_rcp_f32_e32 v63, v63
	v_pk_mul_f32 v[48:49], v[68:69], v[48:49] op_sel_hi:[0,1]
	v_pk_mul_f32 v[56:57], v[56:57], v[60:61]
	s_nop 0
	v_pk_mul_f32 v[56:57], v[56:57], v[48:49]
	v_pk_mul_f32 v[48:49], v[68:69], v[50:51] op_sel_hi:[0,1]
	v_pk_mul_f32 v[50:51], v[58:59], v[62:63]
	s_nop 0
	v_pk_mul_f32 v[58:59], v[50:51], v[48:49]
	v_mul_f32_e32 v49, 0x4b800000, v64
	v_cndmask_b32_e32 v49, v64, v49, vcc
	v_cvt_pk_bf16_f32 v48, v52, v53
	v_rsq_f32_e32 v52, v49
	v_cvt_pk_bf16_f32 v49, v54, v55
	v_cvt_pk_bf16_f32 v50, v56, v57
	v_cvt_pk_bf16_f32 v51, v58, v59
	v_mul_f32_e32 v53, 0x45800000, v52
	v_cndmask_b32_e32 v52, v52, v53, vcc
	v_pk_mul_f32 v[44:45], v[52:53], v[44:45] op_sel_hi:[0,1]
	v_mul_f32_e32 v53, 0xbfb8aa3b, v44
	v_exp_f32_e32 v53, v53
	global_store_dwordx4 v[66:67], v[48:51], off
	v_pk_mul_f32 v[46:47], v[52:53], v[46:47] op_sel_hi:[0,1]
	s_nop 0
	v_mul_f32_e32 v48, 0xbfb8aa3b, v45
	v_exp_f32_e32 v49, v48
	v_mul_f32_e32 v50, 0xbfb8aa3b, v46
	v_mul_f32_e32 v51, 0xbfb8aa3b, v47
	v_exp_f32_e32 v50, v50
	v_exp_f32_e32 v51, v51
	v_add_f32_e32 v48, 1.0, v53
	v_add_f32_e32 v49, 1.0, v49
	v_rcp_f32_e32 v48, v48
	v_rcp_f32_e32 v49, v49
	v_add_f32_e32 v50, 1.0, v50
	v_add_f32_e32 v51, 1.0, v51
	v_rcp_f32_e32 v50, v50
	v_rcp_f32_e32 v51, v51
	v_pk_mul_f32 v[36:37], v[52:53], v[36:37] op_sel_hi:[0,1]
	v_pk_mul_f32 v[44:45], v[44:45], v[48:49]
	v_pk_mul_f32 v[40:41], v[52:53], v[40:41] op_sel_hi:[0,1]
	v_pk_mul_f32 v[36:37], v[44:45], v[36:37]
	v_pk_mul_f32 v[44:45], v[46:47], v[50:51]
	v_mul_f32_e32 v46, 0xbfb8aa3b, v40
	v_exp_f32_e32 v46, v46
	v_pk_mul_f32 v[38:39], v[52:53], v[38:39] op_sel_hi:[0,1]
	v_pk_mul_f32 v[38:39], v[44:45], v[38:39]
	v_mul_f32_e32 v44, 0xbfb8aa3b, v41
	v_pk_mul_f32 v[42:43], v[52:53], v[42:43] op_sel_hi:[0,1]
	v_exp_f32_e32 v45, v44
	v_add_f32_e32 v44, 1.0, v46
	v_mul_f32_e32 v46, 0xbfb8aa3b, v42
	v_mul_f32_e32 v47, 0xbfb8aa3b, v43
	v_exp_f32_e32 v46, v46
	v_exp_f32_e32 v47, v47
	v_add_f32_e32 v45, 1.0, v45
	v_rcp_f32_e32 v44, v44
	v_rcp_f32_e32 v45, v45
	v_add_f32_e32 v46, 1.0, v46
	v_add_f32_e32 v47, 1.0, v47
	v_rcp_f32_e32 v46, v46
	v_rcp_f32_e32 v47, v47
	v_pk_mul_f32 v[32:33], v[52:53], v[32:33] op_sel_hi:[0,1]
	v_pk_mul_f32 v[40:41], v[40:41], v[44:45]
	s_nop 0
	v_pk_mul_f32 v[40:41], v[40:41], v[32:33]
	v_pk_mul_f32 v[32:33], v[52:53], v[34:35] op_sel_hi:[0,1]
	v_pk_mul_f32 v[34:35], v[42:43], v[46:47]
	s_nop 0
	v_pk_mul_f32 v[42:43], v[34:35], v[32:33]
	v_cvt_pk_bf16_f32 v32, v36, v37
	v_add_u32_e32 v36, 0x90, v152
	v_mad_i64_i32 v[36:37], s[28:29], v36, s45, v[154:155]
	v_cvt_pk_bf16_f32 v33, v38, v39
	v_cvt_pk_bf16_f32 v34, v40, v41
	v_cvt_pk_bf16_f32 v35, v42, v43
	v_lshl_add_u64 v[36:37], v[36:37], 0, v[156:157]
	global_store_dwordx4 v[36:37], v[32:35], off
	s_nop 1
	v_pk_fma_f32 v[32:33], v[150:151], s[18:19], v[158:159] op_sel_hi:[1,0,0]
	s_nop 0
	v_mul_f32_e32 v34, 0x4b800000, v33
	v_cmp_gt_f32_e32 vcc, s46, v33
	s_nop 1
	v_cndmask_b32_e32 v33, v33, v34, vcc
	v_rsq_f32_e32 v33, v33
	v_add_u32_e32 v34, 0xa0, v152
	v_mad_i64_i32 v[34:35], s[28:29], v34, s45, v[154:155]
	v_mul_f32_e32 v36, 0x45800000, v33
	v_cndmask_b32_e32 v36, v33, v36, vcc
	v_pk_mul_f32 v[28:29], v[36:37], v[28:29] op_sel_hi:[0,1]
	v_mul_f32_e32 v33, 0xbfb8aa3b, v28
	v_mul_f32_e32 v37, 0xbfb8aa3b, v29
	v_exp_f32_e32 v33, v33
	v_exp_f32_e32 v37, v37
	v_cmp_gt_f32_e32 vcc, s46, v32
	v_lshl_add_u64 v[34:35], v[34:35], 0, v[156:157]
	v_add_f32_e32 v33, 1.0, v33
	v_pk_mul_f32 v[30:31], v[36:37], v[30:31] op_sel_hi:[0,1]
	v_rcp_f32_e32 v38, v33
	v_pk_mul_f32 v[20:21], v[36:37], v[20:21] op_sel_hi:[0,1]
	v_add_f32_e32 v33, 1.0, v37
	v_mul_f32_e32 v37, 0xbfb8aa3b, v30
	v_exp_f32_e32 v37, v37
	v_mul_f32_e32 v39, 0xbfb8aa3b, v31
	v_exp_f32_e32 v41, v39
	v_rcp_f32_e32 v39, v33
	v_add_f32_e32 v33, 1.0, v37
	v_rcp_f32_e32 v40, v33
	v_add_f32_e32 v33, 1.0, v41
	v_rcp_f32_e32 v41, v33
	v_pk_mul_f32 v[28:29], v[28:29], v[38:39]
	v_pk_mul_f32 v[24:25], v[36:37], v[24:25] op_sel_hi:[0,1]
	v_pk_mul_f32 v[20:21], v[28:29], v[20:21]
	v_pk_mul_f32 v[28:29], v[30:31], v[40:41]
	v_mul_f32_e32 v30, 0xbfb8aa3b, v24
	v_exp_f32_e32 v30, v30
	v_pk_mul_f32 v[22:23], v[36:37], v[22:23] op_sel_hi:[0,1]
	v_pk_mul_f32 v[22:23], v[28:29], v[22:23]
	v_mul_f32_e32 v28, 0xbfb8aa3b, v25
	v_pk_mul_f32 v[26:27], v[36:37], v[26:27] op_sel_hi:[0,1]
	v_exp_f32_e32 v29, v28
	v_add_f32_e32 v28, 1.0, v30
	v_mul_f32_e32 v30, 0xbfb8aa3b, v26
	v_mul_f32_e32 v31, 0xbfb8aa3b, v27
	v_exp_f32_e32 v30, v30
	v_exp_f32_e32 v31, v31
	v_add_f32_e32 v29, 1.0, v29
	v_rcp_f32_e32 v28, v28
	v_rcp_f32_e32 v29, v29
	v_add_f32_e32 v30, 1.0, v30
	v_add_f32_e32 v31, 1.0, v31
	v_rcp_f32_e32 v30, v30
	v_rcp_f32_e32 v31, v31
	v_pk_mul_f32 v[16:17], v[36:37], v[16:17] op_sel_hi:[0,1]
	v_pk_mul_f32 v[24:25], v[24:25], v[28:29]
	s_nop 0
	v_pk_mul_f32 v[24:25], v[24:25], v[16:17]
	v_pk_mul_f32 v[16:17], v[36:37], v[18:19] op_sel_hi:[0,1]
	v_pk_mul_f32 v[18:19], v[26:27], v[30:31]
	s_nop 0
	v_pk_mul_f32 v[26:27], v[18:19], v[16:17]
	v_mul_f32_e32 v17, 0x4b800000, v32
	v_cndmask_b32_e32 v17, v32, v17, vcc
	v_cvt_pk_bf16_f32 v16, v20, v21
	v_rsq_f32_e32 v20, v17
	v_cvt_pk_bf16_f32 v17, v22, v23
	v_cvt_pk_bf16_f32 v18, v24, v25
	v_cvt_pk_bf16_f32 v19, v26, v27
	v_mul_f32_e32 v21, 0x45800000, v20
	v_cndmask_b32_e32 v20, v20, v21, vcc
	v_pk_mul_f32 v[12:13], v[20:21], v[12:13] op_sel_hi:[0,1]
	v_mul_f32_e32 v21, 0xbfb8aa3b, v12
	v_exp_f32_e32 v21, v21
	global_store_dwordx4 v[34:35], v[16:19], off
	s_andn2_b64 vcc, exec, s[0:1]
	s_mov_b64 s[0:1], -1
	v_mul_f32_e32 v16, 0xbfb8aa3b, v13
	v_pk_mul_f32 v[14:15], v[20:21], v[14:15] op_sel_hi:[0,1]
	v_exp_f32_e32 v17, v16
	v_mul_f32_e32 v18, 0xbfb8aa3b, v14
	v_mul_f32_e32 v19, 0xbfb8aa3b, v15
	v_exp_f32_e32 v18, v18
	v_exp_f32_e32 v19, v19
	v_add_f32_e32 v16, 1.0, v21
	v_add_f32_e32 v17, 1.0, v17
	v_rcp_f32_e32 v16, v16
	v_rcp_f32_e32 v17, v17
	v_add_f32_e32 v18, 1.0, v18
	v_add_f32_e32 v19, 1.0, v19
	v_rcp_f32_e32 v18, v18
	v_rcp_f32_e32 v19, v19
	v_pk_mul_f32 v[4:5], v[20:21], v[4:5] op_sel_hi:[0,1]
	v_pk_mul_f32 v[12:13], v[12:13], v[16:17]
	v_pk_mul_f32 v[8:9], v[20:21], v[8:9] op_sel_hi:[0,1]
	v_pk_mul_f32 v[4:5], v[12:13], v[4:5]
	v_pk_mul_f32 v[12:13], v[14:15], v[18:19]
	v_mul_f32_e32 v14, 0xbfb8aa3b, v8
	v_exp_f32_e32 v14, v14
	v_pk_mul_f32 v[6:7], v[20:21], v[6:7] op_sel_hi:[0,1]
	v_pk_mul_f32 v[6:7], v[12:13], v[6:7]
	v_mul_f32_e32 v12, 0xbfb8aa3b, v9
	v_pk_mul_f32 v[10:11], v[20:21], v[10:11] op_sel_hi:[0,1]
	v_exp_f32_e32 v13, v12
	v_add_f32_e32 v12, 1.0, v14
	v_mul_f32_e32 v14, 0xbfb8aa3b, v10
	v_mul_f32_e32 v15, 0xbfb8aa3b, v11
	v_exp_f32_e32 v14, v14
	v_exp_f32_e32 v15, v15
	v_add_f32_e32 v13, 1.0, v13
	v_rcp_f32_e32 v12, v12
	v_rcp_f32_e32 v13, v13
	v_add_f32_e32 v14, 1.0, v14
	v_add_f32_e32 v15, 1.0, v15
	v_rcp_f32_e32 v14, v14
	v_rcp_f32_e32 v15, v15
	v_pk_mul_f32 v[0:1], v[20:21], v[0:1] op_sel_hi:[0,1]
	v_pk_mul_f32 v[8:9], v[8:9], v[12:13]
	s_nop 0
	v_pk_mul_f32 v[8:9], v[8:9], v[0:1]
	v_pk_mul_f32 v[0:1], v[20:21], v[2:3] op_sel_hi:[0,1]
	v_pk_mul_f32 v[2:3], v[10:11], v[14:15]
	s_nop 0
	v_pk_mul_f32 v[10:11], v[2:3], v[0:1]
	v_cvt_pk_bf16_f32 v0, v4, v5
	v_add_u32_e32 v4, 0xb0, v152
	v_mad_i64_i32 v[4:5], s[28:29], v4, s45, v[154:155]
	v_cvt_pk_bf16_f32 v1, v6, v7
	v_cvt_pk_bf16_f32 v2, v8, v9
	v_cvt_pk_bf16_f32 v3, v10, v11
	v_lshl_add_u64 v[4:5], v[4:5], 0, v[156:157]
	global_store_dwordx4 v[4:5], v[0:3], off
	s_cbranch_vccnz .LBB0_128
	s_andn2_b64 vcc, exec, s[4:5]
	s_cbranch_vccnz .LBB0_127
	s_barrier
	s_branch .LBB0_127

.LBB0_220:
	v_cndmask_b32_e64 v0, 0, 1, s[0:1]
	s_add_u32 s16, s88, 0x3a110000
	v_cmp_ne_u32_e64 s[4:5], 1, v0
	s_addc_u32 s17, s89, 0
	s_andn2_b64 vcc, exec, s[0:1]
	v_writelane_b32 v237, s4, 30
	s_nop 1
	v_writelane_b32 v237, s5, 31
	s_cbranch_vccnz .LBB0_260
	v_ashrrev_i32_e32 v1, 31, v8
	v_lshrrev_b32_e32 v1, 26, v1
	v_add_u32_e32 v1, v8, v1
	v_ashrrev_i32_e32 v9, 6, v1
	v_bfe_i32 v1, v8, 27, 1
	v_lshlrev_b32_e32 v0, 4, v8
	v_lshrrev_b32_e32 v1, 22, v1
	v_add_u32_e32 v1, v0, v1
	v_and_b32_e32 v1, 0xfffffc00, v1
	v_sub_u32_e32 v1, v0, v1
	v_lshrrev_b32_e32 v2, 4, v1
	v_bitop3_b32 v1, v2, v1, 32 bitop3:0x6c
	v_ashrrev_i32_e32 v3, 31, v1
	v_lshrrev_b32_e32 v3, 26, v3
	v_lshlrev_b32_e32 v2, 3, v9
	v_add_u32_e32 v3, v1, v3
	v_and_b32_e32 v2, -16, v2
	v_ashrrev_i32_e32 v10, 6, v3
	v_and_b32_e32 v3, 0xc0, v3
	v_add_u32_e32 v2, v10, v2
	v_lshlrev_b32_e32 v4, 5, v9
	v_sub_u32_e32 v1, v1, v3
	v_mov_b32_e32 v3, 1
	v_and_b32_e32 v11, 32, v4
	v_ashrrev_i16_sdwa v1, v3, sext(v1) dst_sel:DWORD dst_unused:UNUSED_PAD src0_sel:DWORD src1_sel:BYTE_0
	v_lshlrev_b32_e32 v4, 1, v2
	v_lshrrev_b32_e32 v5, 2, v2
	v_and_b32_e32 v6, 3, v10
	s_mov_b32 s4, 0x7fffe0
	v_bfe_i32 v12, v1, 0, 16
	v_and_b32_e32 v4, 24, v4
	v_and_b32_e32 v5, 4, v5
	v_and_or_b32 v6, v2, s4, v6
	s_movk_i32 s1, 0x1600
	v_add_u32_e32 v1, v11, v12
	v_or3_b32 v4, v6, v5, v4
	v_mul_lo_u32 v2, v2, s1
	v_add_lshl_u32 v128, v1, v2, 1
	v_mul_u32_u24_e32 v2, 0x1600, v4
	v_add_u32_e32 v0, 0x2000, v0
	v_add_lshl_u32 v130, v2, v1, 1
	v_ashrrev_i32_e32 v1, 31, v0
	v_lshrrev_b32_e32 v1, 22, v1
	v_add_u32_e32 v1, v0, v1
	v_ashrrev_i32_e32 v13, 10, v1
	v_mul_i32_i24_e32 v1, 0x400, v13
	v_sub_u32_e32 v0, v0, v1
	v_lshrrev_b32_e32 v1, 4, v0
	v_bitop3_b32 v0, v1, v0, 32 bitop3:0x6c
	v_ashrrev_i32_e32 v2, 31, v0
	v_lshrrev_b32_e32 v2, 26, v2
	v_lshlrev_b32_e32 v1, 3, v13
	v_add_u32_e32 v2, v0, v2
	v_and_b32_e32 v1, -16, v1
	v_ashrrev_i32_e32 v14, 6, v2
	v_lshlrev_b32_e32 v4, 5, v13
	v_add_u32_e32 v1, v14, v1
	v_and_b32_e32 v15, 32, v4
	v_and_b32_e32 v4, 3, v14
	v_and_b32_e32 v2, 0xc0, v2
	v_and_or_b32 v4, v1, s4, v4
	s_ashr_i32 s4, s6, 6
	s_ashr_i32 s0, s6, 8
	v_sub_u32_e32 v0, v0, v2
	s_lshl_b32 s30, s4, 10
	s_mul_i32 s9, s47, 0x2c0000
	v_ashrrev_i16_sdwa v0, v3, sext(v0) dst_sel:DWORD dst_unused:UNUSED_PAD src0_sel:DWORD src1_sel:BYTE_0
	v_lshlrev_b32_e32 v2, 1, v1
	v_lshrrev_b32_e32 v3, 2, v1
	s_mul_hi_i32 s8, s47, 0x2c0000
	s_add_u32 s24, s2, s9
	v_bfe_i32 v16, v0, 0, 16
	v_and_b32_e32 v2, 24, v2
	v_and_b32_e32 v3, 4, v3
	s_addc_u32 s25, s3, s8
	s_add_i32 s31, s30, 0
	v_add_u32_e32 v0, v15, v16
	v_or3_b32 v2, v4, v3, v2
	v_mul_lo_u32 v1, v1, s1
	s_add_i32 m0, s31, 0x10000
	v_add_lshl_u32 v132, v0, v1, 1
	v_mul_u32_u24_e32 v1, 0x1600, v2
	global_load_lds_dwordx4 v130, s[24:25]
	s_add_i32 m0, s31, 0x12000
	v_add_lshl_u32 v134, v1, v0, 1
	s_add_u32 s8, s24, 0x160000
	global_load_lds_dwordx4 v134, s[24:25]
	s_addc_u32 s9, s25, 0
	s_add_i32 m0, s31, 0x14000
	s_mul_i32 s7, s46, 0x2c0000
	global_load_lds_dwordx4 v130, s[8:9]
	s_add_i32 m0, s31, 0x16000
	s_mul_hi_i32 s5, s46, 0x2c0000
	global_load_lds_dwordx4 v134, s[8:9]
	v_readlane_b32 s8, v237, 24
	v_readlane_b32 s9, v237, 25
	s_add_u32 s22, s8, s7
	s_addc_u32 s23, s9, s5
	s_add_i32 s33, s31, 0x2000
	s_mov_b32 m0, s31
	s_add_u32 s8, s22, 0x160000
	global_load_lds_dwordx4 v128, s[22:23]
	s_mov_b32 m0, s33
	s_addc_u32 s9, s23, 0
	s_add_i32 s34, s31, 0x4000
	global_load_lds_dwordx4 v132, s[22:23]
	s_mov_b32 m0, s34
	s_add_i32 s35, s31, 0x6000
	global_load_lds_dwordx4 v128, s[8:9]
	s_mov_b32 m0, s35
	v_mov_b32_e32 v131, 0
	global_load_lds_dwordx4 v132, s[8:9]
	v_mov_b32_e32 v135, v131
	v_mov_b32_e32 v129, v131
	v_mov_b32_e32 v133, v131
	s_cmp_eq_u32 s0, 1
	s_mov_b32 s36, 0
	v_lshl_add_u64 v[6:7], s[24:25], 0, v[130:131]
	v_lshl_add_u64 v[2:3], s[24:25], 0, v[134:135]
	s_mov_b32 s7, 0x16000
	v_lshl_add_u64 v[0:1], s[22:23], 0, v[128:129]
	s_cselect_b64 s[8:9], -1, 0
	s_cmp_lg_u32 s0, 1
	v_lshl_add_u64 v[4:5], s[22:23], 0, v[132:133]
	s_cbranch_scc1 .LBB0_223
	s_setprio 1
	s_barrier

.LBB0_240:
	s_setprio 0
	v_lshl_add_u32 v146, s46, 8, v148
	v_ashrrev_i32_e32 v147, 31, v146
	v_lshl_or_b32 v144, s47, 8, v150
	v_lshlrev_b64 v[156:157], 12, v[146:147]
	v_ashrrev_i32_e32 v145, 31, v144
	v_lshl_add_u64 v[156:157], s[60:61], 0, v[156:157]
	v_lshl_add_u64 v[164:165], v[144:145], 1, v[156:157]
	global_load_dwordx4 v[156:159], v[164:165], off
	global_load_dwordx4 v[160:163], v[164:165], off offset:256
	v_and_b32_e32 v166, 64, v154
	v_xor_b32_e32 v155, 16, v154
	v_add_u32_e32 v166, 64, v166
	v_xor_b32_e32 v167, 32, v154
	v_cmp_lt_i32_e32 vcc, v155, v166
	s_waitcnt vmcnt(0)
	v_lshlrev_b32_e32 v168, 16, v158
	v_cndmask_b32_e32 v155, v154, v155, vcc
	v_cmp_lt_i32_e32 vcc, v167, v166
	v_lshlrev_b32_e32 v166, 16, v156
	v_and_b32_e32 v169, 0xffff0000, v158
	v_cndmask_b32_e32 v174, v154, v167, vcc
	v_and_b32_e32 v167, 0xffff0000, v156
	v_lshlrev_b32_e32 v156, 16, v157
	v_and_b32_e32 v157, 0xffff0000, v157
	v_lshlrev_b32_e32 v158, 16, v159
	v_and_b32_e32 v159, 0xffff0000, v159
	v_lshlrev_b32_e32 v170, 16, v160
	v_and_b32_e32 v171, 0xffff0000, v160
	v_lshlrev_b32_e32 v160, 16, v161
	v_and_b32_e32 v161, 0xffff0000, v161
	v_lshlrev_b32_e32 v172, 16, v162
	v_and_b32_e32 v173, 0xffff0000, v162
	v_lshlrev_b32_e32 v162, 16, v163
	v_and_b32_e32 v163, 0xffff0000, v163
	v_pk_fma_f32 v[126:127], v[126:127], 0.5, v[156:157] op_sel_hi:[1,0,1]
	v_pk_fma_f32 v[124:125], v[124:125], 0.5, v[166:167] op_sel_hi:[1,0,1]
	v_pk_fma_f32 v[122:123], v[122:123], 0.5, v[158:159] op_sel_hi:[1,0,1]
	v_pk_fma_f32 v[120:121], v[120:121], 0.5, v[168:169] op_sel_hi:[1,0,1]
	v_pk_fma_f32 v[118:119], v[118:119], 0.5, v[160:161] op_sel_hi:[1,0,1]
	v_pk_fma_f32 v[116:117], v[116:117], 0.5, v[170:171] op_sel_hi:[1,0,1]
	v_pk_fma_f32 v[156:157], v[114:115], 0.5, v[162:163] op_sel_hi:[1,0,1]
	v_pk_fma_f32 v[158:159], v[112:113], 0.5, v[172:173] op_sel_hi:[1,0,1]
	v_cvt_pk_bf16_f32 v112, v124, v125
	v_cvt_pk_bf16_f32 v113, v126, v127
	v_mul_f32_e32 v114, v125, v125
	v_mul_f32_e32 v115, v127, v127
	v_mul_f32_e32 v125, v121, v121
	v_mul_f32_e32 v127, v123, v123
	v_mul_f32_e32 v160, v117, v117
	v_mul_f32_e32 v161, v119, v119
	v_mul_f32_e32 v162, v159, v159
	v_mul_f32_e32 v163, v157, v157
	v_fmac_f32_e32 v114, v124, v124
	v_fmac_f32_e32 v115, v126, v126
	v_fmac_f32_e32 v125, v120, v120
	v_fmac_f32_e32 v127, v122, v122
	v_fmac_f32_e32 v160, v116, v116
	v_fmac_f32_e32 v161, v118, v118
	v_fmac_f32_e32 v162, v158, v158
	v_fmac_f32_e32 v163, v156, v156
	v_add_f32_e32 v114, v114, v115
	v_add_f32_e32 v115, v125, v127
	v_add_f32_e32 v124, v160, v161
	v_add_f32_e32 v125, v162, v163
	v_add_f32_e32 v114, v114, v115
	v_add_f32_e32 v115, v124, v125
	v_lshlrev_b32_e32 v155, 2, v155
	v_add_f32_e32 v124, v114, v115
	ds_bpermute_b32 v125, v155, v124
	v_cvt_pk_bf16_f32 v114, v120, v121
	v_cvt_pk_bf16_f32 v115, v122, v123
	global_store_dwordx4 v[164:165], v[112:115], off
	v_cvt_pk_bf16_f32 v116, v116, v117
	v_cvt_pk_bf16_f32 v117, v118, v119
	s_waitcnt lgkmcnt(0)
	v_add_f32_e32 v112, v124, v125
	v_lshlrev_b32_e32 v114, 2, v174
	ds_bpermute_b32 v113, v114, v112
	v_cvt_pk_bf16_f32 v118, v158, v159
	v_cvt_pk_bf16_f32 v119, v156, v157
	global_store_dwordx4 v[164:165], v[116:119], off offset:256
	s_and_saveexec_b64 s[22:23], s[4:5]
	s_cbranch_execz .LBB0_242
	s_waitcnt lgkmcnt(0)
	v_add_f32_e32 v112, v112, v113
	v_mul_f32_e32 v112, 0x4b800000, v112
	v_rndne_f32_e32 v112, v112
	v_mul_f32_e32 v113, 0x2f800000, v112
	v_floor_f32_e32 v113, v113
	v_fmac_f32_e32 v112, 0xcf800000, v113
	v_cvt_u32_f32_e32 v112, v112
	v_cvt_u32_f32_e32 v113, v113
	v_lshl_add_u64 v[116:117], v[146:147], 3, s[16:17]
	global_atomic_add_x2 v[116:117], v[112:113], off

.LBB0_318:
	s_add_u32 s0, s88, 0x1ba00000
	v_cndmask_b32_e64 v0, 0, 1, s[4:5]
	s_addc_u32 s1, s89, 0
	v_cmp_ne_u32_e64 s[66:67], 1, v0
	s_andn2_b64 vcc, exec, s[4:5]
	s_cbranch_vccnz .LBB0_596
	v_ashrrev_i32_e32 v1, 31, v8
	v_lshrrev_b32_e32 v1, 26, v1
	v_add_u32_e32 v1, v8, v1
	v_ashrrev_i32_e32 v9, 6, v1
	v_bfe_i32 v1, v8, 27, 1
	v_lshlrev_b32_e32 v0, 4, v8
	v_lshrrev_b32_e32 v1, 22, v1
	v_add_u32_e32 v1, v0, v1
	v_and_b32_e32 v1, 0xfffffc00, v1
	v_sub_u32_e32 v1, v0, v1
	v_lshrrev_b32_e32 v2, 4, v1
	v_bitop3_b32 v1, v2, v1, 32 bitop3:0x6c
	v_ashrrev_i32_e32 v3, 31, v1
	v_lshrrev_b32_e32 v3, 26, v3
	v_add_u32_e32 v3, v1, v3
	v_lshlrev_b32_e32 v2, 3, v9
	v_ashrrev_i32_e32 v10, 6, v3
	v_and_b32_e32 v3, 0xc0, v3
	v_and_b32_e32 v2, -16, v2
	v_sub_u32_e32 v1, v1, v3
	v_mov_b32_e32 v3, 1
	v_add_u32_e32 v2, v10, v2
	v_ashrrev_i16_sdwa v1, v3, sext(v1) dst_sel:DWORD dst_unused:UNUSED_PAD src0_sel:DWORD src1_sel:BYTE_0
	v_lshlrev_b32_e32 v4, 5, v9
	v_bfe_i32 v11, v1, 0, 16
	v_lshlrev_b32_e32 v1, 1, v2
	v_lshrrev_b32_e32 v5, 2, v2
	v_and_b32_e32 v6, 3, v10
	s_mov_b32 s2, 0xfffe0
	v_and_b32_e32 v4, 32, v4
	v_and_b32_e32 v1, 24, v1
	v_and_b32_e32 v5, 4, v5
	v_and_or_b32 v6, v2, s2, v6
	v_or3_b32 v1, v6, v5, v1
	v_add_lshl_u32 v4, v4, v11, 1
	v_add_u32_e32 v0, 0x2000, v0
	v_lshl_add_u32 v130, v1, 12, v4
	v_ashrrev_i32_e32 v1, 31, v0
	v_lshrrev_b32_e32 v1, 22, v1
	v_add_u32_e32 v1, v0, v1
	v_ashrrev_i32_e32 v12, 10, v1
	v_mul_i32_i24_e32 v1, 0x400, v12
	v_sub_u32_e32 v0, v0, v1
	v_lshrrev_b32_e32 v1, 4, v0
	v_bitop3_b32 v0, v1, v0, 32 bitop3:0x6c
	v_lshl_add_u32 v128, v2, 12, v4
	v_ashrrev_i32_e32 v2, 31, v0
	v_lshrrev_b32_e32 v2, 26, v2
	v_add_u32_e32 v2, v0, v2
	v_lshlrev_b32_e32 v1, 3, v12
	v_ashrrev_i32_e32 v13, 6, v2
	v_and_b32_e32 v2, 0xc0, v2
	v_and_b32_e32 v1, -16, v1
	v_sub_u32_e32 v0, v0, v2
	v_add_u32_e32 v1, v13, v1
	v_ashrrev_i16_sdwa v0, v3, sext(v0) dst_sel:DWORD dst_unused:UNUSED_PAD src0_sel:DWORD src1_sel:BYTE_0
	v_and_b32_e32 v3, 3, v13
	s_ashr_i32 s12, s6, 6
	s_ashr_i32 s9, s8, 31
	s_ashr_i32 s29, s28, 31
	s_ashr_i32 s7, s6, 8
	v_and_or_b32 v3, v1, s2, v3
	s_lshl_b32 s2, s12, 10
	s_lshl_b64 s[4:5], s[8:9], 20
	s_lshl_b64 s[18:19], s[28:29], 20
	s_add_u32 s30, s14, s18
	v_lshlrev_b32_e32 v4, 5, v12
	v_bfe_i32 v14, v0, 0, 16
	v_lshlrev_b32_e32 v0, 1, v1
	v_lshrrev_b32_e32 v2, 2, v1
	s_addc_u32 s31, s15, s19
	s_add_i32 s3, s2, 0
	v_and_b32_e32 v4, 32, v4
	v_and_b32_e32 v0, 24, v0
	v_and_b32_e32 v2, 4, v2
	s_add_i32 m0, s3, 0x10000
	v_or3_b32 v0, v3, v2, v0
	v_add_lshl_u32 v2, v4, v14, 1
	global_load_lds_dwordx4 v130, s[30:31]
	s_add_i32 m0, s3, 0x12000
	v_lshl_add_u32 v134, v0, 12, v2
	s_add_u32 s18, s30, 0x80000
	global_load_lds_dwordx4 v134, s[30:31]
	s_addc_u32 s19, s31, 0
	s_add_i32 m0, s3, 0x14000
	v_lshl_add_u32 v132, v1, 12, v2
	global_load_lds_dwordx4 v130, s[18:19]
	s_add_i32 m0, s3, 0x16000
	s_add_u32 s34, s60, s4
	s_addc_u32 s35, s61, s5
	s_add_i32 s29, s3, 0x2000
	global_load_lds_dwordx4 v134, s[18:19]
	s_mov_b32 m0, s3
	s_add_u32 s4, s34, 0x80000
	global_load_lds_dwordx4 v128, s[34:35]
	s_mov_b32 m0, s29
	s_addc_u32 s5, s35, 0
	s_add_i32 s33, s3, 0x4000
	global_load_lds_dwordx4 v132, s[34:35]
	s_mov_b32 m0, s33
	s_add_i32 s36, s3, 0x6000
	global_load_lds_dwordx4 v128, s[4:5]
	s_mov_b32 m0, s36
	v_mov_b32_e32 v131, 0
	global_load_lds_dwordx4 v132, s[4:5]
	v_mov_b32_e32 v135, v131
	v_mov_b32_e32 v129, v131
	v_mov_b32_e32 v133, v131
	s_cmp_eq_u32 s7, 1
	s_mov_b32 s37, 0
	v_lshl_add_u64 v[6:7], s[30:31], 0, v[130:131]
	v_lshl_add_u64 v[4:5], s[30:31], 0, v[134:135]
	v_lshl_add_u64 v[0:1], s[34:35], 0, v[128:129]
	s_cselect_b64 s[4:5], -1, 0
	s_cmp_lg_u32 s7, 1
	v_lshl_add_u64 v[2:3], s[34:35], 0, v[132:133]
	s_cbranch_scc1 .LBB0_321
	s_setprio 1
	s_barrier

.LBB0_336:
	s_setprio 0
	v_fmamk_f32 v146, v153, 0x3a000000, v152
	v_mul_f32_e32 v147, 0x4b800000, v146
	v_cmp_gt_f32_e32 vcc, s45, v146
	s_cmp_gt_i32 s28, 7
	s_cselect_b64 s[30:31], -1, 0
	v_cndmask_b32_e32 v146, v146, v147, vcc
	v_rsq_f32_e32 v146, v146
	s_cmp_lt_i32 s28, 8
	v_mul_f32_e32 v147, 0x45800000, v146
	v_cndmask_b32_e32 v146, v146, v147, vcc
	v_mul_f32_e32 v124, v146, v124
	s_cbranch_scc1 .LBB0_338
	v_mul_f32_e32 v147, 0x3d372713, v124
	v_mul_f32_e32 v147, v124, v147
	v_fma_f32 v147, v124, v147, v124
	v_mul_f32_e32 v147, 0x3f4c422a, v147
	v_add_f32_e32 v147, v147, v147
	v_mul_f32_e32 v147, 0xbfb8aa3b, v147
	v_exp_f32_e32 v147, v147
	s_nop 0
	v_add_f32_e32 v147, 1.0, v147
	v_rcp_f32_e32 v147, v147
	s_nop 0
	v_mul_f32_e32 v124, v124, v147

.LBB0_1081:
	s_add_u32 s0, s88, 0x3a120000
	s_addc_u32 s1, s89, 0
	s_and_b64 vcc, exec, s[92:93]
	s_cbranch_vccnz .LBB0_1117
	v_ashrrev_i32_e32 v1, 31, v8
	v_lshrrev_b32_e32 v1, 26, v1
	v_add_u32_e32 v1, v8, v1
	v_ashrrev_i32_e32 v9, 6, v1
	v_bfe_i32 v1, v8, 27, 1
	v_lshlrev_b32_e32 v0, 4, v8
	v_lshrrev_b32_e32 v1, 22, v1
	v_add_u32_e32 v1, v0, v1
	v_and_b32_e32 v1, 0xfffffc00, v1
	v_sub_u32_e32 v1, v0, v1
	v_lshrrev_b32_e32 v2, 4, v1
	v_bitop3_b32 v1, v2, v1, 32 bitop3:0x6c
	v_ashrrev_i32_e32 v3, 31, v1
	v_lshrrev_b32_e32 v3, 26, v3
	v_add_u32_e32 v3, v1, v3
	v_lshlrev_b32_e32 v2, 3, v9
	v_ashrrev_i32_e32 v10, 6, v3
	v_and_b32_e32 v3, 0xc0, v3
	v_and_b32_e32 v2, -16, v2
	v_sub_u32_e32 v1, v1, v3
	v_mov_b32_e32 v3, 1
	v_add_u32_e32 v2, v10, v2
	v_ashrrev_i16_sdwa v1, v3, sext(v1) dst_sel:DWORD dst_unused:UNUSED_PAD src0_sel:DWORD src1_sel:BYTE_0
	v_lshlrev_b32_e32 v4, 5, v9
	v_bfe_i32 v11, v1, 0, 16
	v_lshlrev_b32_e32 v1, 1, v2
	v_lshrrev_b32_e32 v5, 2, v2
	v_and_b32_e32 v6, 3, v10
	s_mov_b32 s2, 0xfffe0
	v_and_b32_e32 v4, 32, v4
	v_and_b32_e32 v1, 24, v1
	v_and_b32_e32 v5, 4, v5
	v_and_or_b32 v6, v2, s2, v6
	v_or3_b32 v1, v6, v5, v1
	v_add_lshl_u32 v4, v4, v11, 1
	v_add_u32_e32 v0, 0x2000, v0
	v_lshl_add_u32 v130, v1, 12, v4
	v_ashrrev_i32_e32 v1, 31, v0
	v_lshrrev_b32_e32 v1, 22, v1
	v_add_u32_e32 v1, v0, v1
	v_ashrrev_i32_e32 v12, 10, v1
	v_mul_i32_i24_e32 v1, 0x400, v12
	v_sub_u32_e32 v0, v0, v1
	v_lshrrev_b32_e32 v1, 4, v0
	v_bitop3_b32 v0, v1, v0, 32 bitop3:0x6c
	v_lshl_add_u32 v128, v2, 12, v4
	v_ashrrev_i32_e32 v2, 31, v0
	v_lshrrev_b32_e32 v2, 26, v2
	v_add_u32_e32 v2, v0, v2
	v_lshlrev_b32_e32 v1, 3, v12
	v_ashrrev_i32_e32 v13, 6, v2
	v_and_b32_e32 v2, 0xc0, v2
	v_and_b32_e32 v1, -16, v1
	v_sub_u32_e32 v0, v0, v2
	v_add_u32_e32 v1, v13, v1
	v_ashrrev_i16_sdwa v0, v3, sext(v0) dst_sel:DWORD dst_unused:UNUSED_PAD src0_sel:DWORD src1_sel:BYTE_0
	v_and_b32_e32 v3, 3, v13
	s_ashr_i32 s8, s6, 6
	s_ashr_i32 s7, s6, 8
	v_and_or_b32 v3, v1, s2, v3
	s_lshl_b32 s2, s8, 10
	s_add_u32 s34, s88, 0x21a00000
	s_addc_u32 s35, s89, 0
	s_ashr_i32 s23, s22, 31
	s_ashr_i32 s25, s24, 31
	s_lshl_b64 s[4:5], s[22:23], 20
	s_lshl_b64 s[10:11], s[24:25], 20
	v_readlane_b32 s12, v237, 20
	v_readlane_b32 s13, v237, 21
	s_add_u32 s28, s12, s10
	v_lshlrev_b32_e32 v4, 5, v12
	v_bfe_i32 v14, v0, 0, 16
	v_lshlrev_b32_e32 v0, 1, v1
	v_lshrrev_b32_e32 v2, 2, v1
	s_addc_u32 s29, s13, s11
	s_add_i32 s25, s2, 0
	v_and_b32_e32 v4, 32, v4
	v_and_b32_e32 v0, 24, v0
	v_and_b32_e32 v2, 4, v2
	s_add_i32 m0, s25, 0x10000
	v_or3_b32 v0, v3, v2, v0
	v_add_lshl_u32 v2, v4, v14, 1
	global_load_lds_dwordx4 v130, s[28:29]
	s_add_i32 m0, s25, 0x12000
	v_lshl_add_u32 v134, v0, 12, v2
	s_add_u32 s10, s28, 0x80000
	global_load_lds_dwordx4 v134, s[28:29]
	s_addc_u32 s11, s29, 0
	s_add_i32 m0, s25, 0x14000
	v_lshl_add_u32 v132, v1, 12, v2
	global_load_lds_dwordx4 v130, s[10:11]
	s_add_i32 m0, s25, 0x16000
	s_add_u32 s26, s34, s4
	s_addc_u32 s27, s35, s5
	s_add_i32 s36, s25, 0x2000
	global_load_lds_dwordx4 v134, s[10:11]
	s_mov_b32 m0, s25
	s_add_u32 s4, s26, 0x80000
	global_load_lds_dwordx4 v128, s[26:27]
	s_mov_b32 m0, s36
	s_addc_u32 s5, s27, 0
	s_add_i32 s37, s25, 0x4000
	global_load_lds_dwordx4 v132, s[26:27]
	s_mov_b32 m0, s37
	s_add_i32 s38, s25, 0x6000
	global_load_lds_dwordx4 v128, s[4:5]
	s_mov_b32 m0, s38
	v_mov_b32_e32 v131, 0
	global_load_lds_dwordx4 v132, s[4:5]
	v_mov_b32_e32 v135, v131
	v_mov_b32_e32 v129, v131
	v_mov_b32_e32 v133, v131
	s_cmp_eq_u32 s7, 1
	s_mov_b32 s39, 0
	v_lshl_add_u64 v[6:7], s[28:29], 0, v[130:131]
	v_lshl_add_u64 v[4:5], s[28:29], 0, v[134:135]
	v_lshl_add_u64 v[0:1], s[26:27], 0, v[128:129]
	s_cselect_b64 s[4:5], -1, 0
	s_cmp_lg_u32 s7, 1
	v_lshl_add_u64 v[2:3], s[26:27], 0, v[132:133]
	s_cbranch_scc1 .LBB0_1084
	s_setprio 1
	s_barrier

.LBB0_1097:
	s_setprio 0
	v_lshl_add_u32 v146, s22, 8, v148
	v_ashrrev_i32_e32 v147, 31, v146
	v_lshl_or_b32 v144, s24, 8, v150
	v_lshlrev_b64 v[156:157], 12, v[146:147]
	v_ashrrev_i32_e32 v145, 31, v144
	v_lshl_add_u64 v[156:157], s[60:61], 0, v[156:157]
	v_lshl_add_u64 v[164:165], v[144:145], 1, v[156:157]
	global_load_dwordx4 v[156:159], v[164:165], off
	global_load_dwordx4 v[160:163], v[164:165], off offset:256
	v_and_b32_e32 v166, 64, v154
	v_xor_b32_e32 v155, 16, v154
	v_add_u32_e32 v166, 64, v166
	v_xor_b32_e32 v167, 32, v154
	v_cmp_lt_i32_e32 vcc, v155, v166
	s_waitcnt vmcnt(0)
	v_lshlrev_b32_e32 v168, 16, v158
	v_cndmask_b32_e32 v155, v154, v155, vcc
	v_cmp_lt_i32_e32 vcc, v167, v166
	v_lshlrev_b32_e32 v166, 16, v156
	v_and_b32_e32 v169, 0xffff0000, v158
	v_cndmask_b32_e32 v174, v154, v167, vcc
	v_and_b32_e32 v167, 0xffff0000, v156
	v_lshlrev_b32_e32 v156, 16, v157
	v_and_b32_e32 v157, 0xffff0000, v157
	v_lshlrev_b32_e32 v158, 16, v159
	v_and_b32_e32 v159, 0xffff0000, v159
	v_lshlrev_b32_e32 v170, 16, v160
	v_and_b32_e32 v171, 0xffff0000, v160
	v_lshlrev_b32_e32 v160, 16, v161
	v_and_b32_e32 v161, 0xffff0000, v161
	v_lshlrev_b32_e32 v172, 16, v162
	v_and_b32_e32 v173, 0xffff0000, v162
	v_lshlrev_b32_e32 v162, 16, v163
	v_and_b32_e32 v163, 0xffff0000, v163
	v_pk_add_f32 v[126:127], v[126:127], v[156:157]
	v_pk_add_f32 v[124:125], v[124:125], v[166:167]
	v_pk_add_f32 v[122:123], v[122:123], v[158:159]
	v_pk_add_f32 v[120:121], v[120:121], v[168:169]
	v_pk_add_f32 v[118:119], v[118:119], v[160:161]
	v_pk_add_f32 v[116:117], v[116:117], v[170:171]
	v_pk_add_f32 v[156:157], v[114:115], v[162:163]
	v_pk_add_f32 v[158:159], v[112:113], v[172:173]
	v_cvt_pk_bf16_f32 v112, v124, v125
	v_cvt_pk_bf16_f32 v113, v126, v127
	v_mul_f32_e32 v114, v125, v125
	v_mul_f32_e32 v115, v127, v127
	v_mul_f32_e32 v125, v121, v121
	v_mul_f32_e32 v127, v123, v123
	v_mul_f32_e32 v160, v117, v117
	v_mul_f32_e32 v161, v119, v119
	v_mul_f32_e32 v162, v159, v159
	v_mul_f32_e32 v163, v157, v157
	v_fmac_f32_e32 v114, v124, v124
	v_fmac_f32_e32 v115, v126, v126
	v_fmac_f32_e32 v125, v120, v120
	v_fmac_f32_e32 v127, v122, v122
	v_fmac_f32_e32 v160, v116, v116
	v_fmac_f32_e32 v161, v118, v118
	v_fmac_f32_e32 v162, v158, v158
	v_fmac_f32_e32 v163, v156, v156
	v_add_f32_e32 v114, v114, v115
	v_add_f32_e32 v115, v125, v127
	v_add_f32_e32 v124, v160, v161
	v_add_f32_e32 v125, v162, v163
	v_add_f32_e32 v114, v114, v115
	v_add_f32_e32 v115, v124, v125
	v_lshlrev_b32_e32 v155, 2, v155
	v_add_f32_e32 v124, v114, v115
	ds_bpermute_b32 v125, v155, v124
	v_cvt_pk_bf16_f32 v114, v120, v121
	v_cvt_pk_bf16_f32 v115, v122, v123
	global_store_dwordx4 v[164:165], v[112:115], off
	v_cvt_pk_bf16_f32 v116, v116, v117
	v_cvt_pk_bf16_f32 v117, v118, v119
	s_waitcnt lgkmcnt(0)
	v_add_f32_e32 v112, v124, v125
	v_lshlrev_b32_e32 v114, 2, v174
	ds_bpermute_b32 v113, v114, v112
	v_cvt_pk_bf16_f32 v118, v158, v159
	v_cvt_pk_bf16_f32 v119, v156, v157
	global_store_dwordx4 v[164:165], v[116:119], off offset:256
	s_and_saveexec_b64 s[22:23], s[6:7]
	s_cbranch_execz .LBB0_1099
	s_waitcnt lgkmcnt(0)
	v_add_f32_e32 v112, v112, v113
	v_mul_f32_e32 v112, 0x4b800000, v112
	v_rndne_f32_e32 v112, v112
	v_mul_f32_e32 v113, 0x2f800000, v112
	v_floor_f32_e32 v113, v113
	v_fmac_f32_e32 v112, 0xcf800000, v113
	v_cvt_u32_f32_e32 v112, v112
	v_cvt_u32_f32_e32 v113, v113
	v_lshl_add_u64 v[116:117], v[146:147], 3, s[0:1]
	global_atomic_add_x2 v[116:117], v[112:113], off

.LBB0_1169:
	s_or_b64 exec, exec, s[4:5]
	v_readlane_b32 s6, v237, 26
	v_readlane_b32 s7, v237, 27
	v_mov_b32_e32 v9, v236
	s_waitcnt lgkmcnt(0)
	v_cndmask_b32_e64 v0, 0, 1, s[6:7]
	v_cmp_ne_u32_e64 s[4:5], 1, v0
	s_barrier
	s_nop 0
	v_writelane_b32 v237, s4, 34
	s_andn2_b64 vcc, exec, s[6:7]
	v_readfirstlane_b32 s9, v9
	v_writelane_b32 v237, s5, 35
	s_cbranch_vccnz .LBB0_1187
	v_lshlrev_b32_e32 v0, 4, v9
	v_add_u32_e32 v1, 0x2000, v0
	v_ashrrev_i32_e32 v2, 31, v1
	v_lshrrev_b32_e32 v2, 22, v2
	v_add_u32_e32 v2, v1, v2
	v_ashrrev_i32_e32 v8, 10, v2
	v_mul_i32_i24_e32 v2, 0x400, v8
	v_sub_u32_e32 v1, v1, v2
	v_lshrrev_b32_e32 v2, 4, v1
	v_bitop3_b32 v1, v2, v1, 32 bitop3:0x6c
	v_ashrrev_i32_e32 v2, 31, v1
	v_lshrrev_b32_e32 v2, 26, v2
	v_add_u32_e32 v2, v1, v2
	v_lshlrev_b32_e32 v3, 3, v8
	v_ashrrev_i32_e32 v10, 6, v2
	v_and_b32_e32 v3, -16, v3
	v_add_u32_e32 v3, v10, v3
	v_and_b32_e32 v4, 3, v10
	s_mov_b32 s4, 0xfffe0
	v_lshrrev_b32_e32 v5, 2, v3
	v_lshlrev_b32_e32 v6, 1, v3
	v_and_b32_e32 v2, 0xc0, v2
	v_and_or_b32 v4, v3, s4, v4
	v_and_b32_e32 v5, 4, v5
	v_and_b32_e32 v6, 24, v6
	v_sub_u32_e32 v1, v1, v2
	v_mov_b32_e32 v2, 1
	v_or3_b32 v4, v4, v5, v6
	v_lshlrev_b32_e32 v5, 5, v8
	v_ashrrev_i16_sdwa v1, v2, sext(v1) dst_sel:DWORD dst_unused:UNUSED_PAD src0_sel:DWORD src1_sel:BYTE_0
	v_and_b32_e32 v5, 32, v5
	v_bfe_i32 v11, v1, 0, 16
	v_add_lshl_u32 v1, v5, v11, 1
	v_lshl_add_u32 v128, v4, 12, v1
	v_lshl_add_u32 v130, v3, 12, v1
	v_bfe_i32 v1, v9, 27, 1
	v_lshrrev_b32_e32 v1, 22, v1
	v_add_u32_e32 v1, v0, v1
	v_and_b32_e32 v1, 0xfffffc00, v1
	v_sub_u32_e32 v0, v0, v1
	v_lshrrev_b32_e32 v1, 4, v0
	v_ashrrev_i32_e32 v3, 31, v9
	v_bitop3_b32 v0, v1, v0, 32 bitop3:0x6c
	v_lshrrev_b32_e32 v3, 26, v3
	v_ashrrev_i32_e32 v1, 31, v0
	v_add_u32_e32 v3, v9, v3
	v_lshrrev_b32_e32 v1, 26, v1
	v_ashrrev_i32_e32 v13, 6, v3
	v_add_u32_e32 v1, v0, v1
	v_lshlrev_b32_e32 v3, 3, v13
	s_add_u32 s2, s88, 0x2c00000
	v_ashrrev_i32_e32 v12, 6, v1
	v_and_b32_e32 v3, -16, v3
	s_addc_u32 s6, s89, 0
	v_add_u32_e32 v3, v12, v3
	v_and_b32_e32 v4, 3, v12
	s_ashr_i32 s15, s97, 31
	v_and_or_b32 v4, v3, s4, v4
	s_lshr_b32 s4, s15, 29
	s_add_i32 s4, s97, s4
	s_ashr_i32 s10, s9, 6
	s_ashr_i32 s5, s4, 3
	s_and_b32 s4, s4, -8
	s_ashr_i32 s12, s9, 8
	s_lshl_b32 s7, s10, 10
	s_sub_i32 s4, s97, s4
	s_cmp_lt_i32 s4, 0
	s_movk_i32 s17, 0xb1
	s_cselect_b32 s8, s17, 0xb0
	s_mul_i32 s4, s4, s8
	s_add_i32 s4, s4, s5
	s_mul_hi_i32 s5, s4, 0x2e8ba2e9
	s_lshr_b32 s8, s5, 31
	s_ashr_i32 s5, s5, 6
	s_add_i32 s5, s5, s8
	s_lshl_b32 s11, s5, 3
	s_mulk_i32 s5, 0x160
	s_sub_i32 s4, s4, s5
	s_sext_i32_i16 s5, s4
	s_bfe_u32 s5, s5, 0x3001c
	s_add_i32 s5, s4, s5
	s_sext_i32_i16 s8, s5
	s_and_b32 s5, s5, 0xfff8
	s_sub_i32 s4, s4, s5
	s_sext_i32_i16 s4, s4
	v_lshrrev_b32_e32 v5, 2, v3
	v_lshlrev_b32_e32 v6, 1, v3
	v_and_b32_e32 v1, 0xc0, v1
	s_lshr_b32 s8, s8, 3
	s_add_i32 s28, s11, s4
	v_and_b32_e32 v5, 4, v5
	v_and_b32_e32 v6, 24, v6
	v_sub_u32_e32 v0, v0, v1
	s_ashr_i32 s29, s28, 31
	s_bfe_i64 s[18:19], s[8:9], 0x100000
	v_or3_b32 v4, v4, v5, v6
	v_lshlrev_b32_e32 v5, 5, v13
	v_ashrrev_i16_sdwa v0, v2, sext(v0) dst_sel:DWORD dst_unused:UNUSED_PAD src0_sel:DWORD src1_sel:BYTE_0
	s_lshl_b64 s[4:5], s[28:29], 20
	s_lshl_b64 s[18:19], s[18:19], 20
	v_and_b32_e32 v5, 32, v5
	v_bfe_i32 v14, v0, 0, 16
	s_add_u32 s30, s2, s18
	v_add_lshl_u32 v0, v5, v14, 1
	s_addc_u32 s31, s6, s19
	s_add_i32 s19, s7, 0
	v_lshl_add_u32 v132, v4, 12, v0
	s_add_i32 m0, s19, 0x10000
	v_lshl_add_u32 v134, v3, 12, v0
	global_load_lds_dwordx4 v132, s[30:31]
	s_add_i32 m0, s19, 0x12000
	s_add_u32 s20, s30, 0x80000
	global_load_lds_dwordx4 v128, s[30:31]
	s_addc_u32 s21, s31, 0
	s_add_i32 m0, s19, 0x14000
	v_mov_b32_e32 v133, 0
	global_load_lds_dwordx4 v132, s[20:21]
	s_add_i32 m0, s19, 0x16000
	s_add_u32 s34, s60, s4
	s_addc_u32 s35, s61, s5
	s_add_i32 s36, s19, 0x2000
	global_load_lds_dwordx4 v128, s[20:21]
	s_mov_b32 m0, s19
	s_add_u32 s4, s34, 0x80000
	global_load_lds_dwordx4 v134, s[34:35]
	s_mov_b32 m0, s36
	s_addc_u32 s5, s35, 0
	s_add_i32 s37, s19, 0x4000
	global_load_lds_dwordx4 v130, s[34:35]
	s_mov_b32 m0, s37
	s_add_i32 s38, s19, 0x6000
	global_load_lds_dwordx4 v134, s[4:5]
	s_mov_b32 m0, s38
	v_mov_b32_e32 v129, v133
	global_load_lds_dwordx4 v130, s[4:5]
	v_mov_b32_e32 v135, v133
	v_mov_b32_e32 v131, v133
	s_cmp_eq_u32 s12, 1
	s_mov_b32 s39, 0
	v_lshl_add_u64 v[6:7], s[30:31], 0, v[132:133]
	v_lshl_add_u64 v[4:5], s[30:31], 0, v[128:129]
	v_lshl_add_u64 v[0:1], s[34:35], 0, v[134:135]
	s_cselect_b64 s[4:5], -1, 0
	s_cmp_lg_u32 s12, 1
	v_lshl_add_u64 v[2:3], s[34:35], 0, v[130:131]
	s_cbranch_scc1 .LBB0_1172
	s_setprio 1
	s_barrier

.LBB0_1183:
	s_setprio 0
	v_mov_b64_e32 v[158:159], s[18:19]
	v_pk_fma_f32 v[164:165], v[148:149], s[16:17], v[158:159] op_sel_hi:[1,0,0]
	v_lshl_or_b32 v156, s46, 7, v162
	v_mul_f32_e32 v153, 0x4b800000, v165
	v_cmp_gt_f32_e32 vcc, s45, v165
	v_ashrrev_i32_e32 v157, 31, v156
	v_mov_b64_e32 v[154:155], s[64:65]
	v_cndmask_b32_e32 v153, v165, v153, vcc
	v_rsq_f32_e32 v153, v153
	v_mad_i64_i32 v[166:167], s[28:29], v152, s44, v[154:155]
	v_lshlrev_b64 v[156:157], 1, v[156:157]
	v_mul_f32_e32 v165, 0x45800000, v153
	v_cndmask_b32_e32 v168, v153, v165, vcc
	v_pk_mul_f32 v[124:125], v[168:169], v[124:125] op_sel_hi:[0,1]
	v_mul_f32_e32 v153, 0xbfb8aa3b, v124
	v_exp_f32_e32 v153, v153
	v_mul_f32_e32 v165, 0xbfb8aa3b, v125
	v_exp_f32_e32 v165, v165
	v_pk_mul_f32 v[126:127], v[168:169], v[126:127] op_sel_hi:[0,1]
	v_add_f32_e32 v153, 1.0, v153
	v_rcp_f32_e32 v170, v153
	v_add_f32_e32 v153, 1.0, v165
	v_mul_f32_e32 v165, 0xbfb8aa3b, v126
	v_pk_mul_f32 v[116:117], v[168:169], v[116:117] op_sel_hi:[0,1]
	v_exp_f32_e32 v165, v165
	v_mul_f32_e32 v169, 0xbfb8aa3b, v127
	v_exp_f32_e32 v169, v169
	v_rcp_f32_e32 v171, v153
	v_add_f32_e32 v153, 1.0, v165
	v_rcp_f32_e32 v172, v153
	v_add_f32_e32 v153, 1.0, v169
	v_rcp_f32_e32 v173, v153
	v_pk_mul_f32 v[124:125], v[124:125], v[170:171]
	v_pk_mul_f32 v[120:121], v[168:169], v[120:121] op_sel_hi:[0,1]
	v_pk_mul_f32 v[116:117], v[124:125], v[116:117]
	v_pk_mul_f32 v[124:125], v[126:127], v[172:173]
	v_mul_f32_e32 v126, 0xbfb8aa3b, v120
	v_exp_f32_e32 v126, v126
	v_pk_mul_f32 v[118:119], v[168:169], v[118:119] op_sel_hi:[0,1]
	v_pk_mul_f32 v[118:119], v[124:125], v[118:119]
	v_mul_f32_e32 v124, 0xbfb8aa3b, v121
	v_pk_mul_f32 v[122:123], v[168:169], v[122:123] op_sel_hi:[0,1]
	v_exp_f32_e32 v125, v124
	v_add_f32_e32 v124, 1.0, v126
	v_mul_f32_e32 v126, 0xbfb8aa3b, v122
	v_mul_f32_e32 v127, 0xbfb8aa3b, v123
	v_exp_f32_e32 v126, v126
	v_exp_f32_e32 v127, v127
	v_add_f32_e32 v125, 1.0, v125
	v_rcp_f32_e32 v124, v124
	v_rcp_f32_e32 v125, v125
	v_add_f32_e32 v126, 1.0, v126
	v_add_f32_e32 v127, 1.0, v127
	v_rcp_f32_e32 v126, v126
	v_rcp_f32_e32 v127, v127
	v_pk_mul_f32 v[112:113], v[168:169], v[112:113] op_sel_hi:[0,1]
	v_pk_mul_f32 v[120:121], v[120:121], v[124:125]
	v_cmp_gt_f32_e32 vcc, s45, v164
	v_pk_mul_f32 v[120:121], v[120:121], v[112:113]
	v_pk_mul_f32 v[112:113], v[168:169], v[114:115] op_sel_hi:[0,1]
	v_pk_mul_f32 v[114:115], v[122:123], v[126:127]
	v_lshl_add_u64 v[166:167], v[166:167], 0, v[156:157]
	v_pk_mul_f32 v[122:123], v[114:115], v[112:113]
	v_mul_f32_e32 v113, 0x4b800000, v164
	v_cndmask_b32_e32 v113, v164, v113, vcc
	v_cvt_pk_bf16_f32 v112, v116, v117
	v_rsq_f32_e32 v116, v113
	v_cvt_pk_bf16_f32 v113, v118, v119
	v_cvt_pk_bf16_f32 v114, v120, v121
	v_cvt_pk_bf16_f32 v115, v122, v123
	v_mul_f32_e32 v117, 0x45800000, v116
	v_cndmask_b32_e32 v116, v116, v117, vcc
	v_pk_mul_f32 v[108:109], v[116:117], v[108:109] op_sel_hi:[0,1]
	v_mul_f32_e32 v117, 0xbfb8aa3b, v108
	v_exp_f32_e32 v117, v117
	global_store_dwordx4 v[166:167], v[112:115], off
	v_pk_mul_f32 v[110:111], v[116:117], v[110:111] op_sel_hi:[0,1]
	s_nop 0
	v_mul_f32_e32 v112, 0xbfb8aa3b, v109
	v_exp_f32_e32 v113, v112
	v_mul_f32_e32 v114, 0xbfb8aa3b, v110
	v_mul_f32_e32 v115, 0xbfb8aa3b, v111
	v_exp_f32_e32 v114, v114
	v_exp_f32_e32 v115, v115
	v_add_f32_e32 v112, 1.0, v117
	v_add_f32_e32 v113, 1.0, v113
	v_rcp_f32_e32 v112, v112
	v_rcp_f32_e32 v113, v113
	v_add_f32_e32 v114, 1.0, v114
	v_add_f32_e32 v115, 1.0, v115
	v_rcp_f32_e32 v114, v114
	v_rcp_f32_e32 v115, v115
	v_pk_mul_f32 v[100:101], v[116:117], v[100:101] op_sel_hi:[0,1]
	v_pk_mul_f32 v[108:109], v[108:109], v[112:113]
	v_pk_mul_f32 v[104:105], v[116:117], v[104:105] op_sel_hi:[0,1]
	v_pk_mul_f32 v[100:101], v[108:109], v[100:101]
	v_pk_mul_f32 v[108:109], v[110:111], v[114:115]
	v_mul_f32_e32 v110, 0xbfb8aa3b, v104
	v_exp_f32_e32 v110, v110
	v_pk_mul_f32 v[102:103], v[116:117], v[102:103] op_sel_hi:[0,1]
	v_pk_mul_f32 v[102:103], v[108:109], v[102:103]
	v_mul_f32_e32 v108, 0xbfb8aa3b, v105
	v_pk_mul_f32 v[106:107], v[116:117], v[106:107] op_sel_hi:[0,1]
	v_exp_f32_e32 v109, v108
	v_add_f32_e32 v108, 1.0, v110
	v_mul_f32_e32 v110, 0xbfb8aa3b, v106
	v_mul_f32_e32 v111, 0xbfb8aa3b, v107
	v_exp_f32_e32 v110, v110
	v_exp_f32_e32 v111, v111
	v_add_f32_e32 v109, 1.0, v109
	v_rcp_f32_e32 v108, v108
	v_rcp_f32_e32 v109, v109
	v_add_f32_e32 v110, 1.0, v110
	v_add_f32_e32 v111, 1.0, v111
	v_rcp_f32_e32 v110, v110
	v_rcp_f32_e32 v111, v111
	v_pk_mul_f32 v[96:97], v[116:117], v[96:97] op_sel_hi:[0,1]
	v_pk_mul_f32 v[104:105], v[104:105], v[108:109]
	s_nop 0
	v_pk_mul_f32 v[104:105], v[104:105], v[96:97]
	v_pk_mul_f32 v[96:97], v[116:117], v[98:99] op_sel_hi:[0,1]
	v_pk_mul_f32 v[98:99], v[106:107], v[110:111]
	s_nop 0
	v_pk_mul_f32 v[106:107], v[98:99], v[96:97]
	v_cvt_pk_bf16_f32 v96, v100, v101
	v_or_b32_e32 v100, 16, v152
	v_mad_i64_i32 v[100:101], s[28:29], v100, s44, v[154:155]
	v_cvt_pk_bf16_f32 v97, v102, v103
	v_cvt_pk_bf16_f32 v98, v104, v105
	v_cvt_pk_bf16_f32 v99, v106, v107
	v_lshl_add_u64 v[100:101], v[100:101], 0, v[156:157]
	global_store_dwordx4 v[100:101], v[96:99], off
	s_nop 1
	v_pk_fma_f32 v[96:97], v[146:147], s[16:17], v[158:159] op_sel_hi:[1,0,0]
	s_nop 0
	v_mul_f32_e32 v98, 0x4b800000, v97
	v_cmp_gt_f32_e32 vcc, s45, v97
	s_nop 1
	v_cndmask_b32_e32 v97, v97, v98, vcc
	v_rsq_f32_e32 v97, v97
	v_or_b32_e32 v98, 32, v152
	v_mad_i64_i32 v[98:99], s[28:29], v98, s44, v[154:155]
	v_mul_f32_e32 v100, 0x45800000, v97
	v_cndmask_b32_e32 v100, v97, v100, vcc
	v_pk_mul_f32 v[92:93], v[100:101], v[92:93] op_sel_hi:[0,1]
	v_mul_f32_e32 v97, 0xbfb8aa3b, v92
	v_mul_f32_e32 v101, 0xbfb8aa3b, v93
	v_exp_f32_e32 v97, v97
	v_exp_f32_e32 v101, v101
	v_cmp_gt_f32_e32 vcc, s45, v96
	v_lshl_add_u64 v[98:99], v[98:99], 0, v[156:157]
	v_add_f32_e32 v97, 1.0, v97
	v_pk_mul_f32 v[94:95], v[100:101], v[94:95] op_sel_hi:[0,1]
	v_rcp_f32_e32 v102, v97
	v_pk_mul_f32 v[84:85], v[100:101], v[84:85] op_sel_hi:[0,1]
	v_add_f32_e32 v97, 1.0, v101
	v_mul_f32_e32 v101, 0xbfb8aa3b, v94
	v_exp_f32_e32 v101, v101
	v_mul_f32_e32 v103, 0xbfb8aa3b, v95
	v_exp_f32_e32 v105, v103
	v_rcp_f32_e32 v103, v97
	v_add_f32_e32 v97, 1.0, v101
	v_rcp_f32_e32 v104, v97
	v_add_f32_e32 v97, 1.0, v105
	v_rcp_f32_e32 v105, v97
	v_pk_mul_f32 v[92:93], v[92:93], v[102:103]
	v_pk_mul_f32 v[88:89], v[100:101], v[88:89] op_sel_hi:[0,1]
	v_pk_mul_f32 v[84:85], v[92:93], v[84:85]
	v_pk_mul_f32 v[92:93], v[94:95], v[104:105]
	v_mul_f32_e32 v94, 0xbfb8aa3b, v88
	v_exp_f32_e32 v94, v94
	v_pk_mul_f32 v[86:87], v[100:101], v[86:87] op_sel_hi:[0,1]
	v_pk_mul_f32 v[86:87], v[92:93], v[86:87]
	v_mul_f32_e32 v92, 0xbfb8aa3b, v89
	v_pk_mul_f32 v[90:91], v[100:101], v[90:91] op_sel_hi:[0,1]
	v_exp_f32_e32 v93, v92
	v_add_f32_e32 v92, 1.0, v94
	v_mul_f32_e32 v94, 0xbfb8aa3b, v90
	v_mul_f32_e32 v95, 0xbfb8aa3b, v91
	v_exp_f32_e32 v94, v94
	v_exp_f32_e32 v95, v95
	v_add_f32_e32 v93, 1.0, v93
	v_rcp_f32_e32 v92, v92
	v_rcp_f32_e32 v93, v93
	v_add_f32_e32 v94, 1.0, v94
	v_add_f32_e32 v95, 1.0, v95
	v_rcp_f32_e32 v94, v94
	v_rcp_f32_e32 v95, v95
	v_pk_mul_f32 v[80:81], v[100:101], v[80:81] op_sel_hi:[0,1]
	v_pk_mul_f32 v[88:89], v[88:89], v[92:93]
	s_nop 0
	v_pk_mul_f32 v[88:89], v[88:89], v[80:81]
	v_pk_mul_f32 v[80:81], v[100:101], v[82:83] op_sel_hi:[0,1]
	v_pk_mul_f32 v[82:83], v[90:91], v[94:95]
	s_nop 0
	v_pk_mul_f32 v[90:91], v[82:83], v[80:81]
	v_mul_f32_e32 v81, 0x4b800000, v96
	v_cndmask_b32_e32 v81, v96, v81, vcc
	v_cvt_pk_bf16_f32 v80, v84, v85
	v_rsq_f32_e32 v84, v81
	v_cvt_pk_bf16_f32 v81, v86, v87
	v_cvt_pk_bf16_f32 v82, v88, v89
	v_cvt_pk_bf16_f32 v83, v90, v91
	v_mul_f32_e32 v85, 0x45800000, v84
	v_cndmask_b32_e32 v84, v84, v85, vcc
	v_pk_mul_f32 v[76:77], v[84:85], v[76:77] op_sel_hi:[0,1]
	v_mul_f32_e32 v85, 0xbfb8aa3b, v76
	v_exp_f32_e32 v85, v85
	global_store_dwordx4 v[98:99], v[80:83], off
	v_pk_mul_f32 v[78:79], v[84:85], v[78:79] op_sel_hi:[0,1]
	s_nop 0
	v_mul_f32_e32 v80, 0xbfb8aa3b, v77
	v_exp_f32_e32 v81, v80
	v_mul_f32_e32 v82, 0xbfb8aa3b, v78
	v_mul_f32_e32 v83, 0xbfb8aa3b, v79
	v_exp_f32_e32 v82, v82
	v_exp_f32_e32 v83, v83
	v_add_f32_e32 v80, 1.0, v85
	v_add_f32_e32 v81, 1.0, v81
	v_rcp_f32_e32 v80, v80
	v_rcp_f32_e32 v81, v81
	v_add_f32_e32 v82, 1.0, v82
	v_add_f32_e32 v83, 1.0, v83
	v_rcp_f32_e32 v82, v82
	v_rcp_f32_e32 v83, v83
	v_pk_mul_f32 v[68:69], v[84:85], v[68:69] op_sel_hi:[0,1]
	v_pk_mul_f32 v[76:77], v[76:77], v[80:81]
	v_pk_mul_f32 v[72:73], v[84:85], v[72:73] op_sel_hi:[0,1]
	v_pk_mul_f32 v[68:69], v[76:77], v[68:69]
	v_pk_mul_f32 v[76:77], v[78:79], v[82:83]
	v_mul_f32_e32 v78, 0xbfb8aa3b, v72
	v_exp_f32_e32 v78, v78
	v_pk_mul_f32 v[70:71], v[84:85], v[70:71] op_sel_hi:[0,1]
	v_pk_mul_f32 v[70:71], v[76:77], v[70:71]
	v_mul_f32_e32 v76, 0xbfb8aa3b, v73
	v_pk_mul_f32 v[74:75], v[84:85], v[74:75] op_sel_hi:[0,1]
	v_exp_f32_e32 v77, v76
	v_add_f32_e32 v76, 1.0, v78
	v_mul_f32_e32 v78, 0xbfb8aa3b, v74
	v_mul_f32_e32 v79, 0xbfb8aa3b, v75
	v_exp_f32_e32 v78, v78
	v_exp_f32_e32 v79, v79
	v_add_f32_e32 v77, 1.0, v77
	v_rcp_f32_e32 v76, v76
	v_rcp_f32_e32 v77, v77
	v_add_f32_e32 v78, 1.0, v78
	v_add_f32_e32 v79, 1.0, v79
	v_rcp_f32_e32 v78, v78
	v_rcp_f32_e32 v79, v79
	v_pk_mul_f32 v[64:65], v[84:85], v[64:65] op_sel_hi:[0,1]
	v_pk_mul_f32 v[72:73], v[72:73], v[76:77]
	s_nop 0
	v_pk_mul_f32 v[72:73], v[72:73], v[64:65]
	v_pk_mul_f32 v[64:65], v[84:85], v[66:67] op_sel_hi:[0,1]
	v_pk_mul_f32 v[66:67], v[74:75], v[78:79]
	s_nop 0
	v_pk_mul_f32 v[74:75], v[66:67], v[64:65]
	v_cvt_pk_bf16_f32 v64, v68, v69
	v_or_b32_e32 v68, 48, v152
	v_mad_i64_i32 v[68:69], s[28:29], v68, s44, v[154:155]
	v_cvt_pk_bf16_f32 v65, v70, v71
	v_cvt_pk_bf16_f32 v66, v72, v73
	v_cvt_pk_bf16_f32 v67, v74, v75
	v_lshl_add_u64 v[68:69], v[68:69], 0, v[156:157]
	global_store_dwordx4 v[68:69], v[64:67], off
	s_nop 1
	v_pk_fma_f32 v[64:65], v[144:145], s[16:17], v[158:159] op_sel_hi:[1,0,0]
	s_nop 0
	v_mul_f32_e32 v66, 0x4b800000, v65
	v_cmp_gt_f32_e32 vcc, s45, v65
	s_nop 1
	v_cndmask_b32_e32 v65, v65, v66, vcc
	v_rsq_f32_e32 v65, v65
	v_add_u32_e32 v66, 0x80, v152
	v_mad_i64_i32 v[66:67], s[28:29], v66, s44, v[154:155]
	v_mul_f32_e32 v68, 0x45800000, v65
	v_cndmask_b32_e32 v68, v65, v68, vcc
	v_pk_mul_f32 v[60:61], v[68:69], v[60:61] op_sel_hi:[0,1]
	v_mul_f32_e32 v65, 0xbfb8aa3b, v60
	v_mul_f32_e32 v69, 0xbfb8aa3b, v61
	v_exp_f32_e32 v65, v65
	v_exp_f32_e32 v69, v69
	v_cmp_gt_f32_e32 vcc, s45, v64
	v_lshl_add_u64 v[66:67], v[66:67], 0, v[156:157]
	v_add_f32_e32 v65, 1.0, v65
	v_pk_mul_f32 v[62:63], v[68:69], v[62:63] op_sel_hi:[0,1]
	v_rcp_f32_e32 v70, v65
	v_pk_mul_f32 v[52:53], v[68:69], v[52:53] op_sel_hi:[0,1]
	v_add_f32_e32 v65, 1.0, v69
	v_mul_f32_e32 v69, 0xbfb8aa3b, v62
	v_exp_f32_e32 v69, v69
	v_mul_f32_e32 v71, 0xbfb8aa3b, v63
	v_exp_f32_e32 v73, v71
	v_rcp_f32_e32 v71, v65
	v_add_f32_e32 v65, 1.0, v69
	v_rcp_f32_e32 v72, v65
	v_add_f32_e32 v65, 1.0, v73
	v_rcp_f32_e32 v73, v65
	v_pk_mul_f32 v[60:61], v[60:61], v[70:71]
	v_pk_mul_f32 v[56:57], v[68:69], v[56:57] op_sel_hi:[0,1]
	v_pk_mul_f32 v[52:53], v[60:61], v[52:53]
	v_pk_mul_f32 v[60:61], v[62:63], v[72:73]
	v_mul_f32_e32 v62, 0xbfb8aa3b, v56
	v_exp_f32_e32 v62, v62
	v_pk_mul_f32 v[54:55], v[68:69], v[54:55] op_sel_hi:[0,1]
	v_pk_mul_f32 v[54:55], v[60:61], v[54:55]
	v_mul_f32_e32 v60, 0xbfb8aa3b, v57
	v_pk_mul_f32 v[58:59], v[68:69], v[58:59] op_sel_hi:[0,1]
	v_exp_f32_e32 v61, v60
	v_add_f32_e32 v60, 1.0, v62
	v_mul_f32_e32 v62, 0xbfb8aa3b, v58
	v_mul_f32_e32 v63, 0xbfb8aa3b, v59
	v_exp_f32_e32 v62, v62
	v_exp_f32_e32 v63, v63
	v_add_f32_e32 v61, 1.0, v61
	v_rcp_f32_e32 v60, v60
	v_rcp_f32_e32 v61, v61
	v_add_f32_e32 v62, 1.0, v62
	v_add_f32_e32 v63, 1.0, v63
	v_rcp_f32_e32 v62, v62
	v_rcp_f32_e32 v63, v63
	v_pk_mul_f32 v[48:49], v[68:69], v[48:49] op_sel_hi:[0,1]
	v_pk_mul_f32 v[56:57], v[56:57], v[60:61]
	s_nop 0
	v_pk_mul_f32 v[56:57], v[56:57], v[48:49]
	v_pk_mul_f32 v[48:49], v[68:69], v[50:51] op_sel_hi:[0,1]
	v_pk_mul_f32 v[50:51], v[58:59], v[62:63]
	s_nop 0
	v_pk_mul_f32 v[58:59], v[50:51], v[48:49]
	v_mul_f32_e32 v49, 0x4b800000, v64
	v_cndmask_b32_e32 v49, v64, v49, vcc
	v_cvt_pk_bf16_f32 v48, v52, v53
	v_rsq_f32_e32 v52, v49
	v_cvt_pk_bf16_f32 v49, v54, v55
	v_cvt_pk_bf16_f32 v50, v56, v57
	v_cvt_pk_bf16_f32 v51, v58, v59
	v_mul_f32_e32 v53, 0x45800000, v52
	v_cndmask_b32_e32 v52, v52, v53, vcc
	v_pk_mul_f32 v[44:45], v[52:53], v[44:45] op_sel_hi:[0,1]
	v_mul_f32_e32 v53, 0xbfb8aa3b, v44
	v_exp_f32_e32 v53, v53
	global_store_dwordx4 v[66:67], v[48:51], off
	v_pk_mul_f32 v[46:47], v[52:53], v[46:47] op_sel_hi:[0,1]
	s_nop 0
	v_mul_f32_e32 v48, 0xbfb8aa3b, v45
	v_exp_f32_e32 v49, v48
	v_mul_f32_e32 v50, 0xbfb8aa3b, v46
	v_mul_f32_e32 v51, 0xbfb8aa3b, v47
	v_exp_f32_e32 v50, v50
	v_exp_f32_e32 v51, v51
	v_add_f32_e32 v48, 1.0, v53
	v_add_f32_e32 v49, 1.0, v49
	v_rcp_f32_e32 v48, v48
	v_rcp_f32_e32 v49, v49
	v_add_f32_e32 v50, 1.0, v50
	v_add_f32_e32 v51, 1.0, v51
	v_rcp_f32_e32 v50, v50
	v_rcp_f32_e32 v51, v51
	v_pk_mul_f32 v[36:37], v[52:53], v[36:37] op_sel_hi:[0,1]
	v_pk_mul_f32 v[44:45], v[44:45], v[48:49]
	v_pk_mul_f32 v[40:41], v[52:53], v[40:41] op_sel_hi:[0,1]
	v_pk_mul_f32 v[36:37], v[44:45], v[36:37]
	v_pk_mul_f32 v[44:45], v[46:47], v[50:51]
	v_mul_f32_e32 v46, 0xbfb8aa3b, v40
	v_exp_f32_e32 v46, v46
	v_pk_mul_f32 v[38:39], v[52:53], v[38:39] op_sel_hi:[0,1]
	v_pk_mul_f32 v[38:39], v[44:45], v[38:39]
	v_mul_f32_e32 v44, 0xbfb8aa3b, v41
	v_pk_mul_f32 v[42:43], v[52:53], v[42:43] op_sel_hi:[0,1]
	v_exp_f32_e32 v45, v44
	v_add_f32_e32 v44, 1.0, v46
	v_mul_f32_e32 v46, 0xbfb8aa3b, v42
	v_mul_f32_e32 v47, 0xbfb8aa3b, v43
	v_exp_f32_e32 v46, v46
	v_exp_f32_e32 v47, v47
	v_add_f32_e32 v45, 1.0, v45
	v_rcp_f32_e32 v44, v44
	v_rcp_f32_e32 v45, v45
	v_add_f32_e32 v46, 1.0, v46
	v_add_f32_e32 v47, 1.0, v47
	v_rcp_f32_e32 v46, v46
	v_rcp_f32_e32 v47, v47
	v_pk_mul_f32 v[32:33], v[52:53], v[32:33] op_sel_hi:[0,1]
	v_pk_mul_f32 v[40:41], v[40:41], v[44:45]
	s_nop 0
	v_pk_mul_f32 v[40:41], v[40:41], v[32:33]
	v_pk_mul_f32 v[32:33], v[52:53], v[34:35] op_sel_hi:[0,1]
	v_pk_mul_f32 v[34:35], v[42:43], v[46:47]
	s_nop 0
	v_pk_mul_f32 v[42:43], v[34:35], v[32:33]
	v_cvt_pk_bf16_f32 v32, v36, v37
	v_add_u32_e32 v36, 0x90, v152
	v_mad_i64_i32 v[36:37], s[28:29], v36, s44, v[154:155]
	v_cvt_pk_bf16_f32 v33, v38, v39
	v_cvt_pk_bf16_f32 v34, v40, v41
	v_cvt_pk_bf16_f32 v35, v42, v43
	v_lshl_add_u64 v[36:37], v[36:37], 0, v[156:157]
	global_store_dwordx4 v[36:37], v[32:35], off
	s_nop 1
	v_pk_fma_f32 v[32:33], v[150:151], s[16:17], v[158:159] op_sel_hi:[1,0,0]
	s_nop 0
	v_mul_f32_e32 v34, 0x4b800000, v33
	v_cmp_gt_f32_e32 vcc, s45, v33
	s_nop 1
	v_cndmask_b32_e32 v33, v33, v34, vcc
	v_rsq_f32_e32 v33, v33
	v_add_u32_e32 v34, 0xa0, v152
	v_mad_i64_i32 v[34:35], s[28:29], v34, s44, v[154:155]
	v_mul_f32_e32 v36, 0x45800000, v33
	v_cndmask_b32_e32 v36, v33, v36, vcc
	v_pk_mul_f32 v[28:29], v[36:37], v[28:29] op_sel_hi:[0,1]
	v_mul_f32_e32 v33, 0xbfb8aa3b, v28
	v_mul_f32_e32 v37, 0xbfb8aa3b, v29
	v_exp_f32_e32 v33, v33
	v_exp_f32_e32 v37, v37
	v_cmp_gt_f32_e32 vcc, s45, v32
	v_lshl_add_u64 v[34:35], v[34:35], 0, v[156:157]
	v_add_f32_e32 v33, 1.0, v33
	v_pk_mul_f32 v[30:31], v[36:37], v[30:31] op_sel_hi:[0,1]
	v_rcp_f32_e32 v38, v33
	v_pk_mul_f32 v[20:21], v[36:37], v[20:21] op_sel_hi:[0,1]
	v_add_f32_e32 v33, 1.0, v37
	v_mul_f32_e32 v37, 0xbfb8aa3b, v30
	v_exp_f32_e32 v37, v37
	v_mul_f32_e32 v39, 0xbfb8aa3b, v31
	v_exp_f32_e32 v41, v39
	v_rcp_f32_e32 v39, v33
	v_add_f32_e32 v33, 1.0, v37
	v_rcp_f32_e32 v40, v33
	v_add_f32_e32 v33, 1.0, v41
	v_rcp_f32_e32 v41, v33
	v_pk_mul_f32 v[28:29], v[28:29], v[38:39]
	v_pk_mul_f32 v[24:25], v[36:37], v[24:25] op_sel_hi:[0,1]
	v_pk_mul_f32 v[20:21], v[28:29], v[20:21]
	v_pk_mul_f32 v[28:29], v[30:31], v[40:41]
	v_mul_f32_e32 v30, 0xbfb8aa3b, v24
	v_exp_f32_e32 v30, v30
	v_pk_mul_f32 v[22:23], v[36:37], v[22:23] op_sel_hi:[0,1]
	v_pk_mul_f32 v[22:23], v[28:29], v[22:23]
	v_mul_f32_e32 v28, 0xbfb8aa3b, v25
	v_pk_mul_f32 v[26:27], v[36:37], v[26:27] op_sel_hi:[0,1]
	v_exp_f32_e32 v29, v28
	v_add_f32_e32 v28, 1.0, v30
	v_mul_f32_e32 v30, 0xbfb8aa3b, v26
	v_mul_f32_e32 v31, 0xbfb8aa3b, v27
	v_exp_f32_e32 v30, v30
	v_exp_f32_e32 v31, v31
	v_add_f32_e32 v29, 1.0, v29
	v_rcp_f32_e32 v28, v28
	v_rcp_f32_e32 v29, v29
	v_add_f32_e32 v30, 1.0, v30
	v_add_f32_e32 v31, 1.0, v31
	v_rcp_f32_e32 v30, v30
	v_rcp_f32_e32 v31, v31
	v_pk_mul_f32 v[16:17], v[36:37], v[16:17] op_sel_hi:[0,1]
	v_pk_mul_f32 v[24:25], v[24:25], v[28:29]
	s_nop 0
	v_pk_mul_f32 v[24:25], v[24:25], v[16:17]
	v_pk_mul_f32 v[16:17], v[36:37], v[18:19] op_sel_hi:[0,1]
	v_pk_mul_f32 v[18:19], v[26:27], v[30:31]
	s_nop 0
	v_pk_mul_f32 v[26:27], v[18:19], v[16:17]
	v_mul_f32_e32 v17, 0x4b800000, v32
	v_cndmask_b32_e32 v17, v32, v17, vcc
	v_cvt_pk_bf16_f32 v16, v20, v21
	v_rsq_f32_e32 v20, v17
	v_cvt_pk_bf16_f32 v17, v22, v23
	v_cvt_pk_bf16_f32 v18, v24, v25
	v_cvt_pk_bf16_f32 v19, v26, v27
	v_mul_f32_e32 v21, 0x45800000, v20
	v_cndmask_b32_e32 v20, v20, v21, vcc
	v_pk_mul_f32 v[12:13], v[20:21], v[12:13] op_sel_hi:[0,1]
	v_mul_f32_e32 v21, 0xbfb8aa3b, v12
	v_exp_f32_e32 v21, v21
	global_store_dwordx4 v[34:35], v[16:19], off
	s_andn2_b64 vcc, exec, s[8:9]
	s_mov_b64 s[8:9], -1
	v_mul_f32_e32 v16, 0xbfb8aa3b, v13
	v_pk_mul_f32 v[14:15], v[20:21], v[14:15] op_sel_hi:[0,1]
	v_exp_f32_e32 v17, v16
	v_mul_f32_e32 v18, 0xbfb8aa3b, v14
	v_mul_f32_e32 v19, 0xbfb8aa3b, v15
	v_exp_f32_e32 v18, v18
	v_exp_f32_e32 v19, v19
	v_add_f32_e32 v16, 1.0, v21
	v_add_f32_e32 v17, 1.0, v17
	v_rcp_f32_e32 v16, v16
	v_rcp_f32_e32 v17, v17
	v_add_f32_e32 v18, 1.0, v18
	v_add_f32_e32 v19, 1.0, v19
	v_rcp_f32_e32 v18, v18
	v_rcp_f32_e32 v19, v19
	v_pk_mul_f32 v[4:5], v[20:21], v[4:5] op_sel_hi:[0,1]
	v_pk_mul_f32 v[12:13], v[12:13], v[16:17]
	v_pk_mul_f32 v[8:9], v[20:21], v[8:9] op_sel_hi:[0,1]
	v_pk_mul_f32 v[4:5], v[12:13], v[4:5]
	v_pk_mul_f32 v[12:13], v[14:15], v[18:19]
	v_mul_f32_e32 v14, 0xbfb8aa3b, v8
	v_exp_f32_e32 v14, v14
	v_pk_mul_f32 v[6:7], v[20:21], v[6:7] op_sel_hi:[0,1]
	v_pk_mul_f32 v[6:7], v[12:13], v[6:7]
	v_mul_f32_e32 v12, 0xbfb8aa3b, v9
	v_pk_mul_f32 v[10:11], v[20:21], v[10:11] op_sel_hi:[0,1]
	v_exp_f32_e32 v13, v12
	v_add_f32_e32 v12, 1.0, v14
	v_mul_f32_e32 v14, 0xbfb8aa3b, v10
	v_mul_f32_e32 v15, 0xbfb8aa3b, v11
	v_exp_f32_e32 v14, v14
	v_exp_f32_e32 v15, v15
	v_add_f32_e32 v13, 1.0, v13
	v_rcp_f32_e32 v12, v12
	v_rcp_f32_e32 v13, v13
	v_add_f32_e32 v14, 1.0, v14
	v_add_f32_e32 v15, 1.0, v15
	v_rcp_f32_e32 v14, v14
	v_rcp_f32_e32 v15, v15
	v_pk_mul_f32 v[0:1], v[20:21], v[0:1] op_sel_hi:[0,1]
	v_pk_mul_f32 v[8:9], v[8:9], v[12:13]
	s_nop 0
	v_pk_mul_f32 v[8:9], v[8:9], v[0:1]
	v_pk_mul_f32 v[0:1], v[20:21], v[2:3] op_sel_hi:[0,1]
	v_pk_mul_f32 v[2:3], v[10:11], v[14:15]
	s_nop 0
	v_pk_mul_f32 v[10:11], v[2:3], v[0:1]
	v_cvt_pk_bf16_f32 v0, v4, v5
	v_add_u32_e32 v4, 0xb0, v152
	v_mad_i64_i32 v[4:5], s[28:29], v4, s44, v[154:155]
	v_cvt_pk_bf16_f32 v1, v6, v7
	v_cvt_pk_bf16_f32 v2, v8, v9
	v_cvt_pk_bf16_f32 v3, v10, v11
	v_lshl_add_u64 v[4:5], v[4:5], 0, v[156:157]
	global_store_dwordx4 v[4:5], v[0:3], off
	s_cbranch_vccnz .LBB0_1174
	s_andn2_b64 vcc, exec, s[4:5]
	s_cbranch_vccnz .LBB0_1173
	s_barrier
	s_branch .LBB0_1173

.LBB0_1277:
	s_add_u32 s4, s88, 0x3a130000
	s_addc_u32 s5, s89, 0
	s_and_b64 vcc, exec, s[92:93]
	s_cbranch_vccnz .LBB0_1317
	v_ashrrev_i32_e32 v1, 31, v8
	v_lshrrev_b32_e32 v1, 26, v1
	v_add_u32_e32 v1, v8, v1
	v_ashrrev_i32_e32 v9, 6, v1
	v_bfe_i32 v1, v8, 27, 1
	v_lshlrev_b32_e32 v0, 4, v8
	v_lshrrev_b32_e32 v1, 22, v1
	v_add_u32_e32 v1, v0, v1
	v_and_b32_e32 v1, 0xfffffc00, v1
	v_sub_u32_e32 v1, v0, v1
	v_lshrrev_b32_e32 v2, 4, v1
	v_bitop3_b32 v1, v2, v1, 32 bitop3:0x6c
	v_ashrrev_i32_e32 v3, 31, v1
	v_lshrrev_b32_e32 v3, 26, v3
	v_lshlrev_b32_e32 v2, 3, v9
	v_add_u32_e32 v3, v1, v3
	v_and_b32_e32 v2, -16, v2
	v_ashrrev_i32_e32 v10, 6, v3
	v_and_b32_e32 v3, 0xc0, v3
	v_add_u32_e32 v2, v10, v2
	v_lshlrev_b32_e32 v4, 5, v9
	v_sub_u32_e32 v1, v1, v3
	v_mov_b32_e32 v3, 1
	v_and_b32_e32 v11, 32, v4
	v_ashrrev_i16_sdwa v1, v3, sext(v1) dst_sel:DWORD dst_unused:UNUSED_PAD src0_sel:DWORD src1_sel:BYTE_0
	v_lshlrev_b32_e32 v4, 1, v2
	v_lshrrev_b32_e32 v5, 2, v2
	v_and_b32_e32 v6, 3, v10
	s_mov_b32 s7, 0x7fffe0
	v_bfe_i32 v12, v1, 0, 16
	v_and_b32_e32 v4, 24, v4
	v_and_b32_e32 v5, 4, v5
	v_and_or_b32 v6, v2, s7, v6
	s_movk_i32 s1, 0x1600
	v_add_u32_e32 v1, v11, v12
	v_or3_b32 v4, v6, v5, v4
	v_mul_lo_u32 v2, v2, s1
	v_add_lshl_u32 v128, v1, v2, 1
	v_mul_u32_u24_e32 v2, 0x1600, v4
	v_add_u32_e32 v0, 0x2000, v0
	v_add_lshl_u32 v130, v2, v1, 1
	v_ashrrev_i32_e32 v1, 31, v0
	v_lshrrev_b32_e32 v1, 22, v1
	v_add_u32_e32 v1, v0, v1
	v_ashrrev_i32_e32 v13, 10, v1
	v_mul_i32_i24_e32 v1, 0x400, v13
	v_sub_u32_e32 v0, v0, v1
	v_lshrrev_b32_e32 v1, 4, v0
	v_bitop3_b32 v0, v1, v0, 32 bitop3:0x6c
	v_ashrrev_i32_e32 v2, 31, v0
	v_lshrrev_b32_e32 v2, 26, v2
	v_lshlrev_b32_e32 v1, 3, v13
	v_add_u32_e32 v2, v0, v2
	s_add_u32 s2, s88, 0xc600000
	v_and_b32_e32 v1, -16, v1
	v_ashrrev_i32_e32 v14, 6, v2
	v_lshlrev_b32_e32 v4, 5, v13
	s_addc_u32 s6, s89, 0
	v_add_u32_e32 v1, v14, v1
	v_and_b32_e32 v15, 32, v4
	v_and_b32_e32 v2, 0xc0, v2
	v_and_b32_e32 v4, 3, v14
	s_ashr_i32 s9, s8, 6
	s_ashr_i32 s0, s8, 8
	v_sub_u32_e32 v0, v0, v2
	v_and_or_b32 v4, v1, s7, v4
	s_lshl_b32 s7, s9, 10
	s_mul_i32 s11, s43, 0x2c0000
	v_ashrrev_i16_sdwa v0, v3, sext(v0) dst_sel:DWORD dst_unused:UNUSED_PAD src0_sel:DWORD src1_sel:BYTE_0
	v_lshlrev_b32_e32 v2, 1, v1
	v_lshrrev_b32_e32 v3, 2, v1
	s_mul_hi_i32 s10, s43, 0x2c0000
	s_add_u32 s22, s2, s11
	v_bfe_i32 v16, v0, 0, 16
	v_and_b32_e32 v2, 24, v2
	v_and_b32_e32 v3, 4, v3
	s_addc_u32 s23, s6, s10
	s_add_i32 s28, s7, 0
	v_add_u32_e32 v0, v15, v16
	v_or3_b32 v2, v4, v3, v2
	v_mul_lo_u32 v1, v1, s1
	s_add_i32 m0, s28, 0x10000
	v_add_lshl_u32 v132, v0, v1, 1
	v_mul_u32_u24_e32 v1, 0x1600, v2
	global_load_lds_dwordx4 v130, s[22:23]
	s_add_i32 m0, s28, 0x12000
	v_add_lshl_u32 v134, v1, v0, 1
	s_add_u32 s10, s22, 0x160000
	global_load_lds_dwordx4 v134, s[22:23]
	s_addc_u32 s11, s23, 0
	s_add_i32 m0, s28, 0x14000
	s_mul_i32 s13, s42, 0x2c0000
	global_load_lds_dwordx4 v130, s[10:11]
	s_add_i32 m0, s28, 0x16000
	s_mul_hi_i32 s12, s42, 0x2c0000
	s_add_u32 s20, s64, s13
	s_addc_u32 s21, s65, s12
	s_add_i32 s29, s28, 0x2000
	global_load_lds_dwordx4 v134, s[10:11]
	s_mov_b32 m0, s28
	s_add_u32 s10, s20, 0x160000
	global_load_lds_dwordx4 v128, s[20:21]
	s_mov_b32 m0, s29
	s_addc_u32 s11, s21, 0
	s_add_i32 s30, s28, 0x4000
	global_load_lds_dwordx4 v132, s[20:21]
	s_mov_b32 m0, s30
	s_add_i32 s31, s28, 0x6000
	global_load_lds_dwordx4 v128, s[10:11]
	s_mov_b32 m0, s31
	v_mov_b32_e32 v131, 0
	global_load_lds_dwordx4 v132, s[10:11]
	v_mov_b32_e32 v135, v131
	v_mov_b32_e32 v129, v131
	v_mov_b32_e32 v133, v131
	s_cmp_eq_u32 s0, 1
	s_mov_b32 s34, 0
	v_lshl_add_u64 v[6:7], s[22:23], 0, v[130:131]
	v_lshl_add_u64 v[2:3], s[22:23], 0, v[134:135]
	s_mov_b32 s10, 0x16000
	v_lshl_add_u64 v[0:1], s[20:21], 0, v[128:129]
	s_cselect_b64 s[12:13], -1, 0
	s_cmp_lg_u32 s0, 1
	v_lshl_add_u64 v[4:5], s[20:21], 0, v[132:133]
	s_cbranch_scc1 .LBB0_1280
	s_setprio 1
	s_barrier

.LBB0_1297:
	s_setprio 0
	v_lshl_add_u32 v146, s42, 8, v148
	v_ashrrev_i32_e32 v147, 31, v146
	v_lshl_or_b32 v144, s43, 8, v150
	v_lshlrev_b64 v[156:157], 12, v[146:147]
	v_ashrrev_i32_e32 v145, 31, v144
	v_lshl_add_u64 v[156:157], s[60:61], 0, v[156:157]
	v_lshl_add_u64 v[164:165], v[144:145], 1, v[156:157]
	global_load_dwordx4 v[156:159], v[164:165], off
	global_load_dwordx4 v[160:163], v[164:165], off offset:256
	v_and_b32_e32 v166, 64, v154
	v_xor_b32_e32 v155, 16, v154
	v_add_u32_e32 v166, 64, v166
	v_xor_b32_e32 v167, 32, v154
	v_cmp_lt_i32_e32 vcc, v155, v166
	s_waitcnt vmcnt(0)
	v_lshlrev_b32_e32 v168, 16, v158
	v_cndmask_b32_e32 v155, v154, v155, vcc
	v_cmp_lt_i32_e32 vcc, v167, v166
	v_lshlrev_b32_e32 v166, 16, v156
	v_and_b32_e32 v169, 0xffff0000, v158
	v_cndmask_b32_e32 v174, v154, v167, vcc
	v_and_b32_e32 v167, 0xffff0000, v156
	v_lshlrev_b32_e32 v156, 16, v157
	v_and_b32_e32 v157, 0xffff0000, v157
	v_lshlrev_b32_e32 v158, 16, v159
	v_and_b32_e32 v159, 0xffff0000, v159
	v_lshlrev_b32_e32 v170, 16, v160
	v_and_b32_e32 v171, 0xffff0000, v160
	v_lshlrev_b32_e32 v160, 16, v161
	v_and_b32_e32 v161, 0xffff0000, v161
	v_lshlrev_b32_e32 v172, 16, v162
	v_and_b32_e32 v173, 0xffff0000, v162
	v_lshlrev_b32_e32 v162, 16, v163
	v_and_b32_e32 v163, 0xffff0000, v163
	v_pk_fma_f32 v[126:127], v[126:127], 0.5, v[156:157] op_sel_hi:[1,0,1]
	v_pk_fma_f32 v[124:125], v[124:125], 0.5, v[166:167] op_sel_hi:[1,0,1]
	v_pk_fma_f32 v[122:123], v[122:123], 0.5, v[158:159] op_sel_hi:[1,0,1]
	v_pk_fma_f32 v[120:121], v[120:121], 0.5, v[168:169] op_sel_hi:[1,0,1]
	v_pk_fma_f32 v[118:119], v[118:119], 0.5, v[160:161] op_sel_hi:[1,0,1]
	v_pk_fma_f32 v[116:117], v[116:117], 0.5, v[170:171] op_sel_hi:[1,0,1]
	v_pk_fma_f32 v[156:157], v[114:115], 0.5, v[162:163] op_sel_hi:[1,0,1]
	v_pk_fma_f32 v[158:159], v[112:113], 0.5, v[172:173] op_sel_hi:[1,0,1]
	v_cvt_pk_bf16_f32 v112, v124, v125
	v_cvt_pk_bf16_f32 v113, v126, v127
	v_mul_f32_e32 v114, v125, v125
	v_mul_f32_e32 v115, v127, v127
	v_mul_f32_e32 v125, v121, v121
	v_mul_f32_e32 v127, v123, v123
	v_mul_f32_e32 v160, v117, v117
	v_mul_f32_e32 v161, v119, v119
	v_mul_f32_e32 v162, v159, v159
	v_mul_f32_e32 v163, v157, v157
	v_fmac_f32_e32 v114, v124, v124
	v_fmac_f32_e32 v115, v126, v126
	v_fmac_f32_e32 v125, v120, v120
	v_fmac_f32_e32 v127, v122, v122
	v_fmac_f32_e32 v160, v116, v116
	v_fmac_f32_e32 v161, v118, v118
	v_fmac_f32_e32 v162, v158, v158
	v_fmac_f32_e32 v163, v156, v156
	v_add_f32_e32 v114, v114, v115
	v_add_f32_e32 v115, v125, v127
	v_add_f32_e32 v124, v160, v161
	v_add_f32_e32 v125, v162, v163
	v_add_f32_e32 v114, v114, v115
	v_add_f32_e32 v115, v124, v125
	v_lshlrev_b32_e32 v155, 2, v155
	v_add_f32_e32 v124, v114, v115
	ds_bpermute_b32 v125, v155, v124
	v_cvt_pk_bf16_f32 v114, v120, v121
	v_cvt_pk_bf16_f32 v115, v122, v123
	global_store_dwordx4 v[164:165], v[112:115], off
	v_cvt_pk_bf16_f32 v116, v116, v117
	v_cvt_pk_bf16_f32 v117, v118, v119
	s_waitcnt lgkmcnt(0)
	v_add_f32_e32 v112, v124, v125
	v_lshlrev_b32_e32 v114, 2, v174
	ds_bpermute_b32 v113, v114, v112
	v_cvt_pk_bf16_f32 v118, v158, v159
	v_cvt_pk_bf16_f32 v119, v156, v157
	global_store_dwordx4 v[164:165], v[116:119], off offset:256
	s_and_saveexec_b64 s[20:21], s[8:9]
	s_cbranch_execz .LBB0_1299
	s_waitcnt lgkmcnt(0)
	v_add_f32_e32 v112, v112, v113
	v_mul_f32_e32 v112, 0x4b800000, v112
	v_rndne_f32_e32 v112, v112
	v_mul_f32_e32 v113, 0x2f800000, v112
	v_floor_f32_e32 v113, v113
	v_fmac_f32_e32 v112, 0xcf800000, v113
	v_cvt_u32_f32_e32 v112, v112
	v_cvt_u32_f32_e32 v113, v113
	v_lshl_add_u64 v[116:117], v[146:147], 3, s[4:5]
	global_atomic_add_x2 v[116:117], v[112:113], off

.LBB0_1374:
	v_ashrrev_i32_e32 v1, 31, v8
	v_lshrrev_b32_e32 v1, 26, v1
	v_add_u32_e32 v1, v8, v1
	v_ashrrev_i32_e32 v9, 6, v1
	v_bfe_i32 v1, v8, 27, 1
	v_lshlrev_b32_e32 v0, 4, v8
	v_lshrrev_b32_e32 v1, 22, v1
	v_add_u32_e32 v1, v0, v1
	v_and_b32_e32 v1, 0xfffffc00, v1
	v_sub_u32_e32 v1, v0, v1
	v_lshrrev_b32_e32 v2, 4, v1
	v_bitop3_b32 v1, v2, v1, 32 bitop3:0x6c
	v_ashrrev_i32_e32 v3, 31, v1
	v_lshrrev_b32_e32 v3, 26, v3
	v_add_u32_e32 v3, v1, v3
	v_lshlrev_b32_e32 v2, 3, v9
	v_ashrrev_i32_e32 v10, 6, v3
	v_and_b32_e32 v3, 0xc0, v3
	v_and_b32_e32 v2, -16, v2
	v_sub_u32_e32 v1, v1, v3
	v_mov_b32_e32 v3, 1
	v_add_u32_e32 v2, v10, v2
	v_ashrrev_i16_sdwa v1, v3, sext(v1) dst_sel:DWORD dst_unused:UNUSED_PAD src0_sel:DWORD src1_sel:BYTE_0
	v_lshlrev_b32_e32 v4, 5, v9
	v_bfe_i32 v11, v1, 0, 16
	v_lshlrev_b32_e32 v1, 1, v2
	v_lshrrev_b32_e32 v5, 2, v2
	v_and_b32_e32 v6, 3, v10
	s_mov_b32 s1, 0xfffe0
	v_and_b32_e32 v4, 32, v4
	v_and_b32_e32 v1, 24, v1
	v_and_b32_e32 v5, 4, v5
	v_and_or_b32 v6, v2, s1, v6
	v_or3_b32 v1, v6, v5, v1
	v_add_lshl_u32 v4, v4, v11, 1
	v_add_u32_e32 v0, 0x2000, v0
	v_lshl_add_u32 v130, v1, 12, v4
	v_ashrrev_i32_e32 v1, 31, v0
	v_lshrrev_b32_e32 v1, 22, v1
	v_add_u32_e32 v1, v0, v1
	v_ashrrev_i32_e32 v12, 10, v1
	v_mul_i32_i24_e32 v1, 0x400, v12
	v_sub_u32_e32 v0, v0, v1
	v_lshrrev_b32_e32 v1, 4, v0
	v_bitop3_b32 v0, v1, v0, 32 bitop3:0x6c
	v_lshl_add_u32 v128, v2, 12, v4
	v_ashrrev_i32_e32 v2, 31, v0
	v_lshrrev_b32_e32 v2, 26, v2
	v_add_u32_e32 v2, v0, v2
	v_lshlrev_b32_e32 v1, 3, v12
	v_ashrrev_i32_e32 v13, 6, v2
	v_and_b32_e32 v2, 0xc0, v2
	s_ashr_i32 s0, s6, 3
	v_and_b32_e32 v1, -16, v1
	v_sub_u32_e32 v0, v0, v2
	v_add_u32_e32 v1, v13, v1
	v_ashrrev_i16_sdwa v0, v3, sext(v0) dst_sel:DWORD dst_unused:UNUSED_PAD src0_sel:DWORD src1_sel:BYTE_0
	v_and_b32_e32 v3, 3, v13
	s_add_i32 s0, s7, s0
	v_and_or_b32 v3, v1, s1, v3
	s_ashr_i32 s1, s0, 31
	s_lshr_b32 s1, s1, 25
	s_add_i32 s1, s0, s1
	s_ashr_i32 s7, s1, 7
	s_and_b32 s1, s1, 0xffffff80
	s_sub_i32 s0, s0, s1
	s_bfe_i32 s1, s0, 0x80000
	s_bfe_u32 s1, s1, 0x3000c
	s_add_i32 s1, s0, s1
	s_bfe_i32 s8, s1, 0x80000
	s_and_b32 s1, s1, 0xf8
	s_sub_i32 s0, s0, s1
	s_lshl_b32 s7, s7, 3
	s_sext_i32_i16 s8, s8
	s_sext_i32_i8 s0, s0
	s_lshr_b32 s8, s8, 3
	s_add_i32 s34, s7, s0
	s_ashr_i32 s12, s9, 6
	s_ashr_i32 s35, s34, 31
	s_bfe_i64 s[16:17], s[8:9], 0x100000
	s_ashr_i32 s14, s9, 8
	s_lshl_b32 s6, s12, 10
	s_lshl_b64 s[0:1], s[34:35], 20
	s_lshl_b64 s[16:17], s[16:17], 20
	s_add_u32 s36, s50, s16
	v_lshlrev_b32_e32 v4, 5, v12
	v_bfe_i32 v14, v0, 0, 16
	v_lshlrev_b32_e32 v0, 1, v1
	v_lshrrev_b32_e32 v2, 2, v1
	s_addc_u32 s37, s51, s17
	s_add_i32 s7, s6, 0
	v_and_b32_e32 v4, 32, v4
	v_and_b32_e32 v0, 24, v0
	v_and_b32_e32 v2, 4, v2
	s_add_i32 m0, s7, 0x10000
	v_or3_b32 v0, v3, v2, v0
	v_add_lshl_u32 v2, v4, v14, 1
	global_load_lds_dwordx4 v130, s[36:37]
	s_add_i32 m0, s7, 0x12000
	v_lshl_add_u32 v134, v0, 12, v2
	s_add_u32 s16, s36, 0x80000
	global_load_lds_dwordx4 v134, s[36:37]
	s_addc_u32 s17, s37, 0
	s_add_i32 m0, s7, 0x14000
	v_lshl_add_u32 v132, v1, 12, v2
	global_load_lds_dwordx4 v130, s[16:17]
	s_add_i32 m0, s7, 0x16000
	s_add_u32 s38, s60, s0
	global_load_lds_dwordx4 v134, s[16:17]
	s_addc_u32 s39, s61, s1
	s_add_i32 s17, s7, 0x2000
	s_mov_b32 m0, s7
	s_add_u32 s0, s38, 0x80000
	global_load_lds_dwordx4 v128, s[38:39]
	s_mov_b32 m0, s17
	s_addc_u32 s1, s39, 0
	s_add_i32 s19, s7, 0x4000
	global_load_lds_dwordx4 v132, s[38:39]
	s_mov_b32 m0, s19
	s_add_i32 s40, s7, 0x6000
	global_load_lds_dwordx4 v128, s[0:1]
	s_mov_b32 m0, s40
	v_mov_b32_e32 v131, 0
	global_load_lds_dwordx4 v132, s[0:1]
	v_mov_b32_e32 v135, v131
	v_mov_b32_e32 v129, v131
	v_mov_b32_e32 v133, v131
	s_cmp_eq_u32 s14, 1
	s_mov_b32 s41, 0
	v_lshl_add_u64 v[6:7], s[36:37], 0, v[130:131]
	v_lshl_add_u64 v[4:5], s[36:37], 0, v[134:135]
	v_lshl_add_u64 v[0:1], s[38:39], 0, v[128:129]
	s_cselect_b64 s[0:1], -1, 0
	s_cmp_lg_u32 s14, 1
	v_lshl_add_u64 v[2:3], s[38:39], 0, v[132:133]
	s_cbranch_scc1 .LBB0_1376
	s_setprio 1
	s_barrier

.LBB0_1391:
	s_setprio 0
	s_mov_b32 s34, 0x358637bd
	v_mov_b64_e32 v[156:157], s[34:35]
	v_pk_fma_f32 v[164:165], v[144:145], s[18:19], v[156:157] op_sel_hi:[1,0,0]
	v_lshlrev_b64 v[162:163], 13, v[150:151]
	v_mul_f32_e32 v151, 0x4b800000, v165
	v_cmp_gt_f32_e32 vcc, s46, v165
	v_lshl_or_b32 v154, s49, 8, v160
	v_ashrrev_i32_e32 v155, 31, v154
	v_cndmask_b32_e32 v151, v165, v151, vcc
	v_rsq_f32_e32 v151, v151
	v_lshl_add_u64 v[162:163], s[10:11], 0, v[162:163]
	v_lshlrev_b64 v[166:167], 1, v[154:155]
	v_lshl_add_u64 v[154:155], v[162:163], 0, v[166:167]
	v_mul_f32_e32 v162, 0x45800000, v151
	v_cndmask_b32_e32 v162, v151, v162, vcc
	v_pk_mul_f32 v[124:125], v[162:163], v[124:125] op_sel_hi:[0,1]
	v_pk_mul_f32 v[126:127], v[162:163], v[126:127] op_sel_hi:[0,1]
	v_pk_mul_f32 v[168:169], v[162:163], v[120:121] op_sel_hi:[0,1]
	v_pk_mul_f32 v[170:171], v[162:163], v[122:123] op_sel_hi:[0,1]
	v_cvt_pk_bf16_f32 v120, v124, v125
	v_cvt_pk_bf16_f32 v121, v126, v127
	v_cvt_pk_bf16_f32 v122, v168, v169
	v_cvt_pk_bf16_f32 v123, v170, v171
	global_store_dwordx4 v[154:155], v[120:123], off
	v_cmp_gt_f32_e32 vcc, s46, v164
	v_pk_mul_f32 v[112:113], v[162:163], v[112:113] op_sel_hi:[0,1]
	v_pk_mul_f32 v[122:123], v[162:163], v[110:111] op_sel_hi:[0,1]
	v_mul_f32_e32 v110, 0x4b800000, v164
	v_cndmask_b32_e32 v110, v164, v110, vcc
	v_pk_mul_f32 v[120:121], v[162:163], v[108:109] op_sel_hi:[0,1]
	v_cvt_pk_bf16_f32 v108, v112, v113
	v_rsq_f32_e32 v112, v110
	v_pk_mul_f32 v[114:115], v[162:163], v[114:115] op_sel_hi:[0,1]
	v_cvt_pk_bf16_f32 v109, v114, v115
	v_cvt_pk_bf16_f32 v110, v120, v121
	v_cvt_pk_bf16_f32 v111, v122, v123
	global_store_dwordx4 v[154:155], v[108:111], off offset:256
	s_mov_b32 s25, 0x100000
	s_mov_b64 s[34:35], 0x100000
	v_or_b32_e32 v110, 16, v150
	v_mul_f32_e32 v108, 0x45800000, v112
	v_ashrrev_i32_e32 v111, 31, v110
	v_cndmask_b32_e32 v108, v112, v108, vcc
	v_lshlrev_b64 v[110:111], 13, v[110:111]
	v_pk_mul_f32 v[112:113], v[108:109], v[116:117] op_sel_hi:[0,1]
	v_pk_mul_f32 v[114:115], v[108:109], v[118:119] op_sel_hi:[0,1]
	v_pk_mul_f32 v[116:117], v[108:109], v[104:105] op_sel_hi:[0,1]
	v_pk_mul_f32 v[118:119], v[108:109], v[106:107] op_sel_hi:[0,1]
	v_lshl_add_u64 v[110:111], s[10:11], 0, v[110:111]
	v_cvt_pk_bf16_f32 v104, v112, v113
	v_cvt_pk_bf16_f32 v105, v114, v115
	v_cvt_pk_bf16_f32 v106, v116, v117
	v_cvt_pk_bf16_f32 v107, v118, v119
	v_lshl_add_u64 v[110:111], v[110:111], 0, v[166:167]
	global_store_dwordx4 v[110:111], v[104:107], off
	v_pk_mul_f32 v[100:101], v[108:109], v[100:101] op_sel_hi:[0,1]
	v_pk_mul_f32 v[102:103], v[108:109], v[102:103] op_sel_hi:[0,1]
	v_pk_mul_f32 v[104:105], v[108:109], v[96:97] op_sel_hi:[0,1]
	v_pk_mul_f32 v[106:107], v[108:109], v[98:99] op_sel_hi:[0,1]
	v_cvt_pk_bf16_f32 v96, v100, v101
	v_cvt_pk_bf16_f32 v97, v102, v103
	v_cvt_pk_bf16_f32 v98, v104, v105
	v_cvt_pk_bf16_f32 v99, v106, v107
	global_store_dwordx4 v[110:111], v[96:99], off offset:256
	s_nop 1
	v_pk_fma_f32 v[98:99], v[146:147], s[18:19], v[156:157] op_sel_hi:[1,0,0]
	v_or_b32_e32 v96, 32, v150
	v_mul_f32_e32 v100, 0x4b800000, v99
	v_cmp_gt_f32_e32 vcc, s46, v99
	v_ashrrev_i32_e32 v97, 31, v96
	v_lshlrev_b64 v[96:97], 13, v[96:97]
	v_cndmask_b32_e32 v99, v99, v100, vcc
	v_rsq_f32_e32 v99, v99
	v_lshl_add_u64 v[96:97], s[10:11], 0, v[96:97]
	v_lshl_add_u64 v[96:97], v[96:97], 0, v[166:167]
	v_mul_f32_e32 v100, 0x45800000, v99
	v_cndmask_b32_e32 v100, v99, v100, vcc
	v_pk_mul_f32 v[92:93], v[100:101], v[92:93] op_sel_hi:[0,1]
	v_pk_mul_f32 v[94:95], v[100:101], v[94:95] op_sel_hi:[0,1]
	v_pk_mul_f32 v[102:103], v[100:101], v[88:89] op_sel_hi:[0,1]
	v_pk_mul_f32 v[104:105], v[100:101], v[90:91] op_sel_hi:[0,1]
	v_cvt_pk_bf16_f32 v88, v92, v93
	v_cvt_pk_bf16_f32 v89, v94, v95
	v_cvt_pk_bf16_f32 v90, v102, v103
	v_cvt_pk_bf16_f32 v91, v104, v105
	global_store_dwordx4 v[96:97], v[88:91], off
	v_cmp_gt_f32_e32 vcc, s46, v98
	v_pk_mul_f32 v[80:81], v[100:101], v[80:81] op_sel_hi:[0,1]
	v_pk_mul_f32 v[90:91], v[100:101], v[78:79] op_sel_hi:[0,1]
	v_mul_f32_e32 v78, 0x4b800000, v98
	v_cndmask_b32_e32 v78, v98, v78, vcc
	v_pk_mul_f32 v[88:89], v[100:101], v[76:77] op_sel_hi:[0,1]
	v_cvt_pk_bf16_f32 v76, v80, v81
	v_rsq_f32_e32 v80, v78
	v_pk_mul_f32 v[82:83], v[100:101], v[82:83] op_sel_hi:[0,1]
	v_cvt_pk_bf16_f32 v77, v82, v83
	v_cvt_pk_bf16_f32 v78, v88, v89
	v_cvt_pk_bf16_f32 v79, v90, v91
	global_store_dwordx4 v[96:97], v[76:79], off offset:256
	s_nop 1
	v_or_b32_e32 v78, 48, v150
	v_mul_f32_e32 v76, 0x45800000, v80
	v_ashrrev_i32_e32 v79, 31, v78
	v_cndmask_b32_e32 v76, v80, v76, vcc
	v_lshlrev_b64 v[78:79], 13, v[78:79]
	v_pk_mul_f32 v[80:81], v[76:77], v[84:85] op_sel_hi:[0,1]
	v_pk_mul_f32 v[82:83], v[76:77], v[86:87] op_sel_hi:[0,1]
	v_pk_mul_f32 v[84:85], v[76:77], v[72:73] op_sel_hi:[0,1]
	v_pk_mul_f32 v[86:87], v[76:77], v[74:75] op_sel_hi:[0,1]
	v_lshl_add_u64 v[78:79], s[10:11], 0, v[78:79]
	v_cvt_pk_bf16_f32 v72, v80, v81
	v_cvt_pk_bf16_f32 v73, v82, v83
	v_cvt_pk_bf16_f32 v74, v84, v85
	v_cvt_pk_bf16_f32 v75, v86, v87
	v_lshl_add_u64 v[78:79], v[78:79], 0, v[166:167]
	v_pk_mul_f32 v[68:69], v[76:77], v[68:69] op_sel_hi:[0,1]
	global_store_dwordx4 v[78:79], v[72:75], off
	v_pk_mul_f32 v[70:71], v[76:77], v[70:71] op_sel_hi:[0,1]
	s_nop 0
	v_pk_mul_f32 v[72:73], v[76:77], v[64:65] op_sel_hi:[0,1]
	v_cvt_pk_bf16_f32 v64, v68, v69
	v_pk_fma_f32 v[68:69], v[148:149], s[18:19], v[156:157] op_sel_hi:[1,0,0]
	v_pk_mul_f32 v[74:75], v[76:77], v[66:67] op_sel_hi:[0,1]
	v_mul_f32_e32 v67, 0x4b800000, v69
	v_cmp_gt_f32_e32 vcc, s46, v69
	v_cvt_pk_bf16_f32 v65, v70, v71
	v_cvt_pk_bf16_f32 v66, v72, v73
	v_cndmask_b32_e32 v67, v69, v67, vcc
	v_rsq_f32_e32 v69, v67
	v_cvt_pk_bf16_f32 v67, v74, v75
	global_store_dwordx4 v[78:79], v[64:67], off offset:256
	s_nop 1
	v_mul_f32_e32 v66, 0x45800000, v69
	v_cndmask_b32_e32 v66, v69, v66, vcc
	v_pk_mul_f32 v[60:61], v[66:67], v[60:61] op_sel_hi:[0,1]
	v_pk_mul_f32 v[62:63], v[66:67], v[62:63] op_sel_hi:[0,1]
	v_pk_mul_f32 v[70:71], v[66:67], v[56:57] op_sel_hi:[0,1]
	v_pk_mul_f32 v[72:73], v[66:67], v[58:59] op_sel_hi:[0,1]
	v_cvt_pk_bf16_f32 v56, v60, v61
	v_add_co_u32_e32 v60, vcc, s25, v154
	v_cvt_pk_bf16_f32 v57, v62, v63
	v_cvt_pk_bf16_f32 v58, v70, v71
	v_cvt_pk_bf16_f32 v59, v72, v73
	v_addc_co_u32_e32 v61, vcc, 0, v155, vcc
	global_store_dwordx4 v[60:61], v[56:59], off
	v_cmp_gt_f32_e32 vcc, s46, v68
	v_pk_mul_f32 v[48:49], v[66:67], v[48:49] op_sel_hi:[0,1]
	v_pk_mul_f32 v[58:59], v[66:67], v[42:43] op_sel_hi:[0,1]
	v_mul_f32_e32 v42, 0x4b800000, v68
	v_cndmask_b32_e32 v42, v68, v42, vcc
	v_pk_mul_f32 v[56:57], v[66:67], v[40:41] op_sel_hi:[0,1]
	v_cvt_pk_bf16_f32 v40, v48, v49
	v_rsq_f32_e32 v48, v42
	v_pk_mul_f32 v[50:51], v[66:67], v[50:51] op_sel_hi:[0,1]
	v_lshl_add_u64 v[64:65], v[154:155], 0, s[34:35]
	v_cvt_pk_bf16_f32 v41, v50, v51
	v_cvt_pk_bf16_f32 v42, v56, v57
	v_cvt_pk_bf16_f32 v43, v58, v59
	global_store_dwordx4 v[64:65], v[40:43], off offset:256
	s_mov_b32 s25, 0x120000
	s_mov_b64 s[34:35], 0x120000
	v_mul_f32_e32 v40, 0x45800000, v48
	v_cndmask_b32_e32 v48, v48, v40, vcc
	v_pk_mul_f32 v[40:41], v[48:49], v[52:53] op_sel_hi:[0,1]
	v_pk_mul_f32 v[42:43], v[48:49], v[54:55] op_sel_hi:[0,1]
	v_pk_mul_f32 v[46:47], v[48:49], v[46:47] op_sel_hi:[0,1]
	v_pk_mul_f32 v[44:45], v[48:49], v[44:45] op_sel_hi:[0,1]
	v_cvt_pk_bf16_f32 v40, v40, v41
	v_cvt_pk_bf16_f32 v41, v42, v43
	v_cvt_pk_bf16_f32 v43, v46, v47
	v_add_co_u32_e32 v46, vcc, s25, v154
	v_cvt_pk_bf16_f32 v42, v44, v45
	s_nop 0
	v_addc_co_u32_e32 v47, vcc, 0, v155, vcc
	v_pk_mul_f32 v[36:37], v[48:49], v[36:37] op_sel_hi:[0,1]
	global_store_dwordx4 v[46:47], v[40:43], off
	v_pk_mul_f32 v[38:39], v[48:49], v[38:39] op_sel_hi:[0,1]
	v_lshl_add_u64 v[44:45], v[154:155], 0, s[34:35]
	v_pk_mul_f32 v[40:41], v[48:49], v[28:29] op_sel_hi:[0,1]
	v_cvt_pk_bf16_f32 v28, v36, v37
	v_pk_fma_f32 v[36:37], v[152:153], s[18:19], v[156:157] op_sel_hi:[1,0,0]
	v_pk_mul_f32 v[42:43], v[48:49], v[30:31] op_sel_hi:[0,1]
	v_mul_f32_e32 v31, 0x4b800000, v37
	v_cmp_gt_f32_e32 vcc, s46, v37
	v_cvt_pk_bf16_f32 v29, v38, v39
	v_cvt_pk_bf16_f32 v30, v40, v41
	v_cndmask_b32_e32 v31, v37, v31, vcc
	v_rsq_f32_e32 v37, v31
	v_cvt_pk_bf16_f32 v31, v42, v43
	global_store_dwordx4 v[44:45], v[28:31], off offset:256
	s_nop 1
	v_mul_f32_e32 v30, 0x45800000, v37
	v_cndmask_b32_e32 v30, v37, v30, vcc
	v_pk_mul_f32 v[32:33], v[30:31], v[32:33] op_sel_hi:[0,1]
	v_pk_mul_f32 v[34:35], v[30:31], v[34:35] op_sel_hi:[0,1]
	v_pk_mul_f32 v[38:39], v[30:31], v[24:25] op_sel_hi:[0,1]
	v_pk_mul_f32 v[40:41], v[30:31], v[26:27] op_sel_hi:[0,1]
	v_cvt_pk_bf16_f32 v24, v32, v33
	v_add_co_u32_e32 v32, vcc, s47, v154
	v_cvt_pk_bf16_f32 v25, v34, v35
	v_cvt_pk_bf16_f32 v26, v38, v39
	v_cvt_pk_bf16_f32 v27, v40, v41
	v_addc_co_u32_e32 v33, vcc, 0, v155, vcc
	global_store_dwordx4 v[32:33], v[24:27], off
	v_cmp_gt_f32_e32 vcc, s46, v36
	v_pk_mul_f32 v[16:17], v[30:31], v[16:17] op_sel_hi:[0,1]
	v_pk_mul_f32 v[26:27], v[30:31], v[10:11] op_sel_hi:[0,1]
	v_mul_f32_e32 v10, 0x4b800000, v36
	v_cndmask_b32_e32 v10, v36, v10, vcc
	v_pk_mul_f32 v[24:25], v[30:31], v[8:9] op_sel_hi:[0,1]
	v_cvt_pk_bf16_f32 v8, v16, v17
	v_rsq_f32_e32 v16, v10
	v_pk_mul_f32 v[18:19], v[30:31], v[18:19] op_sel_hi:[0,1]
	v_lshl_add_u64 v[28:29], v[154:155], 0, s[20:21]
	v_cvt_pk_bf16_f32 v9, v18, v19
	v_cvt_pk_bf16_f32 v10, v24, v25
	v_cvt_pk_bf16_f32 v11, v26, v27
	global_store_dwordx4 v[28:29], v[8:11], off offset:256
	s_nop 1
	v_mul_f32_e32 v8, 0x45800000, v16
	v_cndmask_b32_e32 v16, v16, v8, vcc
	v_pk_mul_f32 v[8:9], v[16:17], v[20:21] op_sel_hi:[0,1]
	v_pk_mul_f32 v[10:11], v[16:17], v[22:23] op_sel_hi:[0,1]
	v_pk_mul_f32 v[14:15], v[16:17], v[14:15] op_sel_hi:[0,1]
	v_pk_mul_f32 v[12:13], v[16:17], v[12:13] op_sel_hi:[0,1]
	v_cvt_pk_bf16_f32 v8, v8, v9
	v_cvt_pk_bf16_f32 v9, v10, v11
	v_cvt_pk_bf16_f32 v11, v14, v15
	v_add_co_u32_e32 v14, vcc, s48, v154
	v_cvt_pk_bf16_f32 v10, v12, v13
	s_nop 0
	v_addc_co_u32_e32 v15, vcc, 0, v155, vcc
	global_store_dwordx4 v[14:15], v[8:11], off
	v_pk_mul_f32 v[4:5], v[16:17], v[4:5] op_sel_hi:[0,1]
	v_pk_mul_f32 v[6:7], v[16:17], v[6:7] op_sel_hi:[0,1]
	v_pk_mul_f32 v[8:9], v[16:17], v[0:1] op_sel_hi:[0,1]
	v_pk_mul_f32 v[10:11], v[16:17], v[2:3] op_sel_hi:[0,1]
	v_lshl_add_u64 v[12:13], v[154:155], 0, s[22:23]
	v_cvt_pk_bf16_f32 v0, v4, v5
	v_cvt_pk_bf16_f32 v1, v6, v7
	v_cvt_pk_bf16_f32 v2, v8, v9
	v_cvt_pk_bf16_f32 v3, v10, v11
	s_andn2_b64 vcc, exec, s[8:9]
	s_mov_b64 s[8:9], -1
	global_store_dwordx4 v[12:13], v[0:3], off offset:256
	s_cbranch_vccnz .LBB0_1378
	s_andn2_b64 vcc, exec, s[0:1]
	s_cbranch_vccnz .LBB0_1377
	s_barrier
	s_branch .LBB0_1377

.LBB0_1395:
	v_readlane_b32 s0, v237, 34
	v_mov_b32_e32 v9, v236
	v_readlane_b32 s1, v237, 35
	s_and_b64 vcc, exec, s[0:1]
	v_readfirstlane_b32 s9, v9
	s_cbranch_vccnz .LBB0_1413
	v_lshlrev_b32_e32 v0, 4, v9
	v_add_u32_e32 v1, 0x2000, v0
	v_ashrrev_i32_e32 v2, 31, v1
	v_lshrrev_b32_e32 v2, 22, v2
	v_add_u32_e32 v2, v1, v2
	v_ashrrev_i32_e32 v8, 10, v2
	v_mul_i32_i24_e32 v2, 0x400, v8
	v_sub_u32_e32 v1, v1, v2
	v_lshrrev_b32_e32 v2, 4, v1
	v_bitop3_b32 v1, v2, v1, 32 bitop3:0x6c
	v_ashrrev_i32_e32 v2, 31, v1
	v_lshrrev_b32_e32 v2, 26, v2
	v_add_u32_e32 v2, v1, v2
	v_lshlrev_b32_e32 v3, 3, v8
	v_ashrrev_i32_e32 v10, 6, v2
	v_and_b32_e32 v3, -16, v3
	v_add_u32_e32 v3, v10, v3
	v_and_b32_e32 v4, 3, v10
	s_mov_b32 s0, 0xfffe0
	v_lshrrev_b32_e32 v5, 2, v3
	v_lshlrev_b32_e32 v6, 1, v3
	v_and_b32_e32 v2, 0xc0, v2
	v_and_or_b32 v4, v3, s0, v4
	v_and_b32_e32 v5, 4, v5
	v_and_b32_e32 v6, 24, v6
	v_sub_u32_e32 v1, v1, v2
	v_mov_b32_e32 v2, 1
	v_or3_b32 v4, v4, v5, v6
	v_lshlrev_b32_e32 v5, 5, v8
	v_ashrrev_i16_sdwa v1, v2, sext(v1) dst_sel:DWORD dst_unused:UNUSED_PAD src0_sel:DWORD src1_sel:BYTE_0
	v_and_b32_e32 v5, 32, v5
	v_bfe_i32 v11, v1, 0, 16
	v_add_lshl_u32 v1, v5, v11, 1
	v_lshl_add_u32 v128, v4, 12, v1
	v_lshl_add_u32 v130, v3, 12, v1
	v_bfe_i32 v1, v9, 27, 1
	v_lshrrev_b32_e32 v1, 22, v1
	v_add_u32_e32 v1, v0, v1
	v_and_b32_e32 v1, 0xfffffc00, v1
	v_sub_u32_e32 v0, v0, v1
	v_lshrrev_b32_e32 v1, 4, v0
	v_ashrrev_i32_e32 v3, 31, v9
	v_bitop3_b32 v0, v1, v0, 32 bitop3:0x6c
	v_lshrrev_b32_e32 v3, 26, v3
	v_ashrrev_i32_e32 v1, 31, v0
	v_add_u32_e32 v3, v9, v3
	v_lshrrev_b32_e32 v1, 26, v1
	v_ashrrev_i32_e32 v13, 6, v3
	v_add_u32_e32 v1, v0, v1
	v_lshlrev_b32_e32 v3, 3, v13
	s_add_u32 s2, s88, 0x5800000
	v_ashrrev_i32_e32 v12, 6, v1
	v_and_b32_e32 v3, -16, v3
	s_addc_u32 s6, s89, 0
	v_add_u32_e32 v3, v12, v3
	v_and_b32_e32 v4, 3, v12
	s_ashr_i32 s17, s97, 31
	v_and_or_b32 v4, v3, s0, v4
	s_lshr_b32 s0, s17, 29
	s_add_i32 s0, s97, s0
	s_ashr_i32 s12, s9, 6
	s_ashr_i32 s1, s0, 3
	s_and_b32 s0, s0, -8
	s_ashr_i32 s14, s9, 8
	s_lshl_b32 s7, s12, 10
	s_sub_i32 s0, s97, s0
	s_cmp_lt_i32 s0, 0
	s_movk_i32 s19, 0xb1
	s_cselect_b32 s8, s19, 0xb0
	s_mul_i32 s0, s0, s8
	s_add_i32 s0, s0, s1
	s_mul_hi_i32 s1, s0, 0x2e8ba2e9
	s_lshr_b32 s8, s1, 31
	s_ashr_i32 s1, s1, 6
	s_add_i32 s1, s1, s8
	s_lshl_b32 s13, s1, 3
	s_mulk_i32 s1, 0x160
	s_sub_i32 s0, s0, s1
	s_sext_i32_i16 s1, s0
	s_bfe_u32 s1, s1, 0x3001c
	s_add_i32 s1, s0, s1
	s_sext_i32_i16 s8, s1
	s_and_b32 s1, s1, 0xfff8
	s_sub_i32 s0, s0, s1
	s_sext_i32_i16 s0, s0
	v_lshrrev_b32_e32 v5, 2, v3
	v_lshlrev_b32_e32 v6, 1, v3
	v_and_b32_e32 v1, 0xc0, v1
	s_lshr_b32 s8, s8, 3
	s_add_i32 s30, s13, s0
	v_and_b32_e32 v5, 4, v5
	v_and_b32_e32 v6, 24, v6
	v_sub_u32_e32 v0, v0, v1
	s_ashr_i32 s31, s30, 31
	s_bfe_i64 s[20:21], s[8:9], 0x100000
	v_or3_b32 v4, v4, v5, v6
	v_lshlrev_b32_e32 v5, 5, v13
	v_ashrrev_i16_sdwa v0, v2, sext(v0) dst_sel:DWORD dst_unused:UNUSED_PAD src0_sel:DWORD src1_sel:BYTE_0
	s_lshl_b64 s[0:1], s[30:31], 20
	s_lshl_b64 s[20:21], s[20:21], 20
	v_and_b32_e32 v5, 32, v5
	v_bfe_i32 v14, v0, 0, 16
	s_add_u32 s34, s2, s20
	v_add_lshl_u32 v0, v5, v14, 1
	s_addc_u32 s35, s6, s21
	s_add_i32 s21, s7, 0
	v_lshl_add_u32 v132, v4, 12, v0
	s_add_i32 m0, s21, 0x10000
	v_lshl_add_u32 v134, v3, 12, v0
	global_load_lds_dwordx4 v132, s[34:35]
	s_add_i32 m0, s21, 0x12000
	s_add_u32 s22, s34, 0x80000
	global_load_lds_dwordx4 v128, s[34:35]
	s_addc_u32 s23, s35, 0
	s_add_i32 m0, s21, 0x14000
	v_mov_b32_e32 v133, 0
	global_load_lds_dwordx4 v132, s[22:23]
	s_add_i32 m0, s21, 0x16000
	s_add_u32 s36, s60, s0
	s_addc_u32 s37, s61, s1
	s_add_i32 s38, s21, 0x2000
	global_load_lds_dwordx4 v128, s[22:23]
	s_mov_b32 m0, s21
	s_add_u32 s0, s36, 0x80000
	global_load_lds_dwordx4 v134, s[36:37]
	s_mov_b32 m0, s38
	s_addc_u32 s1, s37, 0
	s_add_i32 s39, s21, 0x4000
	global_load_lds_dwordx4 v130, s[36:37]
	s_mov_b32 m0, s39
	s_add_i32 s40, s21, 0x6000
	global_load_lds_dwordx4 v134, s[0:1]
	s_mov_b32 m0, s40
	v_mov_b32_e32 v129, v133
	global_load_lds_dwordx4 v130, s[0:1]
	v_mov_b32_e32 v135, v133
	v_mov_b32_e32 v131, v133
	s_cmp_eq_u32 s14, 1
	s_mov_b32 s41, 0
	v_lshl_add_u64 v[6:7], s[34:35], 0, v[132:133]
	v_lshl_add_u64 v[4:5], s[34:35], 0, v[128:129]
	v_lshl_add_u64 v[0:1], s[36:37], 0, v[134:135]
	s_cselect_b64 s[0:1], -1, 0
	s_cmp_lg_u32 s14, 1
	v_lshl_add_u64 v[2:3], s[36:37], 0, v[130:131]
	s_cbranch_scc1 .LBB0_1398
	s_setprio 1
	s_barrier

.LBB0_1409:
	s_setprio 0
	v_mov_b64_e32 v[158:159], s[20:21]
	v_pk_fma_f32 v[164:165], v[148:149], s[18:19], v[158:159] op_sel_hi:[1,0,0]
	v_lshl_or_b32 v156, s48, 7, v162
	v_mul_f32_e32 v153, 0x4b800000, v165
	v_cmp_gt_f32_e32 vcc, s47, v165
	v_ashrrev_i32_e32 v157, 31, v156
	v_mov_b64_e32 v[154:155], s[64:65]
	v_cndmask_b32_e32 v153, v165, v153, vcc
	v_rsq_f32_e32 v153, v153
	v_mad_i64_i32 v[166:167], s[30:31], v152, s46, v[154:155]
	v_lshlrev_b64 v[156:157], 1, v[156:157]
	v_mul_f32_e32 v165, 0x45800000, v153
	v_cndmask_b32_e32 v168, v153, v165, vcc
	v_pk_mul_f32 v[124:125], v[168:169], v[124:125] op_sel_hi:[0,1]
	v_mul_f32_e32 v153, 0xbfb8aa3b, v124
	v_exp_f32_e32 v153, v153
	v_mul_f32_e32 v165, 0xbfb8aa3b, v125
	v_exp_f32_e32 v165, v165
	v_pk_mul_f32 v[126:127], v[168:169], v[126:127] op_sel_hi:[0,1]
	v_add_f32_e32 v153, 1.0, v153
	v_rcp_f32_e32 v170, v153
	v_add_f32_e32 v153, 1.0, v165
	v_mul_f32_e32 v165, 0xbfb8aa3b, v126
	v_pk_mul_f32 v[116:117], v[168:169], v[116:117] op_sel_hi:[0,1]
	v_exp_f32_e32 v165, v165
	v_mul_f32_e32 v169, 0xbfb8aa3b, v127
	v_exp_f32_e32 v169, v169
	v_rcp_f32_e32 v171, v153
	v_add_f32_e32 v153, 1.0, v165
	v_rcp_f32_e32 v172, v153
	v_add_f32_e32 v153, 1.0, v169
	v_rcp_f32_e32 v173, v153
	v_pk_mul_f32 v[124:125], v[124:125], v[170:171]
	v_pk_mul_f32 v[120:121], v[168:169], v[120:121] op_sel_hi:[0,1]
	v_pk_mul_f32 v[116:117], v[124:125], v[116:117]
	v_pk_mul_f32 v[124:125], v[126:127], v[172:173]
	v_mul_f32_e32 v126, 0xbfb8aa3b, v120
	v_exp_f32_e32 v126, v126
	v_pk_mul_f32 v[118:119], v[168:169], v[118:119] op_sel_hi:[0,1]
	v_pk_mul_f32 v[118:119], v[124:125], v[118:119]
	v_mul_f32_e32 v124, 0xbfb8aa3b, v121
	v_pk_mul_f32 v[122:123], v[168:169], v[122:123] op_sel_hi:[0,1]
	v_exp_f32_e32 v125, v124
	v_add_f32_e32 v124, 1.0, v126
	v_mul_f32_e32 v126, 0xbfb8aa3b, v122
	v_mul_f32_e32 v127, 0xbfb8aa3b, v123
	v_exp_f32_e32 v126, v126
	v_exp_f32_e32 v127, v127
	v_add_f32_e32 v125, 1.0, v125
	v_rcp_f32_e32 v124, v124
	v_rcp_f32_e32 v125, v125
	v_add_f32_e32 v126, 1.0, v126
	v_add_f32_e32 v127, 1.0, v127
	v_rcp_f32_e32 v126, v126
	v_rcp_f32_e32 v127, v127
	v_pk_mul_f32 v[112:113], v[168:169], v[112:113] op_sel_hi:[0,1]
	v_pk_mul_f32 v[120:121], v[120:121], v[124:125]
	v_cmp_gt_f32_e32 vcc, s47, v164
	v_pk_mul_f32 v[120:121], v[120:121], v[112:113]
	v_pk_mul_f32 v[112:113], v[168:169], v[114:115] op_sel_hi:[0,1]
	v_pk_mul_f32 v[114:115], v[122:123], v[126:127]
	v_lshl_add_u64 v[166:167], v[166:167], 0, v[156:157]
	v_pk_mul_f32 v[122:123], v[114:115], v[112:113]
	v_mul_f32_e32 v113, 0x4b800000, v164
	v_cndmask_b32_e32 v113, v164, v113, vcc
	v_cvt_pk_bf16_f32 v112, v116, v117
	v_rsq_f32_e32 v116, v113
	v_cvt_pk_bf16_f32 v113, v118, v119
	v_cvt_pk_bf16_f32 v114, v120, v121
	v_cvt_pk_bf16_f32 v115, v122, v123
	v_mul_f32_e32 v117, 0x45800000, v116
	v_cndmask_b32_e32 v116, v116, v117, vcc
	v_pk_mul_f32 v[108:109], v[116:117], v[108:109] op_sel_hi:[0,1]
	v_mul_f32_e32 v117, 0xbfb8aa3b, v108
	v_exp_f32_e32 v117, v117
	global_store_dwordx4 v[166:167], v[112:115], off
	v_pk_mul_f32 v[110:111], v[116:117], v[110:111] op_sel_hi:[0,1]
	s_nop 0
	v_mul_f32_e32 v112, 0xbfb8aa3b, v109
	v_exp_f32_e32 v113, v112
	v_mul_f32_e32 v114, 0xbfb8aa3b, v110
	v_mul_f32_e32 v115, 0xbfb8aa3b, v111
	v_exp_f32_e32 v114, v114
	v_exp_f32_e32 v115, v115
	v_add_f32_e32 v112, 1.0, v117
	v_add_f32_e32 v113, 1.0, v113
	v_rcp_f32_e32 v112, v112
	v_rcp_f32_e32 v113, v113
	v_add_f32_e32 v114, 1.0, v114
	v_add_f32_e32 v115, 1.0, v115
	v_rcp_f32_e32 v114, v114
	v_rcp_f32_e32 v115, v115
	v_pk_mul_f32 v[100:101], v[116:117], v[100:101] op_sel_hi:[0,1]
	v_pk_mul_f32 v[108:109], v[108:109], v[112:113]
	v_pk_mul_f32 v[104:105], v[116:117], v[104:105] op_sel_hi:[0,1]
	v_pk_mul_f32 v[100:101], v[108:109], v[100:101]
	v_pk_mul_f32 v[108:109], v[110:111], v[114:115]
	v_mul_f32_e32 v110, 0xbfb8aa3b, v104
	v_exp_f32_e32 v110, v110
	v_pk_mul_f32 v[102:103], v[116:117], v[102:103] op_sel_hi:[0,1]
	v_pk_mul_f32 v[102:103], v[108:109], v[102:103]
	v_mul_f32_e32 v108, 0xbfb8aa3b, v105
	v_pk_mul_f32 v[106:107], v[116:117], v[106:107] op_sel_hi:[0,1]
	v_exp_f32_e32 v109, v108
	v_add_f32_e32 v108, 1.0, v110
	v_mul_f32_e32 v110, 0xbfb8aa3b, v106
	v_mul_f32_e32 v111, 0xbfb8aa3b, v107
	v_exp_f32_e32 v110, v110
	v_exp_f32_e32 v111, v111
	v_add_f32_e32 v109, 1.0, v109
	v_rcp_f32_e32 v108, v108
	v_rcp_f32_e32 v109, v109
	v_add_f32_e32 v110, 1.0, v110
	v_add_f32_e32 v111, 1.0, v111
	v_rcp_f32_e32 v110, v110
	v_rcp_f32_e32 v111, v111
	v_pk_mul_f32 v[96:97], v[116:117], v[96:97] op_sel_hi:[0,1]
	v_pk_mul_f32 v[104:105], v[104:105], v[108:109]
	s_nop 0
	v_pk_mul_f32 v[104:105], v[104:105], v[96:97]
	v_pk_mul_f32 v[96:97], v[116:117], v[98:99] op_sel_hi:[0,1]
	v_pk_mul_f32 v[98:99], v[106:107], v[110:111]
	s_nop 0
	v_pk_mul_f32 v[106:107], v[98:99], v[96:97]
	v_cvt_pk_bf16_f32 v96, v100, v101
	v_or_b32_e32 v100, 16, v152
	v_mad_i64_i32 v[100:101], s[30:31], v100, s46, v[154:155]
	v_cvt_pk_bf16_f32 v97, v102, v103
	v_cvt_pk_bf16_f32 v98, v104, v105
	v_cvt_pk_bf16_f32 v99, v106, v107
	v_lshl_add_u64 v[100:101], v[100:101], 0, v[156:157]
	global_store_dwordx4 v[100:101], v[96:99], off
	s_nop 1
	v_pk_fma_f32 v[96:97], v[146:147], s[18:19], v[158:159] op_sel_hi:[1,0,0]
	s_nop 0
	v_mul_f32_e32 v98, 0x4b800000, v97
	v_cmp_gt_f32_e32 vcc, s47, v97
	s_nop 1
	v_cndmask_b32_e32 v97, v97, v98, vcc
	v_rsq_f32_e32 v97, v97
	v_or_b32_e32 v98, 32, v152
	v_mad_i64_i32 v[98:99], s[30:31], v98, s46, v[154:155]
	v_mul_f32_e32 v100, 0x45800000, v97
	v_cndmask_b32_e32 v100, v97, v100, vcc
	v_pk_mul_f32 v[92:93], v[100:101], v[92:93] op_sel_hi:[0,1]
	v_mul_f32_e32 v97, 0xbfb8aa3b, v92
	v_mul_f32_e32 v101, 0xbfb8aa3b, v93
	v_exp_f32_e32 v97, v97
	v_exp_f32_e32 v101, v101
	v_cmp_gt_f32_e32 vcc, s47, v96
	v_lshl_add_u64 v[98:99], v[98:99], 0, v[156:157]
	v_add_f32_e32 v97, 1.0, v97
	v_pk_mul_f32 v[94:95], v[100:101], v[94:95] op_sel_hi:[0,1]
	v_rcp_f32_e32 v102, v97
	v_pk_mul_f32 v[84:85], v[100:101], v[84:85] op_sel_hi:[0,1]
	v_add_f32_e32 v97, 1.0, v101
	v_mul_f32_e32 v101, 0xbfb8aa3b, v94
	v_exp_f32_e32 v101, v101
	v_mul_f32_e32 v103, 0xbfb8aa3b, v95
	v_exp_f32_e32 v105, v103
	v_rcp_f32_e32 v103, v97
	v_add_f32_e32 v97, 1.0, v101
	v_rcp_f32_e32 v104, v97
	v_add_f32_e32 v97, 1.0, v105
	v_rcp_f32_e32 v105, v97
	v_pk_mul_f32 v[92:93], v[92:93], v[102:103]
	v_pk_mul_f32 v[88:89], v[100:101], v[88:89] op_sel_hi:[0,1]
	v_pk_mul_f32 v[84:85], v[92:93], v[84:85]
	v_pk_mul_f32 v[92:93], v[94:95], v[104:105]
	v_mul_f32_e32 v94, 0xbfb8aa3b, v88
	v_exp_f32_e32 v94, v94
	v_pk_mul_f32 v[86:87], v[100:101], v[86:87] op_sel_hi:[0,1]
	v_pk_mul_f32 v[86:87], v[92:93], v[86:87]
	v_mul_f32_e32 v92, 0xbfb8aa3b, v89
	v_pk_mul_f32 v[90:91], v[100:101], v[90:91] op_sel_hi:[0,1]
	v_exp_f32_e32 v93, v92
	v_add_f32_e32 v92, 1.0, v94
	v_mul_f32_e32 v94, 0xbfb8aa3b, v90
	v_mul_f32_e32 v95, 0xbfb8aa3b, v91
	v_exp_f32_e32 v94, v94
	v_exp_f32_e32 v95, v95
	v_add_f32_e32 v93, 1.0, v93
	v_rcp_f32_e32 v92, v92
	v_rcp_f32_e32 v93, v93
	v_add_f32_e32 v94, 1.0, v94
	v_add_f32_e32 v95, 1.0, v95
	v_rcp_f32_e32 v94, v94
	v_rcp_f32_e32 v95, v95
	v_pk_mul_f32 v[80:81], v[100:101], v[80:81] op_sel_hi:[0,1]
	v_pk_mul_f32 v[88:89], v[88:89], v[92:93]
	s_nop 0
	v_pk_mul_f32 v[88:89], v[88:89], v[80:81]
	v_pk_mul_f32 v[80:81], v[100:101], v[82:83] op_sel_hi:[0,1]
	v_pk_mul_f32 v[82:83], v[90:91], v[94:95]
	s_nop 0
	v_pk_mul_f32 v[90:91], v[82:83], v[80:81]
	v_mul_f32_e32 v81, 0x4b800000, v96
	v_cndmask_b32_e32 v81, v96, v81, vcc
	v_cvt_pk_bf16_f32 v80, v84, v85
	v_rsq_f32_e32 v84, v81
	v_cvt_pk_bf16_f32 v81, v86, v87
	v_cvt_pk_bf16_f32 v82, v88, v89
	v_cvt_pk_bf16_f32 v83, v90, v91
	v_mul_f32_e32 v85, 0x45800000, v84
	v_cndmask_b32_e32 v84, v84, v85, vcc
	v_pk_mul_f32 v[76:77], v[84:85], v[76:77] op_sel_hi:[0,1]
	v_mul_f32_e32 v85, 0xbfb8aa3b, v76
	v_exp_f32_e32 v85, v85
	global_store_dwordx4 v[98:99], v[80:83], off
	v_pk_mul_f32 v[78:79], v[84:85], v[78:79] op_sel_hi:[0,1]
	s_nop 0
	v_mul_f32_e32 v80, 0xbfb8aa3b, v77
	v_exp_f32_e32 v81, v80
	v_mul_f32_e32 v82, 0xbfb8aa3b, v78
	v_mul_f32_e32 v83, 0xbfb8aa3b, v79
	v_exp_f32_e32 v82, v82
	v_exp_f32_e32 v83, v83
	v_add_f32_e32 v80, 1.0, v85
	v_add_f32_e32 v81, 1.0, v81
	v_rcp_f32_e32 v80, v80
	v_rcp_f32_e32 v81, v81
	v_add_f32_e32 v82, 1.0, v82
	v_add_f32_e32 v83, 1.0, v83
	v_rcp_f32_e32 v82, v82
	v_rcp_f32_e32 v83, v83
	v_pk_mul_f32 v[68:69], v[84:85], v[68:69] op_sel_hi:[0,1]
	v_pk_mul_f32 v[76:77], v[76:77], v[80:81]
	v_pk_mul_f32 v[72:73], v[84:85], v[72:73] op_sel_hi:[0,1]
	v_pk_mul_f32 v[68:69], v[76:77], v[68:69]
	v_pk_mul_f32 v[76:77], v[78:79], v[82:83]
	v_mul_f32_e32 v78, 0xbfb8aa3b, v72
	v_exp_f32_e32 v78, v78
	v_pk_mul_f32 v[70:71], v[84:85], v[70:71] op_sel_hi:[0,1]
	v_pk_mul_f32 v[70:71], v[76:77], v[70:71]
	v_mul_f32_e32 v76, 0xbfb8aa3b, v73
	v_pk_mul_f32 v[74:75], v[84:85], v[74:75] op_sel_hi:[0,1]
	v_exp_f32_e32 v77, v76
	v_add_f32_e32 v76, 1.0, v78
	v_mul_f32_e32 v78, 0xbfb8aa3b, v74
	v_mul_f32_e32 v79, 0xbfb8aa3b, v75
	v_exp_f32_e32 v78, v78
	v_exp_f32_e32 v79, v79
	v_add_f32_e32 v77, 1.0, v77
	v_rcp_f32_e32 v76, v76
	v_rcp_f32_e32 v77, v77
	v_add_f32_e32 v78, 1.0, v78
	v_add_f32_e32 v79, 1.0, v79
	v_rcp_f32_e32 v78, v78
	v_rcp_f32_e32 v79, v79
	v_pk_mul_f32 v[64:65], v[84:85], v[64:65] op_sel_hi:[0,1]
	v_pk_mul_f32 v[72:73], v[72:73], v[76:77]
	s_nop 0
	v_pk_mul_f32 v[72:73], v[72:73], v[64:65]
	v_pk_mul_f32 v[64:65], v[84:85], v[66:67] op_sel_hi:[0,1]
	v_pk_mul_f32 v[66:67], v[74:75], v[78:79]
	s_nop 0
	v_pk_mul_f32 v[74:75], v[66:67], v[64:65]
	v_cvt_pk_bf16_f32 v64, v68, v69
	v_or_b32_e32 v68, 48, v152
	v_mad_i64_i32 v[68:69], s[30:31], v68, s46, v[154:155]
	v_cvt_pk_bf16_f32 v65, v70, v71
	v_cvt_pk_bf16_f32 v66, v72, v73
	v_cvt_pk_bf16_f32 v67, v74, v75
	v_lshl_add_u64 v[68:69], v[68:69], 0, v[156:157]
	global_store_dwordx4 v[68:69], v[64:67], off
	s_nop 1
	v_pk_fma_f32 v[64:65], v[144:145], s[18:19], v[158:159] op_sel_hi:[1,0,0]
	s_nop 0
	v_mul_f32_e32 v66, 0x4b800000, v65
	v_cmp_gt_f32_e32 vcc, s47, v65
	s_nop 1
	v_cndmask_b32_e32 v65, v65, v66, vcc
	v_rsq_f32_e32 v65, v65
	v_add_u32_e32 v66, 0x80, v152
	v_mad_i64_i32 v[66:67], s[30:31], v66, s46, v[154:155]
	v_mul_f32_e32 v68, 0x45800000, v65
	v_cndmask_b32_e32 v68, v65, v68, vcc
	v_pk_mul_f32 v[60:61], v[68:69], v[60:61] op_sel_hi:[0,1]
	v_mul_f32_e32 v65, 0xbfb8aa3b, v60
	v_mul_f32_e32 v69, 0xbfb8aa3b, v61
	v_exp_f32_e32 v65, v65
	v_exp_f32_e32 v69, v69
	v_cmp_gt_f32_e32 vcc, s47, v64
	v_lshl_add_u64 v[66:67], v[66:67], 0, v[156:157]
	v_add_f32_e32 v65, 1.0, v65
	v_pk_mul_f32 v[62:63], v[68:69], v[62:63] op_sel_hi:[0,1]
	v_rcp_f32_e32 v70, v65
	v_pk_mul_f32 v[52:53], v[68:69], v[52:53] op_sel_hi:[0,1]
	v_add_f32_e32 v65, 1.0, v69
	v_mul_f32_e32 v69, 0xbfb8aa3b, v62
	v_exp_f32_e32 v69, v69
	v_mul_f32_e32 v71, 0xbfb8aa3b, v63
	v_exp_f32_e32 v73, v71
	v_rcp_f32_e32 v71, v65
	v_add_f32_e32 v65, 1.0, v69
	v_rcp_f32_e32 v72, v65
	v_add_f32_e32 v65, 1.0, v73
	v_rcp_f32_e32 v73, v65
	v_pk_mul_f32 v[60:61], v[60:61], v[70:71]
	v_pk_mul_f32 v[56:57], v[68:69], v[56:57] op_sel_hi:[0,1]
	v_pk_mul_f32 v[52:53], v[60:61], v[52:53]
	v_pk_mul_f32 v[60:61], v[62:63], v[72:73]
	v_mul_f32_e32 v62, 0xbfb8aa3b, v56
	v_exp_f32_e32 v62, v62
	v_pk_mul_f32 v[54:55], v[68:69], v[54:55] op_sel_hi:[0,1]
	v_pk_mul_f32 v[54:55], v[60:61], v[54:55]
	v_mul_f32_e32 v60, 0xbfb8aa3b, v57
	v_pk_mul_f32 v[58:59], v[68:69], v[58:59] op_sel_hi:[0,1]
	v_exp_f32_e32 v61, v60
	v_add_f32_e32 v60, 1.0, v62
	v_mul_f32_e32 v62, 0xbfb8aa3b, v58
	v_mul_f32_e32 v63, 0xbfb8aa3b, v59
	v_exp_f32_e32 v62, v62
	v_exp_f32_e32 v63, v63
	v_add_f32_e32 v61, 1.0, v61
	v_rcp_f32_e32 v60, v60
	v_rcp_f32_e32 v61, v61
	v_add_f32_e32 v62, 1.0, v62
	v_add_f32_e32 v63, 1.0, v63
	v_rcp_f32_e32 v62, v62
	v_rcp_f32_e32 v63, v63
	v_pk_mul_f32 v[48:49], v[68:69], v[48:49] op_sel_hi:[0,1]
	v_pk_mul_f32 v[56:57], v[56:57], v[60:61]
	s_nop 0
	v_pk_mul_f32 v[56:57], v[56:57], v[48:49]
	v_pk_mul_f32 v[48:49], v[68:69], v[50:51] op_sel_hi:[0,1]
	v_pk_mul_f32 v[50:51], v[58:59], v[62:63]
	s_nop 0
	v_pk_mul_f32 v[58:59], v[50:51], v[48:49]
	v_mul_f32_e32 v49, 0x4b800000, v64
	v_cndmask_b32_e32 v49, v64, v49, vcc
	v_cvt_pk_bf16_f32 v48, v52, v53
	v_rsq_f32_e32 v52, v49
	v_cvt_pk_bf16_f32 v49, v54, v55
	v_cvt_pk_bf16_f32 v50, v56, v57
	v_cvt_pk_bf16_f32 v51, v58, v59
	v_mul_f32_e32 v53, 0x45800000, v52
	v_cndmask_b32_e32 v52, v52, v53, vcc
	v_pk_mul_f32 v[44:45], v[52:53], v[44:45] op_sel_hi:[0,1]
	v_mul_f32_e32 v53, 0xbfb8aa3b, v44
	v_exp_f32_e32 v53, v53
	global_store_dwordx4 v[66:67], v[48:51], off
	v_pk_mul_f32 v[46:47], v[52:53], v[46:47] op_sel_hi:[0,1]
	s_nop 0
	v_mul_f32_e32 v48, 0xbfb8aa3b, v45
	v_exp_f32_e32 v49, v48
	v_mul_f32_e32 v50, 0xbfb8aa3b, v46
	v_mul_f32_e32 v51, 0xbfb8aa3b, v47
	v_exp_f32_e32 v50, v50
	v_exp_f32_e32 v51, v51
	v_add_f32_e32 v48, 1.0, v53
	v_add_f32_e32 v49, 1.0, v49
	v_rcp_f32_e32 v48, v48
	v_rcp_f32_e32 v49, v49
	v_add_f32_e32 v50, 1.0, v50
	v_add_f32_e32 v51, 1.0, v51
	v_rcp_f32_e32 v50, v50
	v_rcp_f32_e32 v51, v51
	v_pk_mul_f32 v[36:37], v[52:53], v[36:37] op_sel_hi:[0,1]
	v_pk_mul_f32 v[44:45], v[44:45], v[48:49]
	v_pk_mul_f32 v[40:41], v[52:53], v[40:41] op_sel_hi:[0,1]
	v_pk_mul_f32 v[36:37], v[44:45], v[36:37]
	v_pk_mul_f32 v[44:45], v[46:47], v[50:51]
	v_mul_f32_e32 v46, 0xbfb8aa3b, v40
	v_exp_f32_e32 v46, v46
	v_pk_mul_f32 v[38:39], v[52:53], v[38:39] op_sel_hi:[0,1]
	v_pk_mul_f32 v[38:39], v[44:45], v[38:39]
	v_mul_f32_e32 v44, 0xbfb8aa3b, v41
	v_pk_mul_f32 v[42:43], v[52:53], v[42:43] op_sel_hi:[0,1]
	v_exp_f32_e32 v45, v44
	v_add_f32_e32 v44, 1.0, v46
	v_mul_f32_e32 v46, 0xbfb8aa3b, v42
	v_mul_f32_e32 v47, 0xbfb8aa3b, v43
	v_exp_f32_e32 v46, v46
	v_exp_f32_e32 v47, v47
	v_add_f32_e32 v45, 1.0, v45
	v_rcp_f32_e32 v44, v44
	v_rcp_f32_e32 v45, v45
	v_add_f32_e32 v46, 1.0, v46
	v_add_f32_e32 v47, 1.0, v47
	v_rcp_f32_e32 v46, v46
	v_rcp_f32_e32 v47, v47
	v_pk_mul_f32 v[32:33], v[52:53], v[32:33] op_sel_hi:[0,1]
	v_pk_mul_f32 v[40:41], v[40:41], v[44:45]
	s_nop 0
	v_pk_mul_f32 v[40:41], v[40:41], v[32:33]
	v_pk_mul_f32 v[32:33], v[52:53], v[34:35] op_sel_hi:[0,1]
	v_pk_mul_f32 v[34:35], v[42:43], v[46:47]
	s_nop 0
	v_pk_mul_f32 v[42:43], v[34:35], v[32:33]
	v_cvt_pk_bf16_f32 v32, v36, v37
	v_add_u32_e32 v36, 0x90, v152
	v_mad_i64_i32 v[36:37], s[30:31], v36, s46, v[154:155]
	v_cvt_pk_bf16_f32 v33, v38, v39
	v_cvt_pk_bf16_f32 v34, v40, v41
	v_cvt_pk_bf16_f32 v35, v42, v43
	v_lshl_add_u64 v[36:37], v[36:37], 0, v[156:157]
	global_store_dwordx4 v[36:37], v[32:35], off
	s_nop 1
	v_pk_fma_f32 v[32:33], v[150:151], s[18:19], v[158:159] op_sel_hi:[1,0,0]
	s_nop 0
	v_mul_f32_e32 v34, 0x4b800000, v33
	v_cmp_gt_f32_e32 vcc, s47, v33
	s_nop 1
	v_cndmask_b32_e32 v33, v33, v34, vcc
	v_rsq_f32_e32 v33, v33
	v_add_u32_e32 v34, 0xa0, v152
	v_mad_i64_i32 v[34:35], s[30:31], v34, s46, v[154:155]
	v_mul_f32_e32 v36, 0x45800000, v33
	v_cndmask_b32_e32 v36, v33, v36, vcc
	v_pk_mul_f32 v[28:29], v[36:37], v[28:29] op_sel_hi:[0,1]
	v_mul_f32_e32 v33, 0xbfb8aa3b, v28
	v_mul_f32_e32 v37, 0xbfb8aa3b, v29
	v_exp_f32_e32 v33, v33
	v_exp_f32_e32 v37, v37
	v_cmp_gt_f32_e32 vcc, s47, v32
	v_lshl_add_u64 v[34:35], v[34:35], 0, v[156:157]
	v_add_f32_e32 v33, 1.0, v33
	v_pk_mul_f32 v[30:31], v[36:37], v[30:31] op_sel_hi:[0,1]
	v_rcp_f32_e32 v38, v33
	v_pk_mul_f32 v[20:21], v[36:37], v[20:21] op_sel_hi:[0,1]
	v_add_f32_e32 v33, 1.0, v37
	v_mul_f32_e32 v37, 0xbfb8aa3b, v30
	v_exp_f32_e32 v37, v37
	v_mul_f32_e32 v39, 0xbfb8aa3b, v31
	v_exp_f32_e32 v41, v39
	v_rcp_f32_e32 v39, v33
	v_add_f32_e32 v33, 1.0, v37
	v_rcp_f32_e32 v40, v33
	v_add_f32_e32 v33, 1.0, v41
	v_rcp_f32_e32 v41, v33
	v_pk_mul_f32 v[28:29], v[28:29], v[38:39]
	v_pk_mul_f32 v[24:25], v[36:37], v[24:25] op_sel_hi:[0,1]
	v_pk_mul_f32 v[20:21], v[28:29], v[20:21]
	v_pk_mul_f32 v[28:29], v[30:31], v[40:41]
	v_mul_f32_e32 v30, 0xbfb8aa3b, v24
	v_exp_f32_e32 v30, v30
	v_pk_mul_f32 v[22:23], v[36:37], v[22:23] op_sel_hi:[0,1]
	v_pk_mul_f32 v[22:23], v[28:29], v[22:23]
	v_mul_f32_e32 v28, 0xbfb8aa3b, v25
	v_pk_mul_f32 v[26:27], v[36:37], v[26:27] op_sel_hi:[0,1]
	v_exp_f32_e32 v29, v28
	v_add_f32_e32 v28, 1.0, v30
	v_mul_f32_e32 v30, 0xbfb8aa3b, v26
	v_mul_f32_e32 v31, 0xbfb8aa3b, v27
	v_exp_f32_e32 v30, v30
	v_exp_f32_e32 v31, v31
	v_add_f32_e32 v29, 1.0, v29
	v_rcp_f32_e32 v28, v28
	v_rcp_f32_e32 v29, v29
	v_add_f32_e32 v30, 1.0, v30
	v_add_f32_e32 v31, 1.0, v31
	v_rcp_f32_e32 v30, v30
	v_rcp_f32_e32 v31, v31
	v_pk_mul_f32 v[16:17], v[36:37], v[16:17] op_sel_hi:[0,1]
	v_pk_mul_f32 v[24:25], v[24:25], v[28:29]
	s_nop 0
	v_pk_mul_f32 v[24:25], v[24:25], v[16:17]
	v_pk_mul_f32 v[16:17], v[36:37], v[18:19] op_sel_hi:[0,1]
	v_pk_mul_f32 v[18:19], v[26:27], v[30:31]
	s_nop 0
	v_pk_mul_f32 v[26:27], v[18:19], v[16:17]
	v_mul_f32_e32 v17, 0x4b800000, v32
	v_cndmask_b32_e32 v17, v32, v17, vcc
	v_cvt_pk_bf16_f32 v16, v20, v21
	v_rsq_f32_e32 v20, v17
	v_cvt_pk_bf16_f32 v17, v22, v23
	v_cvt_pk_bf16_f32 v18, v24, v25
	v_cvt_pk_bf16_f32 v19, v26, v27
	v_mul_f32_e32 v21, 0x45800000, v20
	v_cndmask_b32_e32 v20, v20, v21, vcc
	v_pk_mul_f32 v[12:13], v[20:21], v[12:13] op_sel_hi:[0,1]
	v_mul_f32_e32 v21, 0xbfb8aa3b, v12
	v_exp_f32_e32 v21, v21
	global_store_dwordx4 v[34:35], v[16:19], off
	s_andn2_b64 vcc, exec, s[8:9]
	s_mov_b64 s[8:9], -1
	v_mul_f32_e32 v16, 0xbfb8aa3b, v13
	v_pk_mul_f32 v[14:15], v[20:21], v[14:15] op_sel_hi:[0,1]
	v_exp_f32_e32 v17, v16
	v_mul_f32_e32 v18, 0xbfb8aa3b, v14
	v_mul_f32_e32 v19, 0xbfb8aa3b, v15
	v_exp_f32_e32 v18, v18
	v_exp_f32_e32 v19, v19
	v_add_f32_e32 v16, 1.0, v21
	v_add_f32_e32 v17, 1.0, v17
	v_rcp_f32_e32 v16, v16
	v_rcp_f32_e32 v17, v17
	v_add_f32_e32 v18, 1.0, v18
	v_add_f32_e32 v19, 1.0, v19
	v_rcp_f32_e32 v18, v18
	v_rcp_f32_e32 v19, v19
	v_pk_mul_f32 v[4:5], v[20:21], v[4:5] op_sel_hi:[0,1]
	v_pk_mul_f32 v[12:13], v[12:13], v[16:17]
	v_pk_mul_f32 v[8:9], v[20:21], v[8:9] op_sel_hi:[0,1]
	v_pk_mul_f32 v[4:5], v[12:13], v[4:5]
	v_pk_mul_f32 v[12:13], v[14:15], v[18:19]
	v_mul_f32_e32 v14, 0xbfb8aa3b, v8
	v_exp_f32_e32 v14, v14
	v_pk_mul_f32 v[6:7], v[20:21], v[6:7] op_sel_hi:[0,1]
	v_pk_mul_f32 v[6:7], v[12:13], v[6:7]
	v_mul_f32_e32 v12, 0xbfb8aa3b, v9
	v_pk_mul_f32 v[10:11], v[20:21], v[10:11] op_sel_hi:[0,1]
	v_exp_f32_e32 v13, v12
	v_add_f32_e32 v12, 1.0, v14
	v_mul_f32_e32 v14, 0xbfb8aa3b, v10
	v_mul_f32_e32 v15, 0xbfb8aa3b, v11
	v_exp_f32_e32 v14, v14
	v_exp_f32_e32 v15, v15
	v_add_f32_e32 v13, 1.0, v13
	v_rcp_f32_e32 v12, v12
	v_rcp_f32_e32 v13, v13
	v_add_f32_e32 v14, 1.0, v14
	v_add_f32_e32 v15, 1.0, v15
	v_rcp_f32_e32 v14, v14
	v_rcp_f32_e32 v15, v15
	v_pk_mul_f32 v[0:1], v[20:21], v[0:1] op_sel_hi:[0,1]
	v_pk_mul_f32 v[8:9], v[8:9], v[12:13]
	s_nop 0
	v_pk_mul_f32 v[8:9], v[8:9], v[0:1]
	v_pk_mul_f32 v[0:1], v[20:21], v[2:3] op_sel_hi:[0,1]
	v_pk_mul_f32 v[2:3], v[10:11], v[14:15]
	s_nop 0
	v_pk_mul_f32 v[10:11], v[2:3], v[0:1]
	v_cvt_pk_bf16_f32 v0, v4, v5
	v_add_u32_e32 v4, 0xb0, v152
	v_mad_i64_i32 v[4:5], s[30:31], v4, s46, v[154:155]
	v_cvt_pk_bf16_f32 v1, v6, v7
	v_cvt_pk_bf16_f32 v2, v8, v9
	v_cvt_pk_bf16_f32 v3, v10, v11
	v_lshl_add_u64 v[4:5], v[4:5], 0, v[156:157]
	global_store_dwordx4 v[4:5], v[0:3], off
	s_cbranch_vccnz .LBB0_1400
	s_andn2_b64 vcc, exec, s[0:1]
	s_cbranch_vccnz .LBB0_1399
	s_barrier
	s_branch .LBB0_1399

.LBB0_1538:
	s_add_u32 s10, s88, 0x3a140000
	s_addc_u32 s11, s89, 0
	s_and_b64 vcc, exec, s[92:93]
	s_cbranch_vccnz .LBB0_1578
	v_ashrrev_i32_e32 v1, 31, v8
	v_lshrrev_b32_e32 v1, 26, v1
	v_add_u32_e32 v1, v8, v1
	v_ashrrev_i32_e32 v9, 6, v1
	v_bfe_i32 v1, v8, 27, 1
	v_lshlrev_b32_e32 v0, 4, v8
	v_lshrrev_b32_e32 v1, 22, v1
	v_add_u32_e32 v1, v0, v1
	v_and_b32_e32 v1, 0xfffffc00, v1
	v_sub_u32_e32 v1, v0, v1
	v_lshrrev_b32_e32 v2, 4, v1
	v_bitop3_b32 v1, v2, v1, 32 bitop3:0x6c
	v_ashrrev_i32_e32 v3, 31, v1
	v_lshrrev_b32_e32 v3, 26, v3
	v_lshlrev_b32_e32 v2, 3, v9
	v_add_u32_e32 v3, v1, v3
	v_and_b32_e32 v2, -16, v2
	v_ashrrev_i32_e32 v10, 6, v3
	v_and_b32_e32 v3, 0xc0, v3
	v_add_u32_e32 v2, v10, v2
	v_lshlrev_b32_e32 v4, 5, v9
	v_sub_u32_e32 v1, v1, v3
	v_mov_b32_e32 v3, 1
	v_and_b32_e32 v11, 32, v4
	v_ashrrev_i16_sdwa v1, v3, sext(v1) dst_sel:DWORD dst_unused:UNUSED_PAD src0_sel:DWORD src1_sel:BYTE_0
	v_lshlrev_b32_e32 v4, 1, v2
	v_lshrrev_b32_e32 v5, 2, v2
	v_and_b32_e32 v6, 3, v10
	s_mov_b32 s5, 0x7fffe0
	v_bfe_i32 v12, v1, 0, 16
	v_and_b32_e32 v4, 24, v4
	v_and_b32_e32 v5, 4, v5
	v_and_or_b32 v6, v2, s5, v6
	s_movk_i32 s1, 0x1600
	v_add_u32_e32 v1, v11, v12
	v_or3_b32 v4, v6, v5, v4
	v_mul_lo_u32 v2, v2, s1
	v_add_lshl_u32 v128, v1, v2, 1
	v_mul_u32_u24_e32 v2, 0x1600, v4
	v_add_u32_e32 v0, 0x2000, v0
	v_add_lshl_u32 v130, v2, v1, 1
	v_ashrrev_i32_e32 v1, 31, v0
	v_lshrrev_b32_e32 v1, 22, v1
	v_add_u32_e32 v1, v0, v1
	v_ashrrev_i32_e32 v13, 10, v1
	v_mul_i32_i24_e32 v1, 0x400, v13
	v_sub_u32_e32 v0, v0, v1
	v_lshrrev_b32_e32 v1, 4, v0
	v_bitop3_b32 v0, v1, v0, 32 bitop3:0x6c
	v_ashrrev_i32_e32 v2, 31, v0
	v_lshrrev_b32_e32 v2, 26, v2
	v_lshlrev_b32_e32 v1, 3, v13
	v_add_u32_e32 v2, v0, v2
	v_and_b32_e32 v1, -16, v1
	v_ashrrev_i32_e32 v14, 6, v2
	v_lshlrev_b32_e32 v4, 5, v13
	s_add_u32 s2, s88, 0xdc00000
	v_add_u32_e32 v1, v14, v1
	v_and_b32_e32 v15, 32, v4
	v_and_b32_e32 v4, 3, v14
	s_addc_u32 s6, s89, 0
	v_and_b32_e32 v2, 0xc0, v2
	v_and_or_b32 v4, v1, s5, v4
	s_ashr_i32 s5, s4, 6
	s_ashr_i32 s0, s4, 8
	v_sub_u32_e32 v0, v0, v2
	s_lshl_b32 s7, s5, 10
	s_mul_i32 s9, s45, 0x2c0000
	v_ashrrev_i16_sdwa v0, v3, sext(v0) dst_sel:DWORD dst_unused:UNUSED_PAD src0_sel:DWORD src1_sel:BYTE_0
	v_lshlrev_b32_e32 v2, 1, v1
	v_lshrrev_b32_e32 v3, 2, v1
	s_mul_hi_i32 s8, s45, 0x2c0000
	s_add_u32 s22, s2, s9
	v_bfe_i32 v16, v0, 0, 16
	v_and_b32_e32 v2, 24, v2
	v_and_b32_e32 v3, 4, v3
	s_addc_u32 s23, s6, s8
	s_add_i32 s28, s7, 0
	v_add_u32_e32 v0, v15, v16
	v_or3_b32 v2, v4, v3, v2
	v_mul_lo_u32 v1, v1, s1
	s_add_i32 m0, s28, 0x10000
	v_add_lshl_u32 v132, v0, v1, 1
	v_mul_u32_u24_e32 v1, 0x1600, v2
	global_load_lds_dwordx4 v130, s[22:23]
	s_add_i32 m0, s28, 0x12000
	v_add_lshl_u32 v134, v1, v0, 1
	s_add_u32 s8, s22, 0x160000
	global_load_lds_dwordx4 v134, s[22:23]
	s_addc_u32 s9, s23, 0
	s_add_i32 m0, s28, 0x14000
	s_mul_i32 s13, s44, 0x2c0000
	global_load_lds_dwordx4 v130, s[8:9]
	s_add_i32 m0, s28, 0x16000
	s_mul_hi_i32 s12, s44, 0x2c0000
	s_add_u32 s20, s64, s13
	s_addc_u32 s21, s65, s12
	s_add_i32 s29, s28, 0x2000
	global_load_lds_dwordx4 v134, s[8:9]
	s_mov_b32 m0, s28
	s_add_u32 s8, s20, 0x160000
	global_load_lds_dwordx4 v128, s[20:21]
	s_mov_b32 m0, s29
	s_addc_u32 s9, s21, 0
	s_add_i32 s30, s28, 0x4000
	global_load_lds_dwordx4 v132, s[20:21]
	s_mov_b32 m0, s30
	s_add_i32 s31, s28, 0x6000
	global_load_lds_dwordx4 v128, s[8:9]
	s_mov_b32 m0, s31
	v_mov_b32_e32 v131, 0
	global_load_lds_dwordx4 v132, s[8:9]
	v_mov_b32_e32 v135, v131
	v_mov_b32_e32 v129, v131
	v_mov_b32_e32 v133, v131
	s_cmp_eq_u32 s0, 1
	s_mov_b32 s34, 0
	v_lshl_add_u64 v[6:7], s[22:23], 0, v[130:131]
	v_lshl_add_u64 v[2:3], s[22:23], 0, v[134:135]
	s_mov_b32 s8, 0x16000
	v_lshl_add_u64 v[0:1], s[20:21], 0, v[128:129]
	s_cselect_b64 s[12:13], -1, 0
	s_cmp_lg_u32 s0, 1
	v_lshl_add_u64 v[4:5], s[20:21], 0, v[132:133]
	s_cbranch_scc1 .LBB0_1541
	s_setprio 1
	s_barrier

.LBB0_1558:
	s_setprio 0
	v_lshl_add_u32 v146, s44, 8, v148
	v_ashrrev_i32_e32 v147, 31, v146
	v_lshl_or_b32 v144, s45, 8, v150
	v_lshlrev_b64 v[156:157], 12, v[146:147]
	v_ashrrev_i32_e32 v145, 31, v144
	v_lshl_add_u64 v[156:157], s[60:61], 0, v[156:157]
	v_lshl_add_u64 v[164:165], v[144:145], 1, v[156:157]
	global_load_dwordx4 v[156:159], v[164:165], off
	global_load_dwordx4 v[160:163], v[164:165], off offset:256
	v_and_b32_e32 v166, 64, v154
	v_xor_b32_e32 v155, 16, v154
	v_add_u32_e32 v166, 64, v166
	v_xor_b32_e32 v167, 32, v154
	v_cmp_lt_i32_e32 vcc, v155, v166
	s_waitcnt vmcnt(0)
	v_lshlrev_b32_e32 v168, 16, v158
	v_cndmask_b32_e32 v155, v154, v155, vcc
	v_cmp_lt_i32_e32 vcc, v167, v166
	v_lshlrev_b32_e32 v166, 16, v156
	v_and_b32_e32 v169, 0xffff0000, v158
	v_cndmask_b32_e32 v174, v154, v167, vcc
	v_and_b32_e32 v167, 0xffff0000, v156
	v_lshlrev_b32_e32 v156, 16, v157
	v_and_b32_e32 v157, 0xffff0000, v157
	v_lshlrev_b32_e32 v158, 16, v159
	v_and_b32_e32 v159, 0xffff0000, v159
	v_lshlrev_b32_e32 v170, 16, v160
	v_and_b32_e32 v171, 0xffff0000, v160
	v_lshlrev_b32_e32 v160, 16, v161
	v_and_b32_e32 v161, 0xffff0000, v161
	v_lshlrev_b32_e32 v172, 16, v162
	v_and_b32_e32 v173, 0xffff0000, v162
	v_lshlrev_b32_e32 v162, 16, v163
	v_and_b32_e32 v163, 0xffff0000, v163
	v_pk_fma_f32 v[126:127], v[126:127], 0.5, v[156:157] op_sel_hi:[1,0,1]
	v_pk_fma_f32 v[124:125], v[124:125], 0.5, v[166:167] op_sel_hi:[1,0,1]
	v_pk_fma_f32 v[122:123], v[122:123], 0.5, v[158:159] op_sel_hi:[1,0,1]
	v_pk_fma_f32 v[120:121], v[120:121], 0.5, v[168:169] op_sel_hi:[1,0,1]
	v_pk_fma_f32 v[118:119], v[118:119], 0.5, v[160:161] op_sel_hi:[1,0,1]
	v_pk_fma_f32 v[116:117], v[116:117], 0.5, v[170:171] op_sel_hi:[1,0,1]
	v_pk_fma_f32 v[156:157], v[114:115], 0.5, v[162:163] op_sel_hi:[1,0,1]
	v_pk_fma_f32 v[158:159], v[112:113], 0.5, v[172:173] op_sel_hi:[1,0,1]
	v_cvt_pk_bf16_f32 v112, v124, v125
	v_cvt_pk_bf16_f32 v113, v126, v127
	v_mul_f32_e32 v114, v125, v125
	v_mul_f32_e32 v115, v127, v127
	v_mul_f32_e32 v125, v121, v121
	v_mul_f32_e32 v127, v123, v123
	v_mul_f32_e32 v160, v117, v117
	v_mul_f32_e32 v161, v119, v119
	v_mul_f32_e32 v162, v159, v159
	v_mul_f32_e32 v163, v157, v157
	v_fmac_f32_e32 v114, v124, v124
	v_fmac_f32_e32 v115, v126, v126
	v_fmac_f32_e32 v125, v120, v120
	v_fmac_f32_e32 v127, v122, v122
	v_fmac_f32_e32 v160, v116, v116
	v_fmac_f32_e32 v161, v118, v118
	v_fmac_f32_e32 v162, v158, v158
	v_fmac_f32_e32 v163, v156, v156
	v_add_f32_e32 v114, v114, v115
	v_add_f32_e32 v115, v125, v127
	v_add_f32_e32 v124, v160, v161
	v_add_f32_e32 v125, v162, v163
	v_add_f32_e32 v114, v114, v115
	v_add_f32_e32 v115, v124, v125
	v_lshlrev_b32_e32 v155, 2, v155
	v_add_f32_e32 v124, v114, v115
	ds_bpermute_b32 v125, v155, v124
	v_cvt_pk_bf16_f32 v114, v120, v121
	v_cvt_pk_bf16_f32 v115, v122, v123
	global_store_dwordx4 v[164:165], v[112:115], off
	v_cvt_pk_bf16_f32 v116, v116, v117
	v_cvt_pk_bf16_f32 v117, v118, v119
	s_waitcnt lgkmcnt(0)
	v_add_f32_e32 v112, v124, v125
	v_lshlrev_b32_e32 v114, 2, v174
	ds_bpermute_b32 v113, v114, v112
	v_cvt_pk_bf16_f32 v118, v158, v159
	v_cvt_pk_bf16_f32 v119, v156, v157
	global_store_dwordx4 v[164:165], v[116:119], off offset:256
	s_and_saveexec_b64 s[20:21], s[4:5]
	s_cbranch_execz .LBB0_1560
	s_waitcnt lgkmcnt(0)
	v_add_f32_e32 v112, v112, v113
	v_mul_f32_e32 v112, 0x4b800000, v112
	v_rndne_f32_e32 v112, v112
	v_mul_f32_e32 v113, 0x2f800000, v112
	v_floor_f32_e32 v113, v113
	v_fmac_f32_e32 v112, 0xcf800000, v113
	v_cvt_u32_f32_e32 v112, v112
	v_cvt_u32_f32_e32 v113, v113
	v_lshl_add_u64 v[116:117], v[146:147], 3, s[10:11]
	global_atomic_add_x2 v[116:117], v[112:113], off

.LBB0_1635:
	v_ashrrev_i32_e32 v1, 31, v8
	v_lshrrev_b32_e32 v1, 26, v1
	v_add_u32_e32 v1, v8, v1
	v_ashrrev_i32_e32 v9, 6, v1
	v_bfe_i32 v1, v8, 27, 1
	v_lshlrev_b32_e32 v0, 4, v8
	v_lshrrev_b32_e32 v1, 22, v1
	v_add_u32_e32 v1, v0, v1
	v_and_b32_e32 v1, 0xfffffc00, v1
	v_sub_u32_e32 v1, v0, v1
	v_lshrrev_b32_e32 v2, 4, v1
	v_bitop3_b32 v1, v2, v1, 32 bitop3:0x6c
	v_ashrrev_i32_e32 v3, 31, v1
	v_lshrrev_b32_e32 v3, 26, v3
	v_add_u32_e32 v3, v1, v3
	v_lshlrev_b32_e32 v2, 3, v9
	v_ashrrev_i32_e32 v10, 6, v3
	v_and_b32_e32 v3, 0xc0, v3
	v_and_b32_e32 v2, -16, v2
	v_sub_u32_e32 v1, v1, v3
	v_mov_b32_e32 v3, 1
	v_add_u32_e32 v2, v10, v2
	v_ashrrev_i16_sdwa v1, v3, sext(v1) dst_sel:DWORD dst_unused:UNUSED_PAD src0_sel:DWORD src1_sel:BYTE_0
	v_lshlrev_b32_e32 v4, 5, v9
	v_bfe_i32 v11, v1, 0, 16
	v_lshlrev_b32_e32 v1, 1, v2
	v_lshrrev_b32_e32 v5, 2, v2
	v_and_b32_e32 v6, 3, v10
	s_mov_b32 s1, 0xfffe0
	v_and_b32_e32 v4, 32, v4
	v_and_b32_e32 v1, 24, v1
	v_and_b32_e32 v5, 4, v5
	v_and_or_b32 v6, v2, s1, v6
	v_or3_b32 v1, v6, v5, v1
	v_add_lshl_u32 v4, v4, v11, 1
	v_add_u32_e32 v0, 0x2000, v0
	v_lshl_add_u32 v130, v1, 12, v4
	v_ashrrev_i32_e32 v1, 31, v0
	v_lshrrev_b32_e32 v1, 22, v1
	v_add_u32_e32 v1, v0, v1
	v_ashrrev_i32_e32 v12, 10, v1
	v_mul_i32_i24_e32 v1, 0x400, v12
	v_sub_u32_e32 v0, v0, v1
	v_lshrrev_b32_e32 v1, 4, v0
	v_bitop3_b32 v0, v1, v0, 32 bitop3:0x6c
	v_lshl_add_u32 v128, v2, 12, v4
	v_ashrrev_i32_e32 v2, 31, v0
	v_lshrrev_b32_e32 v2, 26, v2
	v_add_u32_e32 v2, v0, v2
	s_ashr_i32 s8, s5, 6
	s_ashr_i32 s0, s6, 3
	s_ashr_i32 s12, s5, 8
	v_lshlrev_b32_e32 v1, 3, v12
	v_ashrrev_i32_e32 v13, 6, v2
	v_and_b32_e32 v2, 0xc0, v2
	s_lshl_b32 s6, s8, 10
	v_and_b32_e32 v1, -16, v1
	v_sub_u32_e32 v0, v0, v2
	s_add_u32 s7, s88, 0x13200000
	v_add_u32_e32 v1, v13, v1
	v_ashrrev_i16_sdwa v0, v3, sext(v0) dst_sel:DWORD dst_unused:UNUSED_PAD src0_sel:DWORD src1_sel:BYTE_0
	v_and_b32_e32 v3, 3, v13
	s_addc_u32 s15, s89, 0
	s_add_i32 s0, s4, s0
	v_and_or_b32 v3, v1, s1, v3
	s_ashr_i32 s1, s0, 31
	s_lshr_b32 s1, s1, 26
	s_add_i32 s1, s0, s1
	s_ashr_i32 s4, s1, 6
	s_andn2_b32 s1, s1, 63
	s_sub_i32 s0, s0, s1
	s_bfe_i32 s1, s0, 0x80000
	s_bfe_u32 s1, s1, 0x3000c
	s_add_i32 s1, s0, s1
	s_lshl_b32 s9, s4, 3
	s_bfe_i32 s4, s1, 0x80000
	s_and_b32 s1, s1, 0xf8
	s_sub_i32 s0, s0, s1
	s_sext_i32_i16 s4, s4
	s_sext_i32_i8 s0, s0
	s_lshr_b32 s4, s4, 3
	s_add_i32 s40, s9, s0
	s_ashr_i32 s41, s40, 31
	s_bfe_i64 s[16:17], s[4:5], 0x100000
	s_lshl_b64 s[0:1], s[40:41], 20
	s_lshl_b64 s[16:17], s[16:17], 20
	s_add_u32 s42, s7, s16
	v_lshlrev_b32_e32 v4, 5, v12
	v_bfe_i32 v14, v0, 0, 16
	v_lshlrev_b32_e32 v0, 1, v1
	v_lshrrev_b32_e32 v2, 2, v1
	s_addc_u32 s43, s15, s17
	s_add_i32 s17, s6, 0
	v_and_b32_e32 v4, 32, v4
	v_and_b32_e32 v0, 24, v0
	v_and_b32_e32 v2, 4, v2
	s_add_i32 m0, s17, 0x10000
	v_or3_b32 v0, v3, v2, v0
	v_add_lshl_u32 v2, v4, v14, 1
	global_load_lds_dwordx4 v130, s[42:43]
	s_add_i32 m0, s17, 0x12000
	v_lshl_add_u32 v134, v0, 12, v2
	s_add_u32 s18, s42, 0x80000
	global_load_lds_dwordx4 v134, s[42:43]
	s_addc_u32 s19, s43, 0
	s_add_i32 m0, s17, 0x14000
	v_lshl_add_u32 v132, v1, 12, v2
	global_load_lds_dwordx4 v130, s[18:19]
	s_add_i32 m0, s17, 0x16000
	s_add_u32 s44, s60, s0
	global_load_lds_dwordx4 v134, s[18:19]
	s_addc_u32 s45, s61, s1
	s_add_i32 s19, s17, 0x2000
	s_mov_b32 m0, s17
	s_add_u32 s0, s44, 0x80000
	global_load_lds_dwordx4 v128, s[44:45]
	s_mov_b32 m0, s19
	s_addc_u32 s1, s45, 0
	s_add_i32 s46, s17, 0x4000
	global_load_lds_dwordx4 v132, s[44:45]
	s_mov_b32 m0, s46
	s_add_i32 s47, s17, 0x6000
	global_load_lds_dwordx4 v128, s[0:1]
	s_mov_b32 m0, s47
	v_mov_b32_e32 v131, 0
	global_load_lds_dwordx4 v132, s[0:1]
	v_mov_b32_e32 v135, v131
	v_mov_b32_e32 v129, v131
	v_mov_b32_e32 v133, v131
	s_cmp_eq_u32 s12, 1
	s_mov_b32 s48, 0
	v_lshl_add_u64 v[6:7], s[42:43], 0, v[130:131]
	v_lshl_add_u64 v[2:3], s[42:43], 0, v[134:135]
	v_lshl_add_u64 v[0:1], s[44:45], 0, v[128:129]
	s_cselect_b64 s[0:1], -1, 0
	s_cmp_lg_u32 s12, 1
	v_lshl_add_u64 v[4:5], s[44:45], 0, v[132:133]
	s_cbranch_scc1 .LBB0_1637
	s_setprio 1
	s_barrier

.LBB0_1652:
	s_setprio 0
	v_mov_b64_e32 v[156:157], s[18:19]
	v_pk_fma_f32 v[164:165], v[148:149], s[16:17], v[156:157] op_sel_hi:[1,0,0]
	v_lshlrev_b64 v[162:163], 12, v[152:153]
	v_mul_f32_e32 v153, 0x4b800000, v165
	v_cmp_gt_f32_e32 vcc, s54, v165
	v_lshl_or_b32 v154, s62, 8, v160
	v_ashrrev_i32_e32 v155, 31, v154
	v_cndmask_b32_e32 v153, v165, v153, vcc
	v_rsq_f32_e32 v153, v153
	v_lshl_add_u64 v[162:163], s[38:39], 0, v[162:163]
	v_lshlrev_b64 v[166:167], 1, v[154:155]
	v_lshl_add_u64 v[154:155], v[162:163], 0, v[166:167]
	v_mul_f32_e32 v162, 0x45800000, v153
	v_cndmask_b32_e32 v162, v153, v162, vcc
	v_pk_mul_f32 v[124:125], v[162:163], v[124:125] op_sel_hi:[0,1]
	v_pk_mul_f32 v[126:127], v[162:163], v[126:127] op_sel_hi:[0,1]
	v_pk_mul_f32 v[168:169], v[162:163], v[120:121] op_sel_hi:[0,1]
	v_pk_mul_f32 v[170:171], v[162:163], v[122:123] op_sel_hi:[0,1]
	v_cvt_pk_bf16_f32 v120, v124, v125
	v_cvt_pk_bf16_f32 v121, v126, v127
	v_cvt_pk_bf16_f32 v122, v168, v169
	v_cvt_pk_bf16_f32 v123, v170, v171
	global_store_dwordx4 v[154:155], v[120:123], off
	v_cmp_gt_f32_e32 vcc, s54, v164
	v_pk_mul_f32 v[112:113], v[162:163], v[112:113] op_sel_hi:[0,1]
	v_pk_mul_f32 v[122:123], v[162:163], v[110:111] op_sel_hi:[0,1]
	v_mul_f32_e32 v110, 0x4b800000, v164
	v_cndmask_b32_e32 v110, v164, v110, vcc
	v_pk_mul_f32 v[120:121], v[162:163], v[108:109] op_sel_hi:[0,1]
	v_cvt_pk_bf16_f32 v108, v112, v113
	v_rsq_f32_e32 v112, v110
	v_pk_mul_f32 v[114:115], v[162:163], v[114:115] op_sel_hi:[0,1]
	v_cvt_pk_bf16_f32 v109, v114, v115
	v_cvt_pk_bf16_f32 v110, v120, v121
	v_cvt_pk_bf16_f32 v111, v122, v123
	global_store_dwordx4 v[154:155], v[108:111], off offset:256
	s_mov_b64 s[40:41], 0x80000
	s_nop 0
	v_or_b32_e32 v110, 16, v152
	v_mul_f32_e32 v108, 0x45800000, v112
	v_ashrrev_i32_e32 v111, 31, v110
	v_cndmask_b32_e32 v108, v112, v108, vcc
	v_lshlrev_b64 v[110:111], 12, v[110:111]
	v_pk_mul_f32 v[112:113], v[108:109], v[116:117] op_sel_hi:[0,1]
	v_pk_mul_f32 v[114:115], v[108:109], v[118:119] op_sel_hi:[0,1]
	v_pk_mul_f32 v[116:117], v[108:109], v[104:105] op_sel_hi:[0,1]
	v_pk_mul_f32 v[118:119], v[108:109], v[106:107] op_sel_hi:[0,1]
	v_lshl_add_u64 v[110:111], s[38:39], 0, v[110:111]
	v_cvt_pk_bf16_f32 v104, v112, v113
	v_cvt_pk_bf16_f32 v105, v114, v115
	v_cvt_pk_bf16_f32 v106, v116, v117
	v_cvt_pk_bf16_f32 v107, v118, v119
	v_lshl_add_u64 v[110:111], v[110:111], 0, v[166:167]
	global_store_dwordx4 v[110:111], v[104:107], off
	v_pk_mul_f32 v[100:101], v[108:109], v[100:101] op_sel_hi:[0,1]
	v_pk_mul_f32 v[102:103], v[108:109], v[102:103] op_sel_hi:[0,1]
	v_pk_mul_f32 v[104:105], v[108:109], v[96:97] op_sel_hi:[0,1]
	v_pk_mul_f32 v[106:107], v[108:109], v[98:99] op_sel_hi:[0,1]
	v_cvt_pk_bf16_f32 v96, v100, v101
	v_cvt_pk_bf16_f32 v97, v102, v103
	v_cvt_pk_bf16_f32 v98, v104, v105
	v_cvt_pk_bf16_f32 v99, v106, v107
	global_store_dwordx4 v[110:111], v[96:99], off offset:256
	s_nop 1
	v_pk_fma_f32 v[98:99], v[146:147], s[16:17], v[156:157] op_sel_hi:[1,0,0]
	v_or_b32_e32 v96, 32, v152
	v_mul_f32_e32 v100, 0x4b800000, v99
	v_cmp_gt_f32_e32 vcc, s54, v99
	v_ashrrev_i32_e32 v97, 31, v96
	v_lshlrev_b64 v[96:97], 12, v[96:97]
	v_cndmask_b32_e32 v99, v99, v100, vcc
	v_rsq_f32_e32 v99, v99
	v_lshl_add_u64 v[96:97], s[38:39], 0, v[96:97]
	v_lshl_add_u64 v[96:97], v[96:97], 0, v[166:167]
	v_mul_f32_e32 v100, 0x45800000, v99
	v_cndmask_b32_e32 v100, v99, v100, vcc
	v_pk_mul_f32 v[92:93], v[100:101], v[92:93] op_sel_hi:[0,1]
	v_pk_mul_f32 v[94:95], v[100:101], v[94:95] op_sel_hi:[0,1]
	v_pk_mul_f32 v[102:103], v[100:101], v[88:89] op_sel_hi:[0,1]
	v_pk_mul_f32 v[104:105], v[100:101], v[90:91] op_sel_hi:[0,1]
	v_cvt_pk_bf16_f32 v88, v92, v93
	v_cvt_pk_bf16_f32 v89, v94, v95
	v_cvt_pk_bf16_f32 v90, v102, v103
	v_cvt_pk_bf16_f32 v91, v104, v105
	global_store_dwordx4 v[96:97], v[88:91], off
	v_cmp_gt_f32_e32 vcc, s54, v98
	v_pk_mul_f32 v[80:81], v[100:101], v[80:81] op_sel_hi:[0,1]
	v_pk_mul_f32 v[90:91], v[100:101], v[78:79] op_sel_hi:[0,1]
	v_mul_f32_e32 v78, 0x4b800000, v98
	v_cndmask_b32_e32 v78, v98, v78, vcc
	v_pk_mul_f32 v[88:89], v[100:101], v[76:77] op_sel_hi:[0,1]
	v_cvt_pk_bf16_f32 v76, v80, v81
	v_rsq_f32_e32 v80, v78
	v_pk_mul_f32 v[82:83], v[100:101], v[82:83] op_sel_hi:[0,1]
	v_cvt_pk_bf16_f32 v77, v82, v83
	v_cvt_pk_bf16_f32 v78, v88, v89
	v_cvt_pk_bf16_f32 v79, v90, v91
	global_store_dwordx4 v[96:97], v[76:79], off offset:256
	s_nop 1
	v_or_b32_e32 v78, 48, v152
	v_mul_f32_e32 v76, 0x45800000, v80
	v_ashrrev_i32_e32 v79, 31, v78
	v_cndmask_b32_e32 v76, v80, v76, vcc
	v_lshlrev_b64 v[78:79], 12, v[78:79]
	v_pk_mul_f32 v[80:81], v[76:77], v[84:85] op_sel_hi:[0,1]
	v_pk_mul_f32 v[82:83], v[76:77], v[86:87] op_sel_hi:[0,1]
	v_pk_mul_f32 v[84:85], v[76:77], v[72:73] op_sel_hi:[0,1]
	v_pk_mul_f32 v[86:87], v[76:77], v[74:75] op_sel_hi:[0,1]
	v_lshl_add_u64 v[78:79], s[38:39], 0, v[78:79]
	v_cvt_pk_bf16_f32 v72, v80, v81
	v_cvt_pk_bf16_f32 v73, v82, v83
	v_cvt_pk_bf16_f32 v74, v84, v85
	v_cvt_pk_bf16_f32 v75, v86, v87
	v_lshl_add_u64 v[78:79], v[78:79], 0, v[166:167]
	v_pk_mul_f32 v[68:69], v[76:77], v[68:69] op_sel_hi:[0,1]
	global_store_dwordx4 v[78:79], v[72:75], off
	v_pk_mul_f32 v[70:71], v[76:77], v[70:71] op_sel_hi:[0,1]
	s_nop 0
	v_pk_mul_f32 v[72:73], v[76:77], v[64:65] op_sel_hi:[0,1]
	v_cvt_pk_bf16_f32 v64, v68, v69
	v_pk_fma_f32 v[68:69], v[144:145], s[16:17], v[156:157] op_sel_hi:[1,0,0]
	v_pk_mul_f32 v[74:75], v[76:77], v[66:67] op_sel_hi:[0,1]
	v_mul_f32_e32 v67, 0x4b800000, v69
	v_cmp_gt_f32_e32 vcc, s54, v69
	v_cvt_pk_bf16_f32 v65, v70, v71
	v_cvt_pk_bf16_f32 v66, v72, v73
	v_cndmask_b32_e32 v67, v69, v67, vcc
	v_rsq_f32_e32 v69, v67
	v_cvt_pk_bf16_f32 v67, v74, v75
	global_store_dwordx4 v[78:79], v[64:67], off offset:256
	s_nop 1
	v_mul_f32_e32 v66, 0x45800000, v69
	v_cndmask_b32_e32 v66, v69, v66, vcc
	v_pk_mul_f32 v[60:61], v[66:67], v[60:61] op_sel_hi:[0,1]
	v_pk_mul_f32 v[62:63], v[66:67], v[62:63] op_sel_hi:[0,1]
	v_pk_mul_f32 v[70:71], v[66:67], v[56:57] op_sel_hi:[0,1]
	v_pk_mul_f32 v[72:73], v[66:67], v[58:59] op_sel_hi:[0,1]
	v_cvt_pk_bf16_f32 v56, v60, v61
	v_add_co_u32_e32 v60, vcc, s55, v154
	v_cvt_pk_bf16_f32 v57, v62, v63
	v_cvt_pk_bf16_f32 v58, v70, v71
	v_cvt_pk_bf16_f32 v59, v72, v73
	v_addc_co_u32_e32 v61, vcc, 0, v155, vcc
	global_store_dwordx4 v[60:61], v[56:59], off
	v_cmp_gt_f32_e32 vcc, s54, v68
	v_pk_mul_f32 v[48:49], v[66:67], v[48:49] op_sel_hi:[0,1]
	v_pk_mul_f32 v[58:59], v[66:67], v[42:43] op_sel_hi:[0,1]
	v_mul_f32_e32 v42, 0x4b800000, v68
	v_cndmask_b32_e32 v42, v68, v42, vcc
	v_pk_mul_f32 v[56:57], v[66:67], v[40:41] op_sel_hi:[0,1]
	v_cvt_pk_bf16_f32 v40, v48, v49
	v_rsq_f32_e32 v48, v42
	v_pk_mul_f32 v[50:51], v[66:67], v[50:51] op_sel_hi:[0,1]
	v_lshl_add_u64 v[64:65], v[154:155], 0, s[40:41]
	v_cvt_pk_bf16_f32 v41, v50, v51
	v_cvt_pk_bf16_f32 v42, v56, v57
	v_cvt_pk_bf16_f32 v43, v58, v59
	global_store_dwordx4 v[64:65], v[40:43], off offset:256
	s_nop 1
	v_mul_f32_e32 v40, 0x45800000, v48
	v_cndmask_b32_e32 v48, v48, v40, vcc
	v_pk_mul_f32 v[40:41], v[48:49], v[52:53] op_sel_hi:[0,1]
	v_pk_mul_f32 v[42:43], v[48:49], v[54:55] op_sel_hi:[0,1]
	v_pk_mul_f32 v[46:47], v[48:49], v[46:47] op_sel_hi:[0,1]
	v_pk_mul_f32 v[44:45], v[48:49], v[44:45] op_sel_hi:[0,1]
	v_cvt_pk_bf16_f32 v40, v40, v41
	v_cvt_pk_bf16_f32 v41, v42, v43
	v_cvt_pk_bf16_f32 v43, v46, v47
	v_add_co_u32_e32 v46, vcc, s56, v154
	v_cvt_pk_bf16_f32 v42, v44, v45
	s_nop 0
	v_addc_co_u32_e32 v47, vcc, 0, v155, vcc
	v_pk_mul_f32 v[36:37], v[48:49], v[36:37] op_sel_hi:[0,1]
	global_store_dwordx4 v[46:47], v[40:43], off
	v_pk_mul_f32 v[38:39], v[48:49], v[38:39] op_sel_hi:[0,1]
	v_lshl_add_u64 v[44:45], v[154:155], 0, s[20:21]
	v_pk_mul_f32 v[40:41], v[48:49], v[28:29] op_sel_hi:[0,1]
	v_cvt_pk_bf16_f32 v28, v36, v37
	v_pk_fma_f32 v[36:37], v[150:151], s[16:17], v[156:157] op_sel_hi:[1,0,0]
	v_pk_mul_f32 v[42:43], v[48:49], v[30:31] op_sel_hi:[0,1]
	v_mul_f32_e32 v31, 0x4b800000, v37
	v_cmp_gt_f32_e32 vcc, s54, v37
	v_cvt_pk_bf16_f32 v29, v38, v39
	v_cvt_pk_bf16_f32 v30, v40, v41
	v_cndmask_b32_e32 v31, v37, v31, vcc
	v_rsq_f32_e32 v37, v31
	v_cvt_pk_bf16_f32 v31, v42, v43
	global_store_dwordx4 v[44:45], v[28:31], off offset:256
	s_nop 1
	v_mul_f32_e32 v30, 0x45800000, v37
	v_cndmask_b32_e32 v30, v37, v30, vcc
	v_pk_mul_f32 v[32:33], v[30:31], v[32:33] op_sel_hi:[0,1]
	v_pk_mul_f32 v[34:35], v[30:31], v[34:35] op_sel_hi:[0,1]
	v_pk_mul_f32 v[38:39], v[30:31], v[24:25] op_sel_hi:[0,1]
	v_pk_mul_f32 v[40:41], v[30:31], v[26:27] op_sel_hi:[0,1]
	v_cvt_pk_bf16_f32 v24, v32, v33
	v_add_co_u32_e32 v32, vcc, s57, v154
	v_cvt_pk_bf16_f32 v25, v34, v35
	v_cvt_pk_bf16_f32 v26, v38, v39
	v_cvt_pk_bf16_f32 v27, v40, v41
	v_addc_co_u32_e32 v33, vcc, 0, v155, vcc
	global_store_dwordx4 v[32:33], v[24:27], off
	v_cmp_gt_f32_e32 vcc, s54, v36
	v_pk_mul_f32 v[16:17], v[30:31], v[16:17] op_sel_hi:[0,1]
	v_pk_mul_f32 v[26:27], v[30:31], v[10:11] op_sel_hi:[0,1]
	v_mul_f32_e32 v10, 0x4b800000, v36
	v_cndmask_b32_e32 v10, v36, v10, vcc
	v_pk_mul_f32 v[24:25], v[30:31], v[8:9] op_sel_hi:[0,1]
	v_cvt_pk_bf16_f32 v8, v16, v17
	v_rsq_f32_e32 v16, v10
	v_pk_mul_f32 v[18:19], v[30:31], v[18:19] op_sel_hi:[0,1]
	v_lshl_add_u64 v[28:29], v[154:155], 0, s[22:23]
	v_cvt_pk_bf16_f32 v9, v18, v19
	v_cvt_pk_bf16_f32 v10, v24, v25
	v_cvt_pk_bf16_f32 v11, v26, v27
	global_store_dwordx4 v[28:29], v[8:11], off offset:256
	s_nop 1
	v_mul_f32_e32 v8, 0x45800000, v16
	v_cndmask_b32_e32 v16, v16, v8, vcc
	v_pk_mul_f32 v[8:9], v[16:17], v[20:21] op_sel_hi:[0,1]
	v_pk_mul_f32 v[10:11], v[16:17], v[22:23] op_sel_hi:[0,1]
	v_pk_mul_f32 v[14:15], v[16:17], v[14:15] op_sel_hi:[0,1]
	v_pk_mul_f32 v[12:13], v[16:17], v[12:13] op_sel_hi:[0,1]
	v_cvt_pk_bf16_f32 v8, v8, v9
	v_cvt_pk_bf16_f32 v9, v10, v11
	v_cvt_pk_bf16_f32 v11, v14, v15
	v_add_co_u32_e32 v14, vcc, s59, v154
	v_cvt_pk_bf16_f32 v10, v12, v13
	s_nop 0
	v_addc_co_u32_e32 v15, vcc, 0, v155, vcc
	global_store_dwordx4 v[14:15], v[8:11], off
	v_pk_mul_f32 v[4:5], v[16:17], v[4:5] op_sel_hi:[0,1]
	v_pk_mul_f32 v[6:7], v[16:17], v[6:7] op_sel_hi:[0,1]
	v_pk_mul_f32 v[8:9], v[16:17], v[0:1] op_sel_hi:[0,1]
	v_pk_mul_f32 v[10:11], v[16:17], v[2:3] op_sel_hi:[0,1]
	v_lshl_add_u64 v[12:13], v[154:155], 0, s[24:25]
	v_cvt_pk_bf16_f32 v0, v4, v5
	v_cvt_pk_bf16_f32 v1, v6, v7
	v_cvt_pk_bf16_f32 v2, v8, v9
	v_cvt_pk_bf16_f32 v3, v10, v11
	s_andn2_b64 vcc, exec, s[4:5]
	s_mov_b64 s[4:5], -1
	global_store_dwordx4 v[12:13], v[0:3], off offset:256
	s_cbranch_vccnz .LBB0_1639
	s_andn2_b64 vcc, exec, s[0:1]
	s_cbranch_vccnz .LBB0_1638
	s_barrier
	s_branch .LBB0_1638

.LBB0_1852:
	s_add_u32 s0, s88, 0x3a150000
	s_addc_u32 s1, s89, 0
	s_and_b64 vcc, exec, s[64:65]
	s_cbranch_vccnz .LBB0_1888
	v_ashrrev_i32_e32 v1, 31, v8
	v_lshrrev_b32_e32 v1, 26, v1
	v_add_u32_e32 v1, v8, v1
	v_ashrrev_i32_e32 v9, 6, v1
	v_bfe_i32 v1, v8, 27, 1
	v_lshlrev_b32_e32 v0, 4, v8
	v_lshrrev_b32_e32 v1, 22, v1
	v_add_u32_e32 v1, v0, v1
	v_and_b32_e32 v1, 0xfffffc00, v1
	v_sub_u32_e32 v1, v0, v1
	v_lshrrev_b32_e32 v2, 4, v1
	v_bitop3_b32 v1, v2, v1, 32 bitop3:0x6c
	v_ashrrev_i32_e32 v3, 31, v1
	v_lshrrev_b32_e32 v3, 26, v3
	v_add_u32_e32 v3, v1, v3
	v_lshlrev_b32_e32 v2, 3, v9
	v_ashrrev_i32_e32 v10, 6, v3
	v_and_b32_e32 v3, 0xc0, v3
	v_and_b32_e32 v2, -16, v2
	v_sub_u32_e32 v1, v1, v3
	v_mov_b32_e32 v3, 1
	v_add_u32_e32 v2, v10, v2
	v_ashrrev_i16_sdwa v1, v3, sext(v1) dst_sel:DWORD dst_unused:UNUSED_PAD src0_sel:DWORD src1_sel:BYTE_0
	v_lshlrev_b32_e32 v4, 5, v9
	v_bfe_i32 v11, v1, 0, 16
	v_lshlrev_b32_e32 v1, 1, v2
	v_lshrrev_b32_e32 v5, 2, v2
	v_and_b32_e32 v6, 3, v10
	s_mov_b32 s7, 0xfffe0
	v_and_b32_e32 v4, 32, v4
	v_and_b32_e32 v1, 24, v1
	v_and_b32_e32 v5, 4, v5
	v_and_or_b32 v6, v2, s7, v6
	v_or3_b32 v1, v6, v5, v1
	v_add_lshl_u32 v4, v4, v11, 1
	v_add_u32_e32 v0, 0x2000, v0
	v_lshl_add_u32 v130, v1, 12, v4
	v_ashrrev_i32_e32 v1, 31, v0
	v_lshrrev_b32_e32 v1, 22, v1
	v_add_u32_e32 v1, v0, v1
	v_ashrrev_i32_e32 v12, 10, v1
	v_mul_i32_i24_e32 v1, 0x400, v12
	v_sub_u32_e32 v0, v0, v1
	v_lshrrev_b32_e32 v1, 4, v0
	v_bitop3_b32 v0, v1, v0, 32 bitop3:0x6c
	v_lshl_add_u32 v128, v2, 12, v4
	v_ashrrev_i32_e32 v2, 31, v0
	v_lshrrev_b32_e32 v2, 26, v2
	v_add_u32_e32 v2, v0, v2
	v_lshlrev_b32_e32 v1, 3, v12
	v_ashrrev_i32_e32 v13, 6, v2
	v_and_b32_e32 v2, 0xc0, v2
	s_add_u32 s2, s88, 0x37f00000
	v_and_b32_e32 v1, -16, v1
	v_sub_u32_e32 v0, v0, v2
	s_addc_u32 s6, s89, 0
	v_add_u32_e32 v1, v13, v1
	v_ashrrev_i16_sdwa v0, v3, sext(v0) dst_sel:DWORD dst_unused:UNUSED_PAD src0_sel:DWORD src1_sel:BYTE_0
	v_and_b32_e32 v3, 3, v13
	s_ashr_i32 s8, s4, 6
	s_ashr_i32 s5, s4, 8
	v_and_or_b32 v3, v1, s7, v3
	s_lshl_b32 s7, s8, 10
	s_add_u32 s36, s88, 0x13a00000
	s_addc_u32 s37, s89, 0
	s_ashr_i32 s25, s24, 31
	s_ashr_i32 s27, s26, 31
	s_lshl_b64 s[10:11], s[24:25], 20
	s_lshl_b64 s[12:13], s[26:27], 20
	s_add_u32 s30, s36, s12
	v_lshlrev_b32_e32 v4, 5, v12
	v_bfe_i32 v14, v0, 0, 16
	v_lshlrev_b32_e32 v0, 1, v1
	v_lshrrev_b32_e32 v2, 2, v1
	s_addc_u32 s31, s37, s13
	s_add_i32 s27, s7, 0
	v_and_b32_e32 v4, 32, v4
	v_and_b32_e32 v0, 24, v0
	v_and_b32_e32 v2, 4, v2
	s_add_i32 m0, s27, 0x10000
	v_or3_b32 v0, v3, v2, v0
	v_add_lshl_u32 v2, v4, v14, 1
	global_load_lds_dwordx4 v130, s[30:31]
	s_add_i32 m0, s27, 0x12000
	v_lshl_add_u32 v134, v0, 12, v2
	s_add_u32 s12, s30, 0x80000
	global_load_lds_dwordx4 v134, s[30:31]
	s_addc_u32 s13, s31, 0
	s_add_i32 m0, s27, 0x14000
	v_lshl_add_u32 v132, v1, 12, v2
	global_load_lds_dwordx4 v130, s[12:13]
	s_add_i32 m0, s27, 0x16000
	s_add_u32 s28, s2, s10
	s_addc_u32 s29, s6, s11
	s_add_i32 s38, s27, 0x2000
	global_load_lds_dwordx4 v134, s[12:13]
	s_mov_b32 m0, s27
	s_add_u32 s10, s28, 0x80000
	global_load_lds_dwordx4 v128, s[28:29]
	s_mov_b32 m0, s38
	s_addc_u32 s11, s29, 0
	s_add_i32 s39, s27, 0x4000
	global_load_lds_dwordx4 v132, s[28:29]
	s_mov_b32 m0, s39
	s_add_i32 s40, s27, 0x6000
	global_load_lds_dwordx4 v128, s[10:11]
	s_mov_b32 m0, s40
	v_mov_b32_e32 v131, 0
	global_load_lds_dwordx4 v132, s[10:11]
	v_mov_b32_e32 v135, v131
	v_mov_b32_e32 v129, v131
	v_mov_b32_e32 v133, v131
	s_cmp_eq_u32 s5, 1
	s_mov_b32 s41, 0
	v_lshl_add_u64 v[6:7], s[30:31], 0, v[130:131]
	v_lshl_add_u64 v[4:5], s[30:31], 0, v[134:135]
	v_lshl_add_u64 v[0:1], s[28:29], 0, v[128:129]
	s_cselect_b64 s[10:11], -1, 0
	s_cmp_lg_u32 s5, 1
	v_lshl_add_u64 v[2:3], s[28:29], 0, v[132:133]
	s_cbranch_scc1 .LBB0_1855
	s_setprio 1
	s_barrier

.LBB0_1868:
	s_setprio 0
	v_lshl_add_u32 v146, s24, 8, v148
	v_ashrrev_i32_e32 v147, 31, v146
	v_lshl_or_b32 v144, s26, 8, v150
	v_lshlrev_b64 v[156:157], 12, v[146:147]
	v_ashrrev_i32_e32 v145, 31, v144
	v_lshl_add_u64 v[156:157], s[60:61], 0, v[156:157]
	v_lshl_add_u64 v[164:165], v[144:145], 1, v[156:157]
	global_load_dwordx4 v[156:159], v[164:165], off
	global_load_dwordx4 v[160:163], v[164:165], off offset:256
	v_and_b32_e32 v166, 64, v154
	v_xor_b32_e32 v155, 16, v154
	v_add_u32_e32 v166, 64, v166
	v_xor_b32_e32 v167, 32, v154
	v_cmp_lt_i32_e32 vcc, v155, v166
	s_waitcnt vmcnt(0)
	v_lshlrev_b32_e32 v168, 16, v158
	v_cndmask_b32_e32 v155, v154, v155, vcc
	v_cmp_lt_i32_e32 vcc, v167, v166
	v_lshlrev_b32_e32 v166, 16, v156
	v_and_b32_e32 v169, 0xffff0000, v158
	v_cndmask_b32_e32 v174, v154, v167, vcc
	v_and_b32_e32 v167, 0xffff0000, v156
	v_lshlrev_b32_e32 v156, 16, v157
	v_and_b32_e32 v157, 0xffff0000, v157
	v_lshlrev_b32_e32 v158, 16, v159
	v_and_b32_e32 v159, 0xffff0000, v159
	v_lshlrev_b32_e32 v170, 16, v160
	v_and_b32_e32 v171, 0xffff0000, v160
	v_lshlrev_b32_e32 v160, 16, v161
	v_and_b32_e32 v161, 0xffff0000, v161
	v_lshlrev_b32_e32 v172, 16, v162
	v_and_b32_e32 v173, 0xffff0000, v162
	v_lshlrev_b32_e32 v162, 16, v163
	v_and_b32_e32 v163, 0xffff0000, v163
	v_pk_add_f32 v[126:127], v[126:127], v[156:157]
	v_pk_add_f32 v[124:125], v[124:125], v[166:167]
	v_pk_add_f32 v[122:123], v[122:123], v[158:159]
	v_pk_add_f32 v[120:121], v[120:121], v[168:169]
	v_pk_add_f32 v[118:119], v[118:119], v[160:161]
	v_pk_add_f32 v[116:117], v[116:117], v[170:171]
	v_pk_add_f32 v[156:157], v[114:115], v[162:163]
	v_pk_add_f32 v[158:159], v[112:113], v[172:173]
	v_cvt_pk_bf16_f32 v112, v124, v125
	v_cvt_pk_bf16_f32 v113, v126, v127
	v_mul_f32_e32 v114, v125, v125
	v_mul_f32_e32 v115, v127, v127
	v_mul_f32_e32 v125, v121, v121
	v_mul_f32_e32 v127, v123, v123
	v_mul_f32_e32 v160, v117, v117
	v_mul_f32_e32 v161, v119, v119
	v_mul_f32_e32 v162, v159, v159
	v_mul_f32_e32 v163, v157, v157
	v_fmac_f32_e32 v114, v124, v124
	v_fmac_f32_e32 v115, v126, v126
	v_fmac_f32_e32 v125, v120, v120
	v_fmac_f32_e32 v127, v122, v122
	v_fmac_f32_e32 v160, v116, v116
	v_fmac_f32_e32 v161, v118, v118
	v_fmac_f32_e32 v162, v158, v158
	v_fmac_f32_e32 v163, v156, v156
	v_add_f32_e32 v114, v114, v115
	v_add_f32_e32 v115, v125, v127
	v_add_f32_e32 v124, v160, v161
	v_add_f32_e32 v125, v162, v163
	v_add_f32_e32 v114, v114, v115
	v_add_f32_e32 v115, v124, v125
	v_lshlrev_b32_e32 v155, 2, v155
	v_add_f32_e32 v124, v114, v115
	ds_bpermute_b32 v125, v155, v124
	v_cvt_pk_bf16_f32 v114, v120, v121
	v_cvt_pk_bf16_f32 v115, v122, v123
	global_store_dwordx4 v[164:165], v[112:115], off
	v_cvt_pk_bf16_f32 v116, v116, v117
	v_cvt_pk_bf16_f32 v117, v118, v119
	s_waitcnt lgkmcnt(0)
	v_add_f32_e32 v112, v124, v125
	v_lshlrev_b32_e32 v114, 2, v174
	ds_bpermute_b32 v113, v114, v112
	v_cvt_pk_bf16_f32 v118, v158, v159
	v_cvt_pk_bf16_f32 v119, v156, v157
	global_store_dwordx4 v[164:165], v[116:119], off offset:256
	s_and_saveexec_b64 s[24:25], s[4:5]
	s_cbranch_execz .LBB0_1870
	s_waitcnt lgkmcnt(0)
	v_add_f32_e32 v112, v112, v113
	v_mul_f32_e32 v112, 0x4b800000, v112
	v_rndne_f32_e32 v112, v112
	v_mul_f32_e32 v113, 0x2f800000, v112
	v_floor_f32_e32 v113, v113
	v_fmac_f32_e32 v112, 0xcf800000, v113
	v_cvt_u32_f32_e32 v112, v112
	v_cvt_u32_f32_e32 v113, v113
	v_lshl_add_u64 v[116:117], v[146:147], 3, s[0:1]
	global_atomic_add_x2 v[116:117], v[112:113], off

.LBB0_1940:
	s_or_b64 exec, exec, s[4:5]
	v_readlane_b32 s4, v237, 34
	v_mov_b32_e32 v9, v236
	v_readlane_b32 s5, v237, 35
	s_waitcnt lgkmcnt(0)
	s_barrier
	s_and_b64 vcc, exec, s[4:5]
	v_readfirstlane_b32 s5, v9
	s_cbranch_vccnz .LBB0_1958
	v_lshlrev_b32_e32 v0, 4, v9
	v_add_u32_e32 v1, 0x2000, v0
	v_ashrrev_i32_e32 v2, 31, v1
	v_lshrrev_b32_e32 v2, 22, v2
	v_add_u32_e32 v2, v1, v2
	v_ashrrev_i32_e32 v8, 10, v2
	v_mul_i32_i24_e32 v2, 0x400, v8
	v_sub_u32_e32 v1, v1, v2
	v_lshrrev_b32_e32 v2, 4, v1
	v_bitop3_b32 v1, v2, v1, 32 bitop3:0x6c
	v_ashrrev_i32_e32 v2, 31, v1
	v_lshrrev_b32_e32 v2, 26, v2
	v_add_u32_e32 v2, v1, v2
	v_lshlrev_b32_e32 v3, 3, v8
	v_ashrrev_i32_e32 v10, 6, v2
	v_and_b32_e32 v3, -16, v3
	v_add_u32_e32 v3, v10, v3
	v_and_b32_e32 v4, 3, v10
	s_mov_b32 s4, 0xfffe0
	v_lshrrev_b32_e32 v5, 2, v3
	v_lshlrev_b32_e32 v6, 1, v3
	v_and_b32_e32 v2, 0xc0, v2
	v_and_or_b32 v4, v3, s4, v4
	v_and_b32_e32 v5, 4, v5
	v_and_b32_e32 v6, 24, v6
	v_sub_u32_e32 v1, v1, v2
	v_mov_b32_e32 v2, 1
	v_or3_b32 v4, v4, v5, v6
	v_lshlrev_b32_e32 v5, 5, v8
	v_ashrrev_i16_sdwa v1, v2, sext(v1) dst_sel:DWORD dst_unused:UNUSED_PAD src0_sel:DWORD src1_sel:BYTE_0
	v_and_b32_e32 v5, 32, v5
	v_bfe_i32 v11, v1, 0, 16
	v_add_lshl_u32 v1, v5, v11, 1
	v_lshl_add_u32 v128, v4, 12, v1
	v_lshl_add_u32 v130, v3, 12, v1
	v_bfe_i32 v1, v9, 27, 1
	v_lshrrev_b32_e32 v1, 22, v1
	v_add_u32_e32 v1, v0, v1
	v_and_b32_e32 v1, 0xfffffc00, v1
	v_sub_u32_e32 v0, v0, v1
	v_lshrrev_b32_e32 v1, 4, v0
	v_ashrrev_i32_e32 v3, 31, v9
	v_bitop3_b32 v0, v1, v0, 32 bitop3:0x6c
	v_lshrrev_b32_e32 v3, 26, v3
	v_ashrrev_i32_e32 v1, 31, v0
	v_add_u32_e32 v3, v9, v3
	v_lshrrev_b32_e32 v1, 26, v1
	v_ashrrev_i32_e32 v13, 6, v3
	v_add_u32_e32 v1, v0, v1
	v_lshlrev_b32_e32 v3, 3, v13
	s_add_u32 s2, s88, 0x8400000
	v_ashrrev_i32_e32 v12, 6, v1
	v_and_b32_e32 v3, -16, v3
	s_addc_u32 s13, s89, 0
	v_add_u32_e32 v3, v12, v3
	v_and_b32_e32 v4, 3, v12
	s_ashr_i32 s17, s52, 31
	v_and_or_b32 v4, v3, s4, v4
	s_lshr_b32 s4, s17, 29
	s_add_i32 s4, s52, s4
	s_ashr_i32 s8, s5, 6
	s_ashr_i32 s6, s4, 3
	s_and_b32 s4, s4, -8
	s_ashr_i32 s10, s5, 8
	s_lshl_b32 s15, s8, 10
	s_sub_i32 s4, s52, s4
	s_cmp_lt_i32 s4, 0
	s_movk_i32 s34, 0xb1
	s_cselect_b32 s7, s34, 0xb0
	s_mul_i32 s4, s4, s7
	s_add_i32 s4, s4, s6
	s_mul_hi_i32 s6, s4, 0x2e8ba2e9
	s_lshr_b32 s7, s6, 31
	s_ashr_i32 s6, s6, 6
	s_add_i32 s6, s6, s7
	s_lshl_b32 s7, s6, 3
	s_mulk_i32 s6, 0x160
	s_sub_i32 s6, s4, s6
	s_sext_i32_i16 s4, s6
	s_bfe_u32 s4, s4, 0x3001c
	s_add_i32 s9, s6, s4
	s_sext_i32_i16 s4, s9
	s_and_b32 s9, s9, 0xfff8
	s_sub_i32 s6, s6, s9
	s_sext_i32_i16 s6, s6
	v_lshrrev_b32_e32 v5, 2, v3
	v_lshlrev_b32_e32 v6, 1, v3
	v_and_b32_e32 v1, 0xc0, v1
	s_lshr_b32 s4, s4, 3
	s_add_i32 s26, s7, s6
	v_and_b32_e32 v5, 4, v5
	v_and_b32_e32 v6, 24, v6
	v_sub_u32_e32 v0, v0, v1
	s_ashr_i32 s27, s26, 31
	s_bfe_i64 s[18:19], s[4:5], 0x100000
	v_or3_b32 v4, v4, v5, v6
	v_lshlrev_b32_e32 v5, 5, v13
	v_ashrrev_i16_sdwa v0, v2, sext(v0) dst_sel:DWORD dst_unused:UNUSED_PAD src0_sel:DWORD src1_sel:BYTE_0
	s_lshl_b64 s[6:7], s[26:27], 20
	s_lshl_b64 s[18:19], s[18:19], 20
	v_and_b32_e32 v5, 32, v5
	v_bfe_i32 v14, v0, 0, 16
	s_add_u32 s28, s2, s18
	v_add_lshl_u32 v0, v5, v14, 1
	s_addc_u32 s29, s13, s19
	s_add_i32 s35, s15, 0
	v_lshl_add_u32 v132, v4, 12, v0
	s_add_i32 m0, s35, 0x10000
	v_lshl_add_u32 v134, v3, 12, v0
	global_load_lds_dwordx4 v132, s[28:29]
	s_add_i32 m0, s35, 0x12000
	s_add_u32 s18, s28, 0x80000
	global_load_lds_dwordx4 v128, s[28:29]
	s_addc_u32 s19, s29, 0
	s_add_i32 m0, s35, 0x14000
	v_mov_b32_e32 v133, 0
	global_load_lds_dwordx4 v132, s[18:19]
	s_add_i32 m0, s35, 0x16000
	s_add_u32 s30, s60, s6
	s_addc_u32 s31, s61, s7
	s_add_i32 s36, s35, 0x2000
	global_load_lds_dwordx4 v128, s[18:19]
	s_mov_b32 m0, s35
	s_add_u32 s6, s30, 0x80000
	global_load_lds_dwordx4 v134, s[30:31]
	s_mov_b32 m0, s36
	s_addc_u32 s7, s31, 0
	s_add_i32 s37, s35, 0x4000
	global_load_lds_dwordx4 v130, s[30:31]
	s_mov_b32 m0, s37
	s_add_i32 s38, s35, 0x6000
	global_load_lds_dwordx4 v134, s[6:7]
	s_mov_b32 m0, s38
	v_mov_b32_e32 v129, v133
	global_load_lds_dwordx4 v130, s[6:7]
	v_mov_b32_e32 v135, v133
	v_mov_b32_e32 v131, v133
	s_cmp_eq_u32 s10, 1
	s_mov_b32 s39, 0
	v_lshl_add_u64 v[6:7], s[28:29], 0, v[132:133]
	v_lshl_add_u64 v[4:5], s[28:29], 0, v[128:129]
	v_lshl_add_u64 v[0:1], s[30:31], 0, v[134:135]
	s_cselect_b64 s[6:7], -1, 0
	s_cmp_lg_u32 s10, 1
	v_lshl_add_u64 v[2:3], s[30:31], 0, v[130:131]
	s_cbranch_scc1 .LBB0_1943
	s_setprio 1
	s_barrier

.LBB0_1954:
	s_setprio 0
	v_mov_b64_e32 v[158:159], s[16:17]
	v_pk_fma_f32 v[164:165], v[148:149], s[14:15], v[158:159] op_sel_hi:[1,0,0]
	v_lshl_or_b32 v156, s46, 7, v162
	v_mul_f32_e32 v153, 0x4b800000, v165
	v_cmp_gt_f32_e32 vcc, s45, v165
	v_ashrrev_i32_e32 v157, 31, v156
	v_mov_b64_e32 v[154:155], s[62:63]
	v_cndmask_b32_e32 v153, v165, v153, vcc
	v_rsq_f32_e32 v153, v153
	v_mad_i64_i32 v[166:167], s[26:27], v152, s44, v[154:155]
	v_lshlrev_b64 v[156:157], 1, v[156:157]
	v_mul_f32_e32 v165, 0x45800000, v153
	v_cndmask_b32_e32 v168, v153, v165, vcc
	v_pk_mul_f32 v[124:125], v[168:169], v[124:125] op_sel_hi:[0,1]
	v_mul_f32_e32 v153, 0xbfb8aa3b, v124
	v_exp_f32_e32 v153, v153
	v_mul_f32_e32 v165, 0xbfb8aa3b, v125
	v_exp_f32_e32 v165, v165
	v_pk_mul_f32 v[126:127], v[168:169], v[126:127] op_sel_hi:[0,1]
	v_add_f32_e32 v153, 1.0, v153
	v_rcp_f32_e32 v170, v153
	v_add_f32_e32 v153, 1.0, v165
	v_mul_f32_e32 v165, 0xbfb8aa3b, v126
	v_pk_mul_f32 v[116:117], v[168:169], v[116:117] op_sel_hi:[0,1]
	v_exp_f32_e32 v165, v165
	v_mul_f32_e32 v169, 0xbfb8aa3b, v127
	v_exp_f32_e32 v169, v169
	v_rcp_f32_e32 v171, v153
	v_add_f32_e32 v153, 1.0, v165
	v_rcp_f32_e32 v172, v153
	v_add_f32_e32 v153, 1.0, v169
	v_rcp_f32_e32 v173, v153
	v_pk_mul_f32 v[124:125], v[124:125], v[170:171]
	v_pk_mul_f32 v[120:121], v[168:169], v[120:121] op_sel_hi:[0,1]
	v_pk_mul_f32 v[116:117], v[124:125], v[116:117]
	v_pk_mul_f32 v[124:125], v[126:127], v[172:173]
	v_mul_f32_e32 v126, 0xbfb8aa3b, v120
	v_exp_f32_e32 v126, v126
	v_pk_mul_f32 v[118:119], v[168:169], v[118:119] op_sel_hi:[0,1]
	v_pk_mul_f32 v[118:119], v[124:125], v[118:119]
	v_mul_f32_e32 v124, 0xbfb8aa3b, v121
	v_pk_mul_f32 v[122:123], v[168:169], v[122:123] op_sel_hi:[0,1]
	v_exp_f32_e32 v125, v124
	v_add_f32_e32 v124, 1.0, v126
	v_mul_f32_e32 v126, 0xbfb8aa3b, v122
	v_mul_f32_e32 v127, 0xbfb8aa3b, v123
	v_exp_f32_e32 v126, v126
	v_exp_f32_e32 v127, v127
	v_add_f32_e32 v125, 1.0, v125
	v_rcp_f32_e32 v124, v124
	v_rcp_f32_e32 v125, v125
	v_add_f32_e32 v126, 1.0, v126
	v_add_f32_e32 v127, 1.0, v127
	v_rcp_f32_e32 v126, v126
	v_rcp_f32_e32 v127, v127
	v_pk_mul_f32 v[112:113], v[168:169], v[112:113] op_sel_hi:[0,1]
	v_pk_mul_f32 v[120:121], v[120:121], v[124:125]
	v_cmp_gt_f32_e32 vcc, s45, v164
	v_pk_mul_f32 v[120:121], v[120:121], v[112:113]
	v_pk_mul_f32 v[112:113], v[168:169], v[114:115] op_sel_hi:[0,1]
	v_pk_mul_f32 v[114:115], v[122:123], v[126:127]
	v_lshl_add_u64 v[166:167], v[166:167], 0, v[156:157]
	v_pk_mul_f32 v[122:123], v[114:115], v[112:113]
	v_mul_f32_e32 v113, 0x4b800000, v164
	v_cndmask_b32_e32 v113, v164, v113, vcc
	v_cvt_pk_bf16_f32 v112, v116, v117
	v_rsq_f32_e32 v116, v113
	v_cvt_pk_bf16_f32 v113, v118, v119
	v_cvt_pk_bf16_f32 v114, v120, v121
	v_cvt_pk_bf16_f32 v115, v122, v123
	v_mul_f32_e32 v117, 0x45800000, v116
	v_cndmask_b32_e32 v116, v116, v117, vcc
	v_pk_mul_f32 v[108:109], v[116:117], v[108:109] op_sel_hi:[0,1]
	v_mul_f32_e32 v117, 0xbfb8aa3b, v108
	v_exp_f32_e32 v117, v117
	global_store_dwordx4 v[166:167], v[112:115], off
	v_pk_mul_f32 v[110:111], v[116:117], v[110:111] op_sel_hi:[0,1]
	s_nop 0
	v_mul_f32_e32 v112, 0xbfb8aa3b, v109
	v_exp_f32_e32 v113, v112
	v_mul_f32_e32 v114, 0xbfb8aa3b, v110
	v_mul_f32_e32 v115, 0xbfb8aa3b, v111
	v_exp_f32_e32 v114, v114
	v_exp_f32_e32 v115, v115
	v_add_f32_e32 v112, 1.0, v117
	v_add_f32_e32 v113, 1.0, v113
	v_rcp_f32_e32 v112, v112
	v_rcp_f32_e32 v113, v113
	v_add_f32_e32 v114, 1.0, v114
	v_add_f32_e32 v115, 1.0, v115
	v_rcp_f32_e32 v114, v114
	v_rcp_f32_e32 v115, v115
	v_pk_mul_f32 v[100:101], v[116:117], v[100:101] op_sel_hi:[0,1]
	v_pk_mul_f32 v[108:109], v[108:109], v[112:113]
	v_pk_mul_f32 v[104:105], v[116:117], v[104:105] op_sel_hi:[0,1]
	v_pk_mul_f32 v[100:101], v[108:109], v[100:101]
	v_pk_mul_f32 v[108:109], v[110:111], v[114:115]
	v_mul_f32_e32 v110, 0xbfb8aa3b, v104
	v_exp_f32_e32 v110, v110
	v_pk_mul_f32 v[102:103], v[116:117], v[102:103] op_sel_hi:[0,1]
	v_pk_mul_f32 v[102:103], v[108:109], v[102:103]
	v_mul_f32_e32 v108, 0xbfb8aa3b, v105
	v_pk_mul_f32 v[106:107], v[116:117], v[106:107] op_sel_hi:[0,1]
	v_exp_f32_e32 v109, v108
	v_add_f32_e32 v108, 1.0, v110
	v_mul_f32_e32 v110, 0xbfb8aa3b, v106
	v_mul_f32_e32 v111, 0xbfb8aa3b, v107
	v_exp_f32_e32 v110, v110
	v_exp_f32_e32 v111, v111
	v_add_f32_e32 v109, 1.0, v109
	v_rcp_f32_e32 v108, v108
	v_rcp_f32_e32 v109, v109
	v_add_f32_e32 v110, 1.0, v110
	v_add_f32_e32 v111, 1.0, v111
	v_rcp_f32_e32 v110, v110
	v_rcp_f32_e32 v111, v111
	v_pk_mul_f32 v[96:97], v[116:117], v[96:97] op_sel_hi:[0,1]
	v_pk_mul_f32 v[104:105], v[104:105], v[108:109]
	s_nop 0
	v_pk_mul_f32 v[104:105], v[104:105], v[96:97]
	v_pk_mul_f32 v[96:97], v[116:117], v[98:99] op_sel_hi:[0,1]
	v_pk_mul_f32 v[98:99], v[106:107], v[110:111]
	s_nop 0
	v_pk_mul_f32 v[106:107], v[98:99], v[96:97]
	v_cvt_pk_bf16_f32 v96, v100, v101
	v_or_b32_e32 v100, 16, v152
	v_mad_i64_i32 v[100:101], s[26:27], v100, s44, v[154:155]
	v_cvt_pk_bf16_f32 v97, v102, v103
	v_cvt_pk_bf16_f32 v98, v104, v105
	v_cvt_pk_bf16_f32 v99, v106, v107
	v_lshl_add_u64 v[100:101], v[100:101], 0, v[156:157]
	global_store_dwordx4 v[100:101], v[96:99], off
	s_nop 1
	v_pk_fma_f32 v[96:97], v[146:147], s[14:15], v[158:159] op_sel_hi:[1,0,0]
	s_nop 0
	v_mul_f32_e32 v98, 0x4b800000, v97
	v_cmp_gt_f32_e32 vcc, s45, v97
	s_nop 1
	v_cndmask_b32_e32 v97, v97, v98, vcc
	v_rsq_f32_e32 v97, v97
	v_or_b32_e32 v98, 32, v152
	v_mad_i64_i32 v[98:99], s[26:27], v98, s44, v[154:155]
	v_mul_f32_e32 v100, 0x45800000, v97
	v_cndmask_b32_e32 v100, v97, v100, vcc
	v_pk_mul_f32 v[92:93], v[100:101], v[92:93] op_sel_hi:[0,1]
	v_mul_f32_e32 v97, 0xbfb8aa3b, v92
	v_mul_f32_e32 v101, 0xbfb8aa3b, v93
	v_exp_f32_e32 v97, v97
	v_exp_f32_e32 v101, v101
	v_cmp_gt_f32_e32 vcc, s45, v96
	v_lshl_add_u64 v[98:99], v[98:99], 0, v[156:157]
	v_add_f32_e32 v97, 1.0, v97
	v_pk_mul_f32 v[94:95], v[100:101], v[94:95] op_sel_hi:[0,1]
	v_rcp_f32_e32 v102, v97
	v_pk_mul_f32 v[84:85], v[100:101], v[84:85] op_sel_hi:[0,1]
	v_add_f32_e32 v97, 1.0, v101
	v_mul_f32_e32 v101, 0xbfb8aa3b, v94
	v_exp_f32_e32 v101, v101
	v_mul_f32_e32 v103, 0xbfb8aa3b, v95
	v_exp_f32_e32 v105, v103
	v_rcp_f32_e32 v103, v97
	v_add_f32_e32 v97, 1.0, v101
	v_rcp_f32_e32 v104, v97
	v_add_f32_e32 v97, 1.0, v105
	v_rcp_f32_e32 v105, v97
	v_pk_mul_f32 v[92:93], v[92:93], v[102:103]
	v_pk_mul_f32 v[88:89], v[100:101], v[88:89] op_sel_hi:[0,1]
	v_pk_mul_f32 v[84:85], v[92:93], v[84:85]
	v_pk_mul_f32 v[92:93], v[94:95], v[104:105]
	v_mul_f32_e32 v94, 0xbfb8aa3b, v88
	v_exp_f32_e32 v94, v94
	v_pk_mul_f32 v[86:87], v[100:101], v[86:87] op_sel_hi:[0,1]
	v_pk_mul_f32 v[86:87], v[92:93], v[86:87]
	v_mul_f32_e32 v92, 0xbfb8aa3b, v89
	v_pk_mul_f32 v[90:91], v[100:101], v[90:91] op_sel_hi:[0,1]
	v_exp_f32_e32 v93, v92
	v_add_f32_e32 v92, 1.0, v94
	v_mul_f32_e32 v94, 0xbfb8aa3b, v90
	v_mul_f32_e32 v95, 0xbfb8aa3b, v91
	v_exp_f32_e32 v94, v94
	v_exp_f32_e32 v95, v95
	v_add_f32_e32 v93, 1.0, v93
	v_rcp_f32_e32 v92, v92
	v_rcp_f32_e32 v93, v93
	v_add_f32_e32 v94, 1.0, v94
	v_add_f32_e32 v95, 1.0, v95
	v_rcp_f32_e32 v94, v94
	v_rcp_f32_e32 v95, v95
	v_pk_mul_f32 v[80:81], v[100:101], v[80:81] op_sel_hi:[0,1]
	v_pk_mul_f32 v[88:89], v[88:89], v[92:93]
	s_nop 0
	v_pk_mul_f32 v[88:89], v[88:89], v[80:81]
	v_pk_mul_f32 v[80:81], v[100:101], v[82:83] op_sel_hi:[0,1]
	v_pk_mul_f32 v[82:83], v[90:91], v[94:95]
	s_nop 0
	v_pk_mul_f32 v[90:91], v[82:83], v[80:81]
	v_mul_f32_e32 v81, 0x4b800000, v96
	v_cndmask_b32_e32 v81, v96, v81, vcc
	v_cvt_pk_bf16_f32 v80, v84, v85
	v_rsq_f32_e32 v84, v81
	v_cvt_pk_bf16_f32 v81, v86, v87
	v_cvt_pk_bf16_f32 v82, v88, v89
	v_cvt_pk_bf16_f32 v83, v90, v91
	v_mul_f32_e32 v85, 0x45800000, v84
	v_cndmask_b32_e32 v84, v84, v85, vcc
	v_pk_mul_f32 v[76:77], v[84:85], v[76:77] op_sel_hi:[0,1]
	v_mul_f32_e32 v85, 0xbfb8aa3b, v76
	v_exp_f32_e32 v85, v85
	global_store_dwordx4 v[98:99], v[80:83], off
	v_pk_mul_f32 v[78:79], v[84:85], v[78:79] op_sel_hi:[0,1]
	s_nop 0
	v_mul_f32_e32 v80, 0xbfb8aa3b, v77
	v_exp_f32_e32 v81, v80
	v_mul_f32_e32 v82, 0xbfb8aa3b, v78
	v_mul_f32_e32 v83, 0xbfb8aa3b, v79
	v_exp_f32_e32 v82, v82
	v_exp_f32_e32 v83, v83
	v_add_f32_e32 v80, 1.0, v85
	v_add_f32_e32 v81, 1.0, v81
	v_rcp_f32_e32 v80, v80
	v_rcp_f32_e32 v81, v81
	v_add_f32_e32 v82, 1.0, v82
	v_add_f32_e32 v83, 1.0, v83
	v_rcp_f32_e32 v82, v82
	v_rcp_f32_e32 v83, v83
	v_pk_mul_f32 v[68:69], v[84:85], v[68:69] op_sel_hi:[0,1]
	v_pk_mul_f32 v[76:77], v[76:77], v[80:81]
	v_pk_mul_f32 v[72:73], v[84:85], v[72:73] op_sel_hi:[0,1]
	v_pk_mul_f32 v[68:69], v[76:77], v[68:69]
	v_pk_mul_f32 v[76:77], v[78:79], v[82:83]
	v_mul_f32_e32 v78, 0xbfb8aa3b, v72
	v_exp_f32_e32 v78, v78
	v_pk_mul_f32 v[70:71], v[84:85], v[70:71] op_sel_hi:[0,1]
	v_pk_mul_f32 v[70:71], v[76:77], v[70:71]
	v_mul_f32_e32 v76, 0xbfb8aa3b, v73
	v_pk_mul_f32 v[74:75], v[84:85], v[74:75] op_sel_hi:[0,1]
	v_exp_f32_e32 v77, v76
	v_add_f32_e32 v76, 1.0, v78
	v_mul_f32_e32 v78, 0xbfb8aa3b, v74
	v_mul_f32_e32 v79, 0xbfb8aa3b, v75
	v_exp_f32_e32 v78, v78
	v_exp_f32_e32 v79, v79
	v_add_f32_e32 v77, 1.0, v77
	v_rcp_f32_e32 v76, v76
	v_rcp_f32_e32 v77, v77
	v_add_f32_e32 v78, 1.0, v78
	v_add_f32_e32 v79, 1.0, v79
	v_rcp_f32_e32 v78, v78
	v_rcp_f32_e32 v79, v79
	v_pk_mul_f32 v[64:65], v[84:85], v[64:65] op_sel_hi:[0,1]
	v_pk_mul_f32 v[72:73], v[72:73], v[76:77]
	s_nop 0
	v_pk_mul_f32 v[72:73], v[72:73], v[64:65]
	v_pk_mul_f32 v[64:65], v[84:85], v[66:67] op_sel_hi:[0,1]
	v_pk_mul_f32 v[66:67], v[74:75], v[78:79]
	s_nop 0
	v_pk_mul_f32 v[74:75], v[66:67], v[64:65]
	v_cvt_pk_bf16_f32 v64, v68, v69
	v_or_b32_e32 v68, 48, v152
	v_mad_i64_i32 v[68:69], s[26:27], v68, s44, v[154:155]
	v_cvt_pk_bf16_f32 v65, v70, v71
	v_cvt_pk_bf16_f32 v66, v72, v73
	v_cvt_pk_bf16_f32 v67, v74, v75
	v_lshl_add_u64 v[68:69], v[68:69], 0, v[156:157]
	global_store_dwordx4 v[68:69], v[64:67], off
	s_nop 1
	v_pk_fma_f32 v[64:65], v[144:145], s[14:15], v[158:159] op_sel_hi:[1,0,0]
	s_nop 0
	v_mul_f32_e32 v66, 0x4b800000, v65
	v_cmp_gt_f32_e32 vcc, s45, v65
	s_nop 1
	v_cndmask_b32_e32 v65, v65, v66, vcc
	v_rsq_f32_e32 v65, v65
	v_add_u32_e32 v66, 0x80, v152
	v_mad_i64_i32 v[66:67], s[26:27], v66, s44, v[154:155]
	v_mul_f32_e32 v68, 0x45800000, v65
	v_cndmask_b32_e32 v68, v65, v68, vcc
	v_pk_mul_f32 v[60:61], v[68:69], v[60:61] op_sel_hi:[0,1]
	v_mul_f32_e32 v65, 0xbfb8aa3b, v60
	v_mul_f32_e32 v69, 0xbfb8aa3b, v61
	v_exp_f32_e32 v65, v65
	v_exp_f32_e32 v69, v69
	v_cmp_gt_f32_e32 vcc, s45, v64
	v_lshl_add_u64 v[66:67], v[66:67], 0, v[156:157]
	v_add_f32_e32 v65, 1.0, v65
	v_pk_mul_f32 v[62:63], v[68:69], v[62:63] op_sel_hi:[0,1]
	v_rcp_f32_e32 v70, v65
	v_pk_mul_f32 v[52:53], v[68:69], v[52:53] op_sel_hi:[0,1]
	v_add_f32_e32 v65, 1.0, v69
	v_mul_f32_e32 v69, 0xbfb8aa3b, v62
	v_exp_f32_e32 v69, v69
	v_mul_f32_e32 v71, 0xbfb8aa3b, v63
	v_exp_f32_e32 v73, v71
	v_rcp_f32_e32 v71, v65
	v_add_f32_e32 v65, 1.0, v69
	v_rcp_f32_e32 v72, v65
	v_add_f32_e32 v65, 1.0, v73
	v_rcp_f32_e32 v73, v65
	v_pk_mul_f32 v[60:61], v[60:61], v[70:71]
	v_pk_mul_f32 v[56:57], v[68:69], v[56:57] op_sel_hi:[0,1]
	v_pk_mul_f32 v[52:53], v[60:61], v[52:53]
	v_pk_mul_f32 v[60:61], v[62:63], v[72:73]
	v_mul_f32_e32 v62, 0xbfb8aa3b, v56
	v_exp_f32_e32 v62, v62
	v_pk_mul_f32 v[54:55], v[68:69], v[54:55] op_sel_hi:[0,1]
	v_pk_mul_f32 v[54:55], v[60:61], v[54:55]
	v_mul_f32_e32 v60, 0xbfb8aa3b, v57
	v_pk_mul_f32 v[58:59], v[68:69], v[58:59] op_sel_hi:[0,1]
	v_exp_f32_e32 v61, v60
	v_add_f32_e32 v60, 1.0, v62
	v_mul_f32_e32 v62, 0xbfb8aa3b, v58
	v_mul_f32_e32 v63, 0xbfb8aa3b, v59
	v_exp_f32_e32 v62, v62
	v_exp_f32_e32 v63, v63
	v_add_f32_e32 v61, 1.0, v61
	v_rcp_f32_e32 v60, v60
	v_rcp_f32_e32 v61, v61
	v_add_f32_e32 v62, 1.0, v62
	v_add_f32_e32 v63, 1.0, v63
	v_rcp_f32_e32 v62, v62
	v_rcp_f32_e32 v63, v63
	v_pk_mul_f32 v[48:49], v[68:69], v[48:49] op_sel_hi:[0,1]
	v_pk_mul_f32 v[56:57], v[56:57], v[60:61]
	s_nop 0
	v_pk_mul_f32 v[56:57], v[56:57], v[48:49]
	v_pk_mul_f32 v[48:49], v[68:69], v[50:51] op_sel_hi:[0,1]
	v_pk_mul_f32 v[50:51], v[58:59], v[62:63]
	s_nop 0
	v_pk_mul_f32 v[58:59], v[50:51], v[48:49]
	v_mul_f32_e32 v49, 0x4b800000, v64
	v_cndmask_b32_e32 v49, v64, v49, vcc
	v_cvt_pk_bf16_f32 v48, v52, v53
	v_rsq_f32_e32 v52, v49
	v_cvt_pk_bf16_f32 v49, v54, v55
	v_cvt_pk_bf16_f32 v50, v56, v57
	v_cvt_pk_bf16_f32 v51, v58, v59
	v_mul_f32_e32 v53, 0x45800000, v52
	v_cndmask_b32_e32 v52, v52, v53, vcc
	v_pk_mul_f32 v[44:45], v[52:53], v[44:45] op_sel_hi:[0,1]
	v_mul_f32_e32 v53, 0xbfb8aa3b, v44
	v_exp_f32_e32 v53, v53
	global_store_dwordx4 v[66:67], v[48:51], off
	v_pk_mul_f32 v[46:47], v[52:53], v[46:47] op_sel_hi:[0,1]
	s_nop 0
	v_mul_f32_e32 v48, 0xbfb8aa3b, v45
	v_exp_f32_e32 v49, v48
	v_mul_f32_e32 v50, 0xbfb8aa3b, v46
	v_mul_f32_e32 v51, 0xbfb8aa3b, v47
	v_exp_f32_e32 v50, v50
	v_exp_f32_e32 v51, v51
	v_add_f32_e32 v48, 1.0, v53
	v_add_f32_e32 v49, 1.0, v49
	v_rcp_f32_e32 v48, v48
	v_rcp_f32_e32 v49, v49
	v_add_f32_e32 v50, 1.0, v50
	v_add_f32_e32 v51, 1.0, v51
	v_rcp_f32_e32 v50, v50
	v_rcp_f32_e32 v51, v51
	v_pk_mul_f32 v[36:37], v[52:53], v[36:37] op_sel_hi:[0,1]
	v_pk_mul_f32 v[44:45], v[44:45], v[48:49]
	v_pk_mul_f32 v[40:41], v[52:53], v[40:41] op_sel_hi:[0,1]
	v_pk_mul_f32 v[36:37], v[44:45], v[36:37]
	v_pk_mul_f32 v[44:45], v[46:47], v[50:51]
	v_mul_f32_e32 v46, 0xbfb8aa3b, v40
	v_exp_f32_e32 v46, v46
	v_pk_mul_f32 v[38:39], v[52:53], v[38:39] op_sel_hi:[0,1]
	v_pk_mul_f32 v[38:39], v[44:45], v[38:39]
	v_mul_f32_e32 v44, 0xbfb8aa3b, v41
	v_pk_mul_f32 v[42:43], v[52:53], v[42:43] op_sel_hi:[0,1]
	v_exp_f32_e32 v45, v44
	v_add_f32_e32 v44, 1.0, v46
	v_mul_f32_e32 v46, 0xbfb8aa3b, v42
	v_mul_f32_e32 v47, 0xbfb8aa3b, v43
	v_exp_f32_e32 v46, v46
	v_exp_f32_e32 v47, v47
	v_add_f32_e32 v45, 1.0, v45
	v_rcp_f32_e32 v44, v44
	v_rcp_f32_e32 v45, v45
	v_add_f32_e32 v46, 1.0, v46
	v_add_f32_e32 v47, 1.0, v47
	v_rcp_f32_e32 v46, v46
	v_rcp_f32_e32 v47, v47
	v_pk_mul_f32 v[32:33], v[52:53], v[32:33] op_sel_hi:[0,1]
	v_pk_mul_f32 v[40:41], v[40:41], v[44:45]
	s_nop 0
	v_pk_mul_f32 v[40:41], v[40:41], v[32:33]
	v_pk_mul_f32 v[32:33], v[52:53], v[34:35] op_sel_hi:[0,1]
	v_pk_mul_f32 v[34:35], v[42:43], v[46:47]
	s_nop 0
	v_pk_mul_f32 v[42:43], v[34:35], v[32:33]
	v_cvt_pk_bf16_f32 v32, v36, v37
	v_add_u32_e32 v36, 0x90, v152
	v_mad_i64_i32 v[36:37], s[26:27], v36, s44, v[154:155]
	v_cvt_pk_bf16_f32 v33, v38, v39
	v_cvt_pk_bf16_f32 v34, v40, v41
	v_cvt_pk_bf16_f32 v35, v42, v43
	v_lshl_add_u64 v[36:37], v[36:37], 0, v[156:157]
	global_store_dwordx4 v[36:37], v[32:35], off
	s_nop 1
	v_pk_fma_f32 v[32:33], v[150:151], s[14:15], v[158:159] op_sel_hi:[1,0,0]
	s_nop 0
	v_mul_f32_e32 v34, 0x4b800000, v33
	v_cmp_gt_f32_e32 vcc, s45, v33
	s_nop 1
	v_cndmask_b32_e32 v33, v33, v34, vcc
	v_rsq_f32_e32 v33, v33
	v_add_u32_e32 v34, 0xa0, v152
	v_mad_i64_i32 v[34:35], s[26:27], v34, s44, v[154:155]
	v_mul_f32_e32 v36, 0x45800000, v33
	v_cndmask_b32_e32 v36, v33, v36, vcc
	v_pk_mul_f32 v[28:29], v[36:37], v[28:29] op_sel_hi:[0,1]
	v_mul_f32_e32 v33, 0xbfb8aa3b, v28
	v_mul_f32_e32 v37, 0xbfb8aa3b, v29
	v_exp_f32_e32 v33, v33
	v_exp_f32_e32 v37, v37
	v_cmp_gt_f32_e32 vcc, s45, v32
	v_lshl_add_u64 v[34:35], v[34:35], 0, v[156:157]
	v_add_f32_e32 v33, 1.0, v33
	v_pk_mul_f32 v[30:31], v[36:37], v[30:31] op_sel_hi:[0,1]
	v_rcp_f32_e32 v38, v33
	v_pk_mul_f32 v[20:21], v[36:37], v[20:21] op_sel_hi:[0,1]
	v_add_f32_e32 v33, 1.0, v37
	v_mul_f32_e32 v37, 0xbfb8aa3b, v30
	v_exp_f32_e32 v37, v37
	v_mul_f32_e32 v39, 0xbfb8aa3b, v31
	v_exp_f32_e32 v41, v39
	v_rcp_f32_e32 v39, v33
	v_add_f32_e32 v33, 1.0, v37
	v_rcp_f32_e32 v40, v33
	v_add_f32_e32 v33, 1.0, v41
	v_rcp_f32_e32 v41, v33
	v_pk_mul_f32 v[28:29], v[28:29], v[38:39]
	v_pk_mul_f32 v[24:25], v[36:37], v[24:25] op_sel_hi:[0,1]
	v_pk_mul_f32 v[20:21], v[28:29], v[20:21]
	v_pk_mul_f32 v[28:29], v[30:31], v[40:41]
	v_mul_f32_e32 v30, 0xbfb8aa3b, v24
	v_exp_f32_e32 v30, v30
	v_pk_mul_f32 v[22:23], v[36:37], v[22:23] op_sel_hi:[0,1]
	v_pk_mul_f32 v[22:23], v[28:29], v[22:23]
	v_mul_f32_e32 v28, 0xbfb8aa3b, v25
	v_pk_mul_f32 v[26:27], v[36:37], v[26:27] op_sel_hi:[0,1]
	v_exp_f32_e32 v29, v28
	v_add_f32_e32 v28, 1.0, v30
	v_mul_f32_e32 v30, 0xbfb8aa3b, v26
	v_mul_f32_e32 v31, 0xbfb8aa3b, v27
	v_exp_f32_e32 v30, v30
	v_exp_f32_e32 v31, v31
	v_add_f32_e32 v29, 1.0, v29
	v_rcp_f32_e32 v28, v28
	v_rcp_f32_e32 v29, v29
	v_add_f32_e32 v30, 1.0, v30
	v_add_f32_e32 v31, 1.0, v31
	v_rcp_f32_e32 v30, v30
	v_rcp_f32_e32 v31, v31
	v_pk_mul_f32 v[16:17], v[36:37], v[16:17] op_sel_hi:[0,1]
	v_pk_mul_f32 v[24:25], v[24:25], v[28:29]
	s_nop 0
	v_pk_mul_f32 v[24:25], v[24:25], v[16:17]
	v_pk_mul_f32 v[16:17], v[36:37], v[18:19] op_sel_hi:[0,1]
	v_pk_mul_f32 v[18:19], v[26:27], v[30:31]
	s_nop 0
	v_pk_mul_f32 v[26:27], v[18:19], v[16:17]
	v_mul_f32_e32 v17, 0x4b800000, v32
	v_cndmask_b32_e32 v17, v32, v17, vcc
	v_cvt_pk_bf16_f32 v16, v20, v21
	v_rsq_f32_e32 v20, v17
	v_cvt_pk_bf16_f32 v17, v22, v23
	v_cvt_pk_bf16_f32 v18, v24, v25
	v_cvt_pk_bf16_f32 v19, v26, v27
	v_mul_f32_e32 v21, 0x45800000, v20
	v_cndmask_b32_e32 v20, v20, v21, vcc
	v_pk_mul_f32 v[12:13], v[20:21], v[12:13] op_sel_hi:[0,1]
	v_mul_f32_e32 v21, 0xbfb8aa3b, v12
	v_exp_f32_e32 v21, v21
	global_store_dwordx4 v[34:35], v[16:19], off
	s_andn2_b64 vcc, exec, s[4:5]
	s_mov_b64 s[4:5], -1
	v_mul_f32_e32 v16, 0xbfb8aa3b, v13
	v_pk_mul_f32 v[14:15], v[20:21], v[14:15] op_sel_hi:[0,1]
	v_exp_f32_e32 v17, v16
	v_mul_f32_e32 v18, 0xbfb8aa3b, v14
	v_mul_f32_e32 v19, 0xbfb8aa3b, v15
	v_exp_f32_e32 v18, v18
	v_exp_f32_e32 v19, v19
	v_add_f32_e32 v16, 1.0, v21
	v_add_f32_e32 v17, 1.0, v17
	v_rcp_f32_e32 v16, v16
	v_rcp_f32_e32 v17, v17
	v_add_f32_e32 v18, 1.0, v18
	v_add_f32_e32 v19, 1.0, v19
	v_rcp_f32_e32 v18, v18
	v_rcp_f32_e32 v19, v19
	v_pk_mul_f32 v[4:5], v[20:21], v[4:5] op_sel_hi:[0,1]
	v_pk_mul_f32 v[12:13], v[12:13], v[16:17]
	v_pk_mul_f32 v[8:9], v[20:21], v[8:9] op_sel_hi:[0,1]
	v_pk_mul_f32 v[4:5], v[12:13], v[4:5]
	v_pk_mul_f32 v[12:13], v[14:15], v[18:19]
	v_mul_f32_e32 v14, 0xbfb8aa3b, v8
	v_exp_f32_e32 v14, v14
	v_pk_mul_f32 v[6:7], v[20:21], v[6:7] op_sel_hi:[0,1]
	v_pk_mul_f32 v[6:7], v[12:13], v[6:7]
	v_mul_f32_e32 v12, 0xbfb8aa3b, v9
	v_pk_mul_f32 v[10:11], v[20:21], v[10:11] op_sel_hi:[0,1]
	v_exp_f32_e32 v13, v12
	v_add_f32_e32 v12, 1.0, v14
	v_mul_f32_e32 v14, 0xbfb8aa3b, v10
	v_mul_f32_e32 v15, 0xbfb8aa3b, v11
	v_exp_f32_e32 v14, v14
	v_exp_f32_e32 v15, v15
	v_add_f32_e32 v13, 1.0, v13
	v_rcp_f32_e32 v12, v12
	v_rcp_f32_e32 v13, v13
	v_add_f32_e32 v14, 1.0, v14
	v_add_f32_e32 v15, 1.0, v15
	v_rcp_f32_e32 v14, v14
	v_rcp_f32_e32 v15, v15
	v_pk_mul_f32 v[0:1], v[20:21], v[0:1] op_sel_hi:[0,1]
	v_pk_mul_f32 v[8:9], v[8:9], v[12:13]
	s_nop 0
	v_pk_mul_f32 v[8:9], v[8:9], v[0:1]
	v_pk_mul_f32 v[0:1], v[20:21], v[2:3] op_sel_hi:[0,1]
	v_pk_mul_f32 v[2:3], v[10:11], v[14:15]
	s_nop 0
	v_pk_mul_f32 v[10:11], v[2:3], v[0:1]
	v_cvt_pk_bf16_f32 v0, v4, v5
	v_add_u32_e32 v4, 0xb0, v152
	v_mad_i64_i32 v[4:5], s[26:27], v4, s44, v[154:155]
	v_cvt_pk_bf16_f32 v1, v6, v7
	v_cvt_pk_bf16_f32 v2, v8, v9
	v_cvt_pk_bf16_f32 v3, v10, v11
	v_lshl_add_u64 v[4:5], v[4:5], 0, v[156:157]
	global_store_dwordx4 v[4:5], v[0:3], off
	s_cbranch_vccnz .LBB0_1945
	s_andn2_b64 vcc, exec, s[6:7]
	s_cbranch_vccnz .LBB0_1944
	s_barrier
	s_branch .LBB0_1944

.LBB0_2028:
	v_ashrrev_i32_e32 v1, 31, v236
	v_lshrrev_b32_e32 v1, 26, v1
	v_add_u32_e32 v1, v236, v1
	v_ashrrev_i32_e32 v8, 6, v1
	v_bfe_i32 v1, v236, 27, 1
	v_lshlrev_b32_e32 v0, 4, v236
	v_lshrrev_b32_e32 v1, 22, v1
	v_add_u32_e32 v1, v0, v1
	v_and_b32_e32 v1, 0xfffffc00, v1
	v_sub_u32_e32 v1, v0, v1
	v_lshrrev_b32_e32 v2, 4, v1
	v_bitop3_b32 v1, v2, v1, 32 bitop3:0x6c
	v_ashrrev_i32_e32 v3, 31, v1
	v_lshrrev_b32_e32 v3, 26, v3
	v_lshlrev_b32_e32 v2, 3, v8
	v_add_u32_e32 v3, v1, v3
	v_and_b32_e32 v2, -16, v2
	v_ashrrev_i32_e32 v9, 6, v3
	v_and_b32_e32 v3, 0xc0, v3
	v_add_u32_e32 v2, v9, v2
	v_lshlrev_b32_e32 v4, 5, v8
	v_sub_u32_e32 v1, v1, v3
	v_mov_b32_e32 v3, 1
	v_and_b32_e32 v10, 32, v4
	v_ashrrev_i16_sdwa v1, v3, sext(v1) dst_sel:DWORD dst_unused:UNUSED_PAD src0_sel:DWORD src1_sel:BYTE_0
	v_lshlrev_b32_e32 v4, 1, v2
	v_lshrrev_b32_e32 v5, 2, v2
	v_and_b32_e32 v6, 3, v9
	s_mov_b32 s1, 0x7fffe0
	v_bfe_i32 v11, v1, 0, 16
	v_and_b32_e32 v4, 24, v4
	v_and_b32_e32 v5, 4, v5
	v_and_or_b32 v6, v2, s1, v6
	s_movk_i32 s5, 0x1600
	v_add_u32_e32 v1, v10, v11
	v_or3_b32 v4, v6, v5, v4
	v_mul_lo_u32 v2, v2, s5
	v_add_lshl_u32 v128, v1, v2, 1
	v_mul_u32_u24_e32 v2, 0x1600, v4
	v_add_u32_e32 v0, 0x2000, v0
	v_add_lshl_u32 v130, v2, v1, 1
	v_ashrrev_i32_e32 v1, 31, v0
	v_lshrrev_b32_e32 v1, 22, v1
	v_add_u32_e32 v1, v0, v1
	v_ashrrev_i32_e32 v12, 10, v1
	v_mul_i32_i24_e32 v1, 0x400, v12
	v_sub_u32_e32 v0, v0, v1
	v_lshrrev_b32_e32 v1, 4, v0
	v_bitop3_b32 v0, v1, v0, 32 bitop3:0x6c
	v_ashrrev_i32_e32 v2, 31, v0
	v_lshrrev_b32_e32 v2, 26, v2
	v_lshlrev_b32_e32 v1, 3, v12
	v_add_u32_e32 v2, v0, v2
	v_and_b32_e32 v1, -16, v1
	v_ashrrev_i32_e32 v13, 6, v2
	v_lshlrev_b32_e32 v4, 5, v12
	s_add_u32 s2, s88, 0xf200000
	v_add_u32_e32 v1, v13, v1
	v_and_b32_e32 v14, 32, v4
	v_and_b32_e32 v4, 3, v13
	s_addc_u32 s38, s89, 0
	v_and_b32_e32 v2, 0xc0, v2
	v_and_or_b32 v4, v1, s1, v4
	s_ashr_i32 s1, s4, 6
	s_ashr_i32 s0, s4, 8
	v_sub_u32_e32 v0, v0, v2
	s_lshl_b32 s39, s1, 10
	s_mul_i32 s7, s53, 0x2c0000
	v_ashrrev_i16_sdwa v0, v3, sext(v0) dst_sel:DWORD dst_unused:UNUSED_PAD src0_sel:DWORD src1_sel:BYTE_0
	v_lshlrev_b32_e32 v2, 1, v1
	v_lshrrev_b32_e32 v3, 2, v1
	s_mul_hi_i32 s6, s53, 0x2c0000
	s_add_u32 s34, s2, s7
	v_bfe_i32 v15, v0, 0, 16
	v_and_b32_e32 v2, 24, v2
	v_and_b32_e32 v3, 4, v3
	s_addc_u32 s35, s38, s6
	s_add_i32 s40, s39, 0
	v_add_u32_e32 v0, v14, v15
	v_or3_b32 v2, v4, v3, v2
	v_mul_lo_u32 v1, v1, s5
	s_add_i32 m0, s40, 0x10000
	v_add_lshl_u32 v132, v0, v1, 1
	v_mul_u32_u24_e32 v1, 0x1600, v2
	global_load_lds_dwordx4 v130, s[34:35]
	s_add_i32 m0, s40, 0x12000
	v_add_lshl_u32 v134, v1, v0, 1
	s_add_u32 s6, s34, 0x160000
	global_load_lds_dwordx4 v134, s[34:35]
	s_addc_u32 s7, s35, 0
	s_add_i32 m0, s40, 0x14000
	s_mul_i32 s9, s51, 0x2c0000
	global_load_lds_dwordx4 v130, s[6:7]
	s_add_i32 m0, s40, 0x16000
	s_mul_hi_i32 s8, s51, 0x2c0000
	global_load_lds_dwordx4 v134, s[6:7]
	s_add_u32 s6, s62, s9
	s_addc_u32 s7, s63, s8
	s_add_i32 s41, s40, 0x2000
	s_mov_b32 m0, s40
	s_add_u32 s8, s6, 0x160000
	global_load_lds_dwordx4 v128, s[6:7]
	s_mov_b32 m0, s41
	s_addc_u32 s9, s7, 0
	s_add_i32 s42, s40, 0x4000
	global_load_lds_dwordx4 v132, s[6:7]
	s_mov_b32 m0, s42
	s_add_i32 s43, s40, 0x6000
	global_load_lds_dwordx4 v128, s[8:9]
	s_mov_b32 m0, s43
	v_mov_b32_e32 v131, 0
	global_load_lds_dwordx4 v132, s[8:9]
	v_mov_b32_e32 v135, v131
	v_mov_b32_e32 v129, v131
	v_mov_b32_e32 v133, v131
	s_cmp_eq_u32 s0, 1
	s_mov_b32 s44, 0
	v_lshl_add_u64 v[6:7], s[34:35], 0, v[130:131]
	v_lshl_add_u64 v[2:3], s[34:35], 0, v[134:135]
	s_mov_b32 s8, 0x16000
	v_lshl_add_u64 v[0:1], s[6:7], 0, v[128:129]
	s_cselect_b64 s[10:11], -1, 0
	s_cmp_lg_u32 s0, 1
	v_lshl_add_u64 v[4:5], s[6:7], 0, v[132:133]
	s_cbranch_scc1 .LBB0_2030
	s_setprio 1
	s_barrier

.LBB0_2047:
	s_setprio 0
	v_lshl_add_u32 v144, s51, 8, v154
	v_lshl_or_b32 v148, s53, 8, v156
	v_ashrrev_i32_e32 v145, 31, v144
	v_ashrrev_i32_e32 v149, 31, v148
	v_lshlrev_b64 v[146:147], 11, v[144:145]
	v_lshl_add_u64 v[146:147], v[146:147], 0, v[148:149]
	v_lshl_add_u64 v[150:151], v[146:147], 1, s[60:61]
	global_load_dwordx4 v[162:165], v[150:151], off
	v_cndmask_b32_e64 v152, 0, 1, s[18:19]
	v_cmp_ne_u32_e64 s[4:5], 1, v152
	s_mov_b64 s[6:7], -1
	s_andn2_b64 vcc, exec, s[18:19]
	s_waitcnt vmcnt(0)
	v_lshlrev_b32_e32 v152, 16, v162
	v_and_b32_e32 v153, 0xffff0000, v162
	v_lshlrev_b32_e32 v162, 16, v163
	v_and_b32_e32 v163, 0xffff0000, v163
	v_lshlrev_b32_e32 v166, 16, v164
	v_and_b32_e32 v167, 0xffff0000, v164
	v_lshlrev_b32_e32 v164, 16, v165
	v_and_b32_e32 v165, 0xffff0000, v165
	v_pk_fma_f32 v[126:127], v[126:127], 0.5, v[162:163] op_sel_hi:[1,0,1]
	v_pk_fma_f32 v[124:125], v[124:125], 0.5, v[152:153] op_sel_hi:[1,0,1]
	v_pk_fma_f32 v[122:123], v[122:123], 0.5, v[164:165] op_sel_hi:[1,0,1]
	v_pk_fma_f32 v[120:121], v[120:121], 0.5, v[166:167] op_sel_hi:[1,0,1]
	v_lshl_add_u64 v[152:153], v[146:147], 2, s[86:87]
	s_cbranch_vccnz .LBB0_2049
	s_mov_b64 s[6:7], 0
	global_store_dwordx4 v[152:153], v[124:127], off
	global_store_dwordx4 v[152:153], v[120:123], off offset:16
